# stacked on top: row-sum shuffles in GEMM epilogues via permlane swaps instead of LDS bpermute; attention units remapped to the GEMM panel-to-XCD mapping with q-proj and o-proj running their chunks in
# speedup vs baseline: 1.0161x; 1.0048x over previous
; #define GAS __attribute__((address_space(1)))
;     __device__ __forceinline__ void operator()(const Acc& acc, const Unit& u, int wr, int wc, int fr, int fq) const {
;         const int row0 = u.pm * 256 + wr * 64 + fr, col0 = u.pn * 256 + wc * 32 + 8 * fq;
; #pragma unroll
;         for (int ai = 0; ai < 2; ++ai)
; #pragma unroll
;             for (int m = 0; m < 4; ++m) {
;                 const int r = row0 + ai * 128 + m * 16; float ssum = 0.f;
; #pragma unroll
;                 for (int bj = 0; bj < 2; ++bj) {
;                     f32x4 y0, y1; unpack8(*(const GAS u32x4*)(YG + (size_t)r * CH + col0 + bj * 128), y0, y1);
;                     f32x4 z0 = acc[ai][bj][m][0], z1 = acc[ai][bj][m][1];
; #pragma unroll
;                     for (int e = 0; e < 4; ++e) { y0[e] = y0[e] * __builtin_amdgcn_rcpf(1.0f + __expf(-z0[e])); y1[e] = y1[e] * __builtin_amdgcn_rcpf(1.0f + __expf(-z1[e]));
;                         ssum += y0[e] * y0[e] + y1[e] * y1[e]; }
;                     store8_bf16(YCAT + (size_t)r * D + col0 + bj * 128, y0, y1);
;                 }
;                 ssum += __shfl_xor(ssum, 16); ssum += __shfl_xor(ssum, 32);
;                 if (fq == 0) atomicAdd(ssb + r, ssum);
.LBB0_590:
	v_lshl_add_u32 v142, s16, 8, v144
	v_lshl_or_b32 v140, s4, 8, v146
	v_ashrrev_i32_e32 v143, 31, v142
	v_ashrrev_i32_e32 v141, 31, v140
	v_lshlrev_b64 v[148:149], 10, v[142:143]
	v_lshl_add_u64 v[148:149], s[52:53], 0, v[148:149]
	v_lshlrev_b64 v[140:141], 1, v[140:141]
	v_lshl_add_u64 v[152:153], v[148:149], 0, v[140:141]
	global_load_dwordx4 v[148:151], v[152:153], off
	global_load_dwordx4 v[162:165], v[152:153], off offset:256
	v_add_co_u32_e32 v248, vcc, 0x4000, v152
	s_nop 1
	v_addc_co_u32_e32 v249, vcc, 0, v153, vcc
	global_load_dwordx4 v[166:169], v[248:249], off
	global_load_dwordx4 v[170:173], v[248:249], off offset:256
	v_add_co_u32_e32 v248, vcc, 0x8000, v152
	s_nop 1
	v_addc_co_u32_e32 v249, vcc, 0, v153, vcc
	global_load_dwordx4 v[174:177], v[248:249], off
	global_load_dwordx4 v[178:181], v[248:249], off offset:256
	v_add_co_u32_e32 v248, vcc, 0xc000, v152
	s_nop 1
	v_addc_co_u32_e32 v249, vcc, 0, v153, vcc
	global_load_dwordx4 v[182:185], v[248:249], off
	global_load_dwordx4 v[186:189], v[248:249], off offset:256
	v_add_co_u32_e32 v248, vcc, 0x20000, v152
	s_nop 1
	v_addc_co_u32_e32 v249, vcc, 0, v153, vcc
	global_load_dwordx4 v[190:193], v[248:249], off
	global_load_dwordx4 v[214:217], v[248:249], off offset:256
	v_add_co_u32_e32 v248, vcc, 0x24000, v152
	s_nop 1
	v_addc_co_u32_e32 v249, vcc, 0, v153, vcc
	global_load_dwordx4 v[218:221], v[248:249], off
	global_load_dwordx4 v[222:225], v[248:249], off offset:256
	v_add_co_u32_e32 v248, vcc, 0x28000, v152
	s_nop 1
	v_addc_co_u32_e32 v249, vcc, 0, v153, vcc
	global_load_dwordx4 v[226:229], v[248:249], off
	global_load_dwordx4 v[230:233], v[248:249], off offset:256
	v_add_co_u32_e32 v248, vcc, 0x2c000, v152
	s_nop 1
	v_addc_co_u32_e32 v249, vcc, 0, v153, vcc
	global_load_dwordx4 v[234:237], v[248:249], off
	global_load_dwordx4 v[238:241], v[248:249], off offset:256
	v_mul_f32_e32 v126, 0xbfb8aa3b, v126
	v_mul_f32_e32 v122, 0xbfb8aa3b, v122
	v_mul_f32_e32 v127, 0xbfb8aa3b, v127
	v_mul_f32_e32 v123, 0xbfb8aa3b, v123
	v_mul_f32_e32 v128, 0xbfb8aa3b, v128
	v_mul_f32_e32 v124, 0xbfb8aa3b, v124
	v_mul_f32_e32 v129, 0xbfb8aa3b, v129
	v_mul_f32_e32 v125, 0xbfb8aa3b, v125
	v_exp_f32_e32 v126, v126
	v_exp_f32_e32 v122, v122
	v_exp_f32_e32 v127, v127
	v_exp_f32_e32 v123, v123
	v_exp_f32_e32 v128, v128
	v_exp_f32_e32 v124, v124
	v_exp_f32_e32 v129, v129
	v_exp_f32_e32 v125, v125
	v_add_f32_e32 v126, 1.0, v126
	v_add_f32_e32 v122, 1.0, v122
	v_add_f32_e32 v127, 1.0, v127
	v_add_f32_e32 v123, 1.0, v123
	v_add_f32_e32 v128, 1.0, v128
	v_add_f32_e32 v124, 1.0, v124
	v_add_f32_e32 v129, 1.0, v129
	v_add_f32_e32 v125, 1.0, v125
	v_rcp_f32_e32 v126, v126
	v_rcp_f32_e32 v122, v122
	v_rcp_f32_e32 v127, v127
	v_rcp_f32_e32 v123, v123
	v_rcp_f32_e32 v128, v128
	v_rcp_f32_e32 v124, v124
	v_rcp_f32_e32 v129, v129
	v_rcp_f32_e32 v125, v125
	v_mul_f32_e32 v118, 0xbfb8aa3b, v118
	v_mul_f32_e32 v114, 0xbfb8aa3b, v114
	v_mul_f32_e32 v119, 0xbfb8aa3b, v119
	v_mul_f32_e32 v115, 0xbfb8aa3b, v115
	v_mul_f32_e32 v121, 0xbfb8aa3b, v121
	v_mul_f32_e32 v117, 0xbfb8aa3b, v117
	v_exp_f32_e32 v118, v118
	v_exp_f32_e32 v159, v114
	v_mul_f32_e32 v120, 0xbfb8aa3b, v120
	v_mul_f32_e32 v116, 0xbfb8aa3b, v116
	v_exp_f32_e32 v119, v119
	v_exp_f32_e32 v160, v115
	v_exp_f32_e32 v121, v121
	v_exp_f32_e32 v117, v117
	v_exp_f32_e32 v120, v120
	v_exp_f32_e32 v161, v116
	v_xor_b32_e32 v158, 32, v246
	v_add_f32_e32 v118, 1.0, v118
	v_add_f32_e32 v119, 1.0, v119
	v_add_f32_e32 v121, 1.0, v121
	v_add_f32_e32 v117, 1.0, v117
	v_rcp_f32_e32 v118, v118
	v_add_f32_e32 v120, 1.0, v120
	v_rcp_f32_e32 v119, v119
	v_rcp_f32_e32 v121, v121
	v_rcp_f32_e32 v117, v117
	v_rcp_f32_e32 v120, v120
	v_lshlrev_b64 v[114:115], 11, v[142:143]
	v_lshl_add_u64 v[114:115], s[58:59], 0, v[114:115]
	v_lshl_add_u64 v[114:115], v[114:115], 0, v[140:141]
	s_waitcnt vmcnt(8)
	v_lshlrev_b32_e32 v154, 16, v148
	v_and_b32_e32 v148, 0xffff0000, v148
	v_lshlrev_b32_e32 v155, 16, v149
	v_and_b32_e32 v149, 0xffff0000, v149
	v_lshlrev_b32_e32 v156, 16, v150
	v_and_b32_e32 v150, 0xffff0000, v150
	v_lshlrev_b32_e32 v157, 16, v151
	v_and_b32_e32 v151, 0xffff0000, v151
	v_mul_f32_e32 v154, v126, v154
	v_mul_f32_e32 v156, v122, v156
	v_mul_f32_e32 v148, v127, v148
	v_mul_f32_e32 v150, v123, v150
	v_mul_f32_e32 v155, v128, v155
	v_mul_f32_e32 v157, v124, v157
	v_mul_f32_e32 v149, v129, v149
	v_mul_f32_e32 v151, v125, v151
	v_cvt_pk_bf16_f32 v122, v154, v148
	v_cvt_pk_bf16_f32 v123, v155, v149
	v_cvt_pk_bf16_f32 v124, v156, v150
	v_cvt_pk_bf16_f32 v125, v157, v151
	s_nop 1
	v_mov_b64_e32 v[126:127], v[162:163]
	v_mov_b64_e32 v[128:129], v[164:165]
	v_xor_b32_e32 v152, 16, v246
	v_add_u32_e32 v153, 64, v247
	v_cmp_lt_i32_e32 vcc, v152, v153
	v_mul_f32_e32 v156, v156, v156
	v_mul_f32_e32 v150, v150, v150
	v_cndmask_b32_e32 v116, v246, v152, vcc
	v_cmp_lt_i32_e32 vcc, v158, v153
	v_add_f32_e32 v153, 1.0, v159
	v_rcp_f32_e32 v153, v153
	v_cndmask_b32_e32 v152, v246, v158, vcc
	v_add_f32_e32 v158, 1.0, v160
	v_mul_f32_e32 v157, v157, v157
	v_fmac_f32_e32 v156, v154, v154
	v_fmac_f32_e32 v150, v148, v148
	v_add_f32_e32 v159, 1.0, v161
	v_rcp_f32_e32 v158, v158
	v_mul_f32_e32 v151, v151, v151
	v_fmac_f32_e32 v157, v155, v155
	v_add_f32_e32 v148, v156, v150
	v_rcp_f32_e32 v159, v159
	v_fmac_f32_e32 v151, v149, v149
	v_add_f32_e32 v148, v157, v148
	v_add_f32_e32 v148, v151, v148
	v_lshlrev_b32_e32 v116, 2, v116
	global_store_dwordx4 v[114:115], v[122:125], off
	s_nop 0
	v_lshlrev_b32_e32 v149, 16, v126
	v_lshlrev_b32_e32 v151, 16, v128
	v_and_b32_e32 v126, 0xffff0000, v126
	v_lshlrev_b32_e32 v150, 16, v127
	v_and_b32_e32 v127, 0xffff0000, v127
	v_and_b32_e32 v128, 0xffff0000, v128
	v_lshlrev_b32_e32 v154, 16, v129
	v_and_b32_e32 v129, 0xffff0000, v129
	v_mul_f32_e32 v118, v118, v149
	v_mul_f32_e32 v149, v153, v151
	v_mul_f32_e32 v119, v119, v126
	v_mul_f32_e32 v126, v158, v128
	v_mul_f32_e32 v121, v121, v127
	v_mul_f32_e32 v127, v117, v129
	v_mul_f32_e32 v117, v149, v149
	v_mul_f32_e32 v128, v120, v150
	v_mul_f32_e32 v150, v159, v154
	v_mul_f32_e32 v120, v126, v126
	v_fmac_f32_e32 v117, v118, v118
	v_mul_f32_e32 v129, v150, v150
	v_fmac_f32_e32 v120, v119, v119
	v_add_f32_e32 v117, v148, v117
	v_mul_f32_e32 v151, v127, v127
	v_fmac_f32_e32 v129, v128, v128
	v_add_f32_e32 v117, v120, v117
	v_fmac_f32_e32 v151, v121, v121
	v_add_f32_e32 v117, v129, v117
	v_add_f32_e32 v117, v151, v117
	v_mov_b32_e32 v129, v117
	v_mov_b32_e32 v254, v117
	s_nop 1
	v_permlane16_swap_b32_e32 v129, v254
	v_cvt_pk_bf16_f32 v120, v118, v119
	v_cvt_pk_bf16_f32 v121, v128, v121
	v_cvt_pk_bf16_f32 v122, v149, v126
	v_cvt_pk_bf16_f32 v123, v150, v127
	s_waitcnt lgkmcnt(0)
	v_add_f32_e32 v118, v254, v129
	v_lshlrev_b32_e32 v117, 2, v152
	v_mov_b32_e32 v119, v118
	v_mov_b32_e32 v254, v118
	s_nop 1
	v_permlane32_swap_b32_e32 v119, v254
	global_store_dwordx4 v[114:115], v[120:123], off offset:256
	v_lshl_add_u64 v[114:115], v[142:143], 2, s[60:61]
	s_and_saveexec_b64 s[4:5], s[0:1]
	s_cbranch_execz .LBB0_592
; #define GAS __attribute__((address_space(1)))
;     __device__ __forceinline__ void operator()(const Acc& acc, const Unit& u, int wr, int wc, int fr, int fq) const {
;         const int row0 = u.pm * 256 + wr * 64 + fr, col0 = u.pn * 256 + wc * 32 + 8 * fq;
; #pragma unroll
;         for (int ai = 0; ai < 2; ++ai)
; #pragma unroll
;             for (int m = 0; m < 4; ++m) {
;                 const int r = row0 + ai * 128 + m * 16; float ssum = 0.f;
; #pragma unroll
;                 for (int bj = 0; bj < 2; ++bj) {
;                     f32x4 y0, y1; unpack8(*(const GAS u32x4*)(YG + (size_t)r * CH + col0 + bj * 128), y0, y1);
;                     f32x4 z0 = acc[ai][bj][m][0], z1 = acc[ai][bj][m][1];
; #pragma unroll
;                     for (int e = 0; e < 4; ++e) { y0[e] = y0[e] * __builtin_amdgcn_rcpf(1.0f + __expf(-z0[e])); y1[e] = y1[e] * __builtin_amdgcn_rcpf(1.0f + __expf(-z1[e]));
;                         ssum += y0[e] * y0[e] + y1[e] * y1[e]; }
;                     store8_bf16(YCAT + (size_t)r * D + col0 + bj * 128, y0, y1);
;                 }
;                 ssum += __shfl_xor(ssum, 16); ssum += __shfl_xor(ssum, 32);
;                 if (fq == 0) atomicAdd(ssb + r, ssum);
	s_waitcnt lgkmcnt(0)
	v_add_f32_e32 v118, v254, v119
	flat_atomic_add_f32 v[114:115], v118
.LBB0_592:
	s_or_b64 exec, exec, s[4:5]
	v_or_b32_e32 v122, 16, v142
	v_ashrrev_i32_e32 v123, 31, v122
	s_waitcnt lgkmcnt(0)
	v_lshlrev_b64 v[118:119], 10, v[122:123]
	v_lshl_add_u64 v[118:119], s[52:53], 0, v[118:119]
	v_lshl_add_u64 v[124:125], v[118:119], 0, v[140:141]
	s_nop 1
	v_mov_b64_e32 v[118:119], v[166:167]
	v_mov_b64_e32 v[120:121], v[168:169]
	v_mul_f32_e32 v110, 0xbfb8aa3b, v110
	v_mul_f32_e32 v106, 0xbfb8aa3b, v106
	v_mul_f32_e32 v111, 0xbfb8aa3b, v111
	v_mul_f32_e32 v107, 0xbfb8aa3b, v107
	v_mul_f32_e32 v112, 0xbfb8aa3b, v112
	v_mul_f32_e32 v108, 0xbfb8aa3b, v108
	v_mul_f32_e32 v113, 0xbfb8aa3b, v113
	v_mul_f32_e32 v109, 0xbfb8aa3b, v109
	v_exp_f32_e32 v110, v110
	v_exp_f32_e32 v106, v106
	v_exp_f32_e32 v111, v111
	v_exp_f32_e32 v107, v107
	v_exp_f32_e32 v112, v112
	v_exp_f32_e32 v108, v108
	v_exp_f32_e32 v113, v113
	v_exp_f32_e32 v109, v109
	v_add_f32_e32 v110, 1.0, v110
	v_add_f32_e32 v106, 1.0, v106
	v_add_f32_e32 v111, 1.0, v111
	v_add_f32_e32 v107, 1.0, v107
	v_add_f32_e32 v112, 1.0, v112
	v_add_f32_e32 v108, 1.0, v108
	v_add_f32_e32 v113, 1.0, v113
	v_add_f32_e32 v109, 1.0, v109
	v_rcp_f32_e32 v110, v110
	v_rcp_f32_e32 v106, v106
	v_rcp_f32_e32 v111, v111
	v_rcp_f32_e32 v107, v107
	v_rcp_f32_e32 v112, v112
	v_rcp_f32_e32 v108, v108
	v_rcp_f32_e32 v113, v113
	v_rcp_f32_e32 v109, v109
	v_mul_f32_e32 v102, 0xbfb8aa3b, v102
	v_mul_f32_e32 v98, 0xbfb8aa3b, v98
	v_mul_f32_e32 v103, 0xbfb8aa3b, v103
	v_mul_f32_e32 v99, 0xbfb8aa3b, v99
	v_mul_f32_e32 v104, 0xbfb8aa3b, v104
	v_mul_f32_e32 v100, 0xbfb8aa3b, v100
	v_exp_f32_e32 v102, v102
	v_mul_f32_e32 v101, 0xbfb8aa3b, v101
	v_exp_f32_e32 v103, v103
	v_exp_f32_e32 v104, v104
	v_exp_f32_e32 v100, v100
	v_exp_f32_e32 v101, v101
	v_mul_f32_e32 v105, 0xbfb8aa3b, v105
	v_exp_f32_e32 v105, v105
	v_add_f32_e32 v102, 1.0, v102
	v_add_f32_e32 v103, 1.0, v103
	v_add_f32_e32 v104, 1.0, v104
	v_add_f32_e32 v100, 1.0, v100
	v_rcp_f32_e32 v102, v102
	v_add_f32_e32 v101, 1.0, v101
	v_rcp_f32_e32 v103, v103
	v_rcp_f32_e32 v104, v104
	v_rcp_f32_e32 v100, v100
	v_rcp_f32_e32 v101, v101
	v_add_f32_e32 v105, 1.0, v105
	v_rcp_f32_e32 v105, v105
	s_nop 0
	v_lshlrev_b32_e32 v126, 16, v118
	v_and_b32_e32 v118, 0xffff0000, v118
	v_lshlrev_b32_e32 v127, 16, v119
	v_and_b32_e32 v119, 0xffff0000, v119
	v_lshlrev_b32_e32 v128, 16, v120
	v_and_b32_e32 v120, 0xffff0000, v120
	v_lshlrev_b32_e32 v129, 16, v121
	v_and_b32_e32 v121, 0xffff0000, v121
	v_mul_f32_e32 v126, v110, v126
	v_mul_f32_e32 v128, v106, v128
	v_mul_f32_e32 v118, v111, v118
	v_mul_f32_e32 v120, v107, v120
	v_mul_f32_e32 v127, v112, v127
	v_mul_f32_e32 v129, v108, v129
	v_mul_f32_e32 v119, v113, v119
	v_mul_f32_e32 v121, v109, v121
	v_cvt_pk_bf16_f32 v106, v126, v118
	v_cvt_pk_bf16_f32 v107, v127, v119
	v_cvt_pk_bf16_f32 v108, v128, v120
	v_cvt_pk_bf16_f32 v109, v129, v121
	s_nop 1
	v_mov_b64_e32 v[110:111], v[170:171]
	v_mov_b64_e32 v[112:113], v[172:173]
	v_exp_f32_e32 v124, v98
	v_exp_f32_e32 v125, v99
	v_lshlrev_b64 v[98:99], 11, v[122:123]
	v_mul_f32_e32 v120, v120, v120
	v_add_f32_e32 v122, 1.0, v124
	v_mul_f32_e32 v124, v128, v128
	v_add_f32_e32 v123, 1.0, v125
	v_rcp_f32_e32 v122, v122
	v_mul_f32_e32 v125, v129, v129
	v_fmac_f32_e32 v124, v126, v126
	v_fmac_f32_e32 v120, v118, v118
	v_rcp_f32_e32 v123, v123
	v_mul_f32_e32 v121, v121, v121
	v_fmac_f32_e32 v125, v127, v127
	v_add_f32_e32 v118, v124, v120
	v_fmac_f32_e32 v121, v119, v119
	v_add_f32_e32 v118, v125, v118
	v_add_f32_e32 v118, v121, v118
	v_lshl_add_u64 v[98:99], s[58:59], 0, v[98:99]
	s_nop 0
	v_lshlrev_b32_e32 v119, 16, v110
	v_lshlrev_b32_e32 v121, 16, v112
	v_and_b32_e32 v110, 0xffff0000, v110
	v_lshlrev_b32_e32 v120, 16, v111
	v_and_b32_e32 v112, 0xffff0000, v112
	v_lshlrev_b32_e32 v124, 16, v113
	v_mul_f32_e32 v102, v102, v119
	v_mul_f32_e32 v119, v122, v121
	v_and_b32_e32 v113, 0xffff0000, v113
	v_mul_f32_e32 v103, v103, v110
	v_mul_f32_e32 v110, v123, v112
	v_mul_f32_e32 v112, v104, v120
	v_mul_f32_e32 v120, v100, v124
	v_mul_f32_e32 v100, v119, v119
	v_mul_f32_e32 v113, v101, v113
	v_mul_f32_e32 v101, v110, v110
	v_fmac_f32_e32 v100, v102, v102
	v_and_b32_e32 v111, 0xffff0000, v111
	v_mul_f32_e32 v104, v120, v120
	v_fmac_f32_e32 v101, v103, v103
	v_add_f32_e32 v100, v118, v100
	v_mul_f32_e32 v111, v105, v111
	v_mul_f32_e32 v105, v113, v113
	v_fmac_f32_e32 v104, v112, v112
	v_add_f32_e32 v100, v101, v100
	v_add_f32_e32 v100, v104, v100
	v_fmac_f32_e32 v105, v111, v111
	v_add_f32_e32 v101, v105, v100
	v_mov_b32_e32 v118, v101
	v_mov_b32_e32 v254, v101
	s_nop 1
	v_permlane16_swap_b32_e32 v118, v254
	v_lshl_add_u64 v[104:105], v[98:99], 0, v[140:141]
	global_store_dwordx4 v[104:105], v[106:109], off
	v_cvt_pk_bf16_f32 v100, v102, v103
	s_waitcnt lgkmcnt(0)
	v_add_f32_e32 v98, v254, v118
	v_mov_b32_e32 v99, v98
	v_mov_b32_e32 v254, v98
	s_nop 1
	v_permlane32_swap_b32_e32 v99, v254
	v_cvt_pk_bf16_f32 v101, v112, v111
	v_cvt_pk_bf16_f32 v102, v119, v110
	v_cvt_pk_bf16_f32 v103, v120, v113
	global_store_dwordx4 v[104:105], v[100:103], off offset:256
	s_and_saveexec_b64 s[4:5], s[0:1]
	s_cbranch_execz .LBB0_594
	s_waitcnt lgkmcnt(0)
	v_add_f32_e32 v98, v254, v99
	flat_atomic_add_f32 v[114:115], v98 offset:64
; #define GAS __attribute__((address_space(1)))
;     __device__ __forceinline__ void operator()(const Acc& acc, const Unit& u, int wr, int wc, int fr, int fq) const {
;         const int row0 = u.pm * 256 + wr * 64 + fr, col0 = u.pn * 256 + wc * 32 + 8 * fq;
; #pragma unroll
;         for (int ai = 0; ai < 2; ++ai)
; #pragma unroll
;             for (int m = 0; m < 4; ++m) {
;                 const int r = row0 + ai * 128 + m * 16; float ssum = 0.f;
; #pragma unroll
;                 for (int bj = 0; bj < 2; ++bj) {
;                     f32x4 y0, y1; unpack8(*(const GAS u32x4*)(YG + (size_t)r * CH + col0 + bj * 128), y0, y1);
;                     f32x4 z0 = acc[ai][bj][m][0], z1 = acc[ai][bj][m][1];
; #pragma unroll
;                     for (int e = 0; e < 4; ++e) { y0[e] = y0[e] * __builtin_amdgcn_rcpf(1.0f + __expf(-z0[e])); y1[e] = y1[e] * __builtin_amdgcn_rcpf(1.0f + __expf(-z1[e]));
;                         ssum += y0[e] * y0[e] + y1[e] * y1[e]; }
;                     store8_bf16(YCAT + (size_t)r * D + col0 + bj * 128, y0, y1);
;                 }
;                 ssum += __shfl_xor(ssum, 16); ssum += __shfl_xor(ssum, 32);
;                 if (fq == 0) atomicAdd(ssb + r, ssum);
.LBB0_594:
	s_or_b64 exec, exec, s[4:5]
	v_or_b32_e32 v102, 32, v142
	v_ashrrev_i32_e32 v103, 31, v102
	s_waitcnt lgkmcnt(0)
	v_lshlrev_b64 v[98:99], 10, v[102:103]
	v_lshl_add_u64 v[98:99], s[52:53], 0, v[98:99]
	v_lshl_add_u64 v[104:105], v[98:99], 0, v[140:141]
	s_nop 1
	v_mov_b64_e32 v[98:99], v[174:175]
	v_mov_b64_e32 v[100:101], v[176:177]
	v_mul_f32_e32 v94, 0xbfb8aa3b, v94
	v_mul_f32_e32 v90, 0xbfb8aa3b, v90
	v_mul_f32_e32 v95, 0xbfb8aa3b, v95
	v_mul_f32_e32 v91, 0xbfb8aa3b, v91
	v_mul_f32_e32 v96, 0xbfb8aa3b, v96
	v_mul_f32_e32 v92, 0xbfb8aa3b, v92
	v_mul_f32_e32 v97, 0xbfb8aa3b, v97
	v_mul_f32_e32 v93, 0xbfb8aa3b, v93
	v_exp_f32_e32 v94, v94
	v_exp_f32_e32 v90, v90
	v_exp_f32_e32 v95, v95
	v_exp_f32_e32 v91, v91
	v_exp_f32_e32 v96, v96
	v_exp_f32_e32 v92, v92
	v_exp_f32_e32 v97, v97
	v_exp_f32_e32 v93, v93
	v_add_f32_e32 v94, 1.0, v94
	v_add_f32_e32 v90, 1.0, v90
	v_add_f32_e32 v95, 1.0, v95
	v_add_f32_e32 v91, 1.0, v91
	v_add_f32_e32 v96, 1.0, v96
	v_add_f32_e32 v92, 1.0, v92
	v_add_f32_e32 v97, 1.0, v97
	v_add_f32_e32 v93, 1.0, v93
	v_rcp_f32_e32 v94, v94
	v_rcp_f32_e32 v90, v90
	v_rcp_f32_e32 v95, v95
	v_rcp_f32_e32 v91, v91
	v_rcp_f32_e32 v96, v96
	v_rcp_f32_e32 v92, v92
	v_rcp_f32_e32 v97, v97
	v_rcp_f32_e32 v93, v93
	v_mul_f32_e32 v86, 0xbfb8aa3b, v86
	v_mul_f32_e32 v82, 0xbfb8aa3b, v82
	v_mul_f32_e32 v87, 0xbfb8aa3b, v87
	v_mul_f32_e32 v83, 0xbfb8aa3b, v83
	v_mul_f32_e32 v88, 0xbfb8aa3b, v88
	v_mul_f32_e32 v84, 0xbfb8aa3b, v84
	v_exp_f32_e32 v86, v86
	v_mul_f32_e32 v85, 0xbfb8aa3b, v85
	v_exp_f32_e32 v87, v87
	v_exp_f32_e32 v88, v88
	v_exp_f32_e32 v84, v84
	v_exp_f32_e32 v85, v85
	v_mul_f32_e32 v89, 0xbfb8aa3b, v89
	v_exp_f32_e32 v89, v89
	v_add_f32_e32 v86, 1.0, v86
	v_add_f32_e32 v87, 1.0, v87
	v_add_f32_e32 v88, 1.0, v88
	v_add_f32_e32 v84, 1.0, v84
	v_rcp_f32_e32 v86, v86
	v_add_f32_e32 v85, 1.0, v85
	v_rcp_f32_e32 v87, v87
	v_rcp_f32_e32 v88, v88
	v_rcp_f32_e32 v84, v84
	v_rcp_f32_e32 v85, v85
	v_add_f32_e32 v89, 1.0, v89
	v_rcp_f32_e32 v89, v89
	s_nop 0
	v_lshlrev_b32_e32 v106, 16, v98
	v_and_b32_e32 v98, 0xffff0000, v98
	v_lshlrev_b32_e32 v107, 16, v99
	v_and_b32_e32 v99, 0xffff0000, v99
	v_lshlrev_b32_e32 v108, 16, v100
	v_and_b32_e32 v100, 0xffff0000, v100
	v_lshlrev_b32_e32 v109, 16, v101
	v_and_b32_e32 v101, 0xffff0000, v101
	v_mul_f32_e32 v106, v94, v106
	v_mul_f32_e32 v108, v90, v108
	v_mul_f32_e32 v98, v95, v98
	v_mul_f32_e32 v100, v91, v100
	v_mul_f32_e32 v107, v96, v107
	v_mul_f32_e32 v109, v92, v109
	v_mul_f32_e32 v99, v97, v99
	v_mul_f32_e32 v101, v93, v101
	v_cvt_pk_bf16_f32 v90, v106, v98
	v_cvt_pk_bf16_f32 v91, v107, v99
	v_cvt_pk_bf16_f32 v92, v108, v100
	v_cvt_pk_bf16_f32 v93, v109, v101
	s_nop 1
	v_mov_b64_e32 v[94:95], v[178:179]
	v_mov_b64_e32 v[96:97], v[180:181]
	v_exp_f32_e32 v104, v82
	v_exp_f32_e32 v105, v83
	v_lshlrev_b64 v[82:83], 11, v[102:103]
	v_mul_f32_e32 v100, v100, v100
	v_add_f32_e32 v102, 1.0, v104
	v_mul_f32_e32 v104, v108, v108
	v_add_f32_e32 v103, 1.0, v105
	v_rcp_f32_e32 v102, v102
	v_mul_f32_e32 v105, v109, v109
	v_fmac_f32_e32 v104, v106, v106
	v_fmac_f32_e32 v100, v98, v98
	v_rcp_f32_e32 v103, v103
	v_mul_f32_e32 v101, v101, v101
	v_fmac_f32_e32 v105, v107, v107
	v_add_f32_e32 v98, v104, v100
	v_fmac_f32_e32 v101, v99, v99
	v_add_f32_e32 v98, v105, v98
	v_add_f32_e32 v98, v101, v98
	v_lshl_add_u64 v[82:83], s[58:59], 0, v[82:83]
	s_nop 0
	v_lshlrev_b32_e32 v99, 16, v94
	v_lshlrev_b32_e32 v101, 16, v96
	v_and_b32_e32 v94, 0xffff0000, v94
	v_lshlrev_b32_e32 v100, 16, v95
	v_and_b32_e32 v96, 0xffff0000, v96
	v_lshlrev_b32_e32 v104, 16, v97
	v_mul_f32_e32 v86, v86, v99
	v_mul_f32_e32 v99, v102, v101
	v_and_b32_e32 v97, 0xffff0000, v97
	v_mul_f32_e32 v87, v87, v94
	v_mul_f32_e32 v94, v103, v96
	v_mul_f32_e32 v96, v88, v100
	v_mul_f32_e32 v100, v84, v104
	v_mul_f32_e32 v84, v99, v99
	v_mul_f32_e32 v97, v85, v97
	v_mul_f32_e32 v85, v94, v94
	v_fmac_f32_e32 v84, v86, v86
	v_and_b32_e32 v95, 0xffff0000, v95
	v_mul_f32_e32 v88, v100, v100
	v_fmac_f32_e32 v85, v87, v87
	v_add_f32_e32 v84, v98, v84
	v_mul_f32_e32 v95, v89, v95
	v_mul_f32_e32 v89, v97, v97
	v_fmac_f32_e32 v88, v96, v96
	v_add_f32_e32 v84, v85, v84
	v_add_f32_e32 v84, v88, v84
	v_fmac_f32_e32 v89, v95, v95
	v_add_f32_e32 v85, v89, v84
	v_mov_b32_e32 v98, v85
	v_mov_b32_e32 v254, v85
	s_nop 1
	v_permlane16_swap_b32_e32 v98, v254
	v_lshl_add_u64 v[88:89], v[82:83], 0, v[140:141]
	global_store_dwordx4 v[88:89], v[90:93], off
	v_cvt_pk_bf16_f32 v84, v86, v87
	s_waitcnt lgkmcnt(0)
	v_add_f32_e32 v82, v254, v98
	v_mov_b32_e32 v83, v82
	v_mov_b32_e32 v254, v82
	s_nop 1
	v_permlane32_swap_b32_e32 v83, v254
	v_cvt_pk_bf16_f32 v85, v96, v95
	v_cvt_pk_bf16_f32 v86, v99, v94
	v_cvt_pk_bf16_f32 v87, v100, v97
	global_store_dwordx4 v[88:89], v[84:87], off offset:256
	s_and_saveexec_b64 s[4:5], s[0:1]
	s_cbranch_execz .LBB0_596
	s_waitcnt lgkmcnt(0)
	v_add_f32_e32 v82, v254, v83
	flat_atomic_add_f32 v[114:115], v82 offset:128
; #define GAS __attribute__((address_space(1)))
;     __device__ __forceinline__ void operator()(const Acc& acc, const Unit& u, int wr, int wc, int fr, int fq) const {
;         const int row0 = u.pm * 256 + wr * 64 + fr, col0 = u.pn * 256 + wc * 32 + 8 * fq;
; #pragma unroll
;         for (int ai = 0; ai < 2; ++ai)
; #pragma unroll
;             for (int m = 0; m < 4; ++m) {
;                 const int r = row0 + ai * 128 + m * 16; float ssum = 0.f;
; #pragma unroll
;                 for (int bj = 0; bj < 2; ++bj) {
;                     f32x4 y0, y1; unpack8(*(const GAS u32x4*)(YG + (size_t)r * CH + col0 + bj * 128), y0, y1);
;                     f32x4 z0 = acc[ai][bj][m][0], z1 = acc[ai][bj][m][1];
; #pragma unroll
;                     for (int e = 0; e < 4; ++e) { y0[e] = y0[e] * __builtin_amdgcn_rcpf(1.0f + __expf(-z0[e])); y1[e] = y1[e] * __builtin_amdgcn_rcpf(1.0f + __expf(-z1[e]));
;                         ssum += y0[e] * y0[e] + y1[e] * y1[e]; }
;                     store8_bf16(YCAT + (size_t)r * D + col0 + bj * 128, y0, y1);
;                 }
;                 ssum += __shfl_xor(ssum, 16); ssum += __shfl_xor(ssum, 32);
;                 if (fq == 0) atomicAdd(ssb + r, ssum);
.LBB0_596:
	s_or_b64 exec, exec, s[4:5]
	v_or_b32_e32 v86, 48, v142
	v_ashrrev_i32_e32 v87, 31, v86
	s_waitcnt lgkmcnt(0)
	v_lshlrev_b64 v[82:83], 10, v[86:87]
	v_lshl_add_u64 v[82:83], s[52:53], 0, v[82:83]
	v_lshl_add_u64 v[88:89], v[82:83], 0, v[140:141]
	s_nop 1
	v_mov_b64_e32 v[82:83], v[182:183]
	v_mov_b64_e32 v[84:85], v[184:185]
	v_mul_f32_e32 v78, 0xbfb8aa3b, v78
	v_mul_f32_e32 v74, 0xbfb8aa3b, v74
	v_mul_f32_e32 v79, 0xbfb8aa3b, v79
	v_mul_f32_e32 v75, 0xbfb8aa3b, v75
	v_mul_f32_e32 v80, 0xbfb8aa3b, v80
	v_mul_f32_e32 v76, 0xbfb8aa3b, v76
	v_mul_f32_e32 v81, 0xbfb8aa3b, v81
	v_mul_f32_e32 v77, 0xbfb8aa3b, v77
	v_exp_f32_e32 v78, v78
	v_exp_f32_e32 v74, v74
	v_exp_f32_e32 v79, v79
	v_exp_f32_e32 v75, v75
	v_exp_f32_e32 v80, v80
	v_exp_f32_e32 v76, v76
	v_exp_f32_e32 v81, v81
	v_exp_f32_e32 v77, v77
	v_add_f32_e32 v78, 1.0, v78
	v_add_f32_e32 v74, 1.0, v74
	v_add_f32_e32 v79, 1.0, v79
	v_add_f32_e32 v75, 1.0, v75
	v_add_f32_e32 v80, 1.0, v80
	v_add_f32_e32 v76, 1.0, v76
	v_add_f32_e32 v81, 1.0, v81
	v_add_f32_e32 v77, 1.0, v77
	v_rcp_f32_e32 v78, v78
	v_rcp_f32_e32 v74, v74
	v_rcp_f32_e32 v79, v79
	v_rcp_f32_e32 v75, v75
	v_rcp_f32_e32 v80, v80
	v_rcp_f32_e32 v76, v76
	v_rcp_f32_e32 v81, v81
	v_rcp_f32_e32 v77, v77
	v_mul_f32_e32 v70, 0xbfb8aa3b, v70
	v_mul_f32_e32 v66, 0xbfb8aa3b, v66
	v_mul_f32_e32 v71, 0xbfb8aa3b, v71
	v_mul_f32_e32 v67, 0xbfb8aa3b, v67
	v_mul_f32_e32 v72, 0xbfb8aa3b, v72
	v_mul_f32_e32 v68, 0xbfb8aa3b, v68
	v_exp_f32_e32 v70, v70
	v_mul_f32_e32 v69, 0xbfb8aa3b, v69
	v_exp_f32_e32 v71, v71
	v_exp_f32_e32 v72, v72
	v_exp_f32_e32 v68, v68
	v_exp_f32_e32 v69, v69
	v_mul_f32_e32 v73, 0xbfb8aa3b, v73
	v_exp_f32_e32 v73, v73
	v_add_f32_e32 v70, 1.0, v70
	v_add_f32_e32 v71, 1.0, v71
	v_add_f32_e32 v72, 1.0, v72
	v_add_f32_e32 v68, 1.0, v68
	v_rcp_f32_e32 v70, v70
	v_add_f32_e32 v69, 1.0, v69
	v_rcp_f32_e32 v71, v71
	v_rcp_f32_e32 v72, v72
	v_rcp_f32_e32 v68, v68
	v_rcp_f32_e32 v69, v69
	v_add_f32_e32 v73, 1.0, v73
	v_rcp_f32_e32 v73, v73
	s_nop 0
	v_lshlrev_b32_e32 v90, 16, v82
	v_and_b32_e32 v82, 0xffff0000, v82
	v_lshlrev_b32_e32 v91, 16, v83
	v_and_b32_e32 v83, 0xffff0000, v83
	v_lshlrev_b32_e32 v92, 16, v84
	v_and_b32_e32 v84, 0xffff0000, v84
	v_lshlrev_b32_e32 v93, 16, v85
	v_and_b32_e32 v85, 0xffff0000, v85
	v_mul_f32_e32 v90, v78, v90
	v_mul_f32_e32 v92, v74, v92
	v_mul_f32_e32 v82, v79, v82
	v_mul_f32_e32 v84, v75, v84
	v_mul_f32_e32 v91, v80, v91
	v_mul_f32_e32 v93, v76, v93
	v_mul_f32_e32 v83, v81, v83
	v_mul_f32_e32 v85, v77, v85
	v_cvt_pk_bf16_f32 v74, v90, v82
	v_cvt_pk_bf16_f32 v75, v91, v83
	v_cvt_pk_bf16_f32 v76, v92, v84
	v_cvt_pk_bf16_f32 v77, v93, v85
	s_nop 1
	v_mov_b64_e32 v[78:79], v[186:187]
	v_mov_b64_e32 v[80:81], v[188:189]
	v_exp_f32_e32 v88, v66
	v_exp_f32_e32 v89, v67
	v_lshlrev_b64 v[66:67], 11, v[86:87]
	v_mul_f32_e32 v84, v84, v84
	v_add_f32_e32 v86, 1.0, v88
	v_mul_f32_e32 v88, v92, v92
	v_add_f32_e32 v87, 1.0, v89
	v_rcp_f32_e32 v86, v86
	v_mul_f32_e32 v89, v93, v93
	v_fmac_f32_e32 v88, v90, v90
	v_fmac_f32_e32 v84, v82, v82
	v_rcp_f32_e32 v87, v87
	v_mul_f32_e32 v85, v85, v85
	v_fmac_f32_e32 v89, v91, v91
	v_add_f32_e32 v82, v88, v84
	v_fmac_f32_e32 v85, v83, v83
	v_add_f32_e32 v82, v89, v82
	v_add_f32_e32 v82, v85, v82
	v_lshl_add_u64 v[66:67], s[58:59], 0, v[66:67]
	s_nop 0
	v_lshlrev_b32_e32 v83, 16, v78
	v_lshlrev_b32_e32 v85, 16, v80
	v_and_b32_e32 v78, 0xffff0000, v78
	v_lshlrev_b32_e32 v84, 16, v79
	v_and_b32_e32 v80, 0xffff0000, v80
	v_lshlrev_b32_e32 v88, 16, v81
	v_mul_f32_e32 v70, v70, v83
	v_mul_f32_e32 v83, v86, v85
	v_and_b32_e32 v81, 0xffff0000, v81
	v_mul_f32_e32 v71, v71, v78
	v_mul_f32_e32 v78, v87, v80
	v_mul_f32_e32 v80, v72, v84
	v_mul_f32_e32 v84, v68, v88
	v_mul_f32_e32 v68, v83, v83
	v_mul_f32_e32 v81, v69, v81
	v_mul_f32_e32 v69, v78, v78
	v_fmac_f32_e32 v68, v70, v70
	v_and_b32_e32 v79, 0xffff0000, v79
	v_mul_f32_e32 v72, v84, v84
	v_fmac_f32_e32 v69, v71, v71
	v_add_f32_e32 v68, v82, v68
	v_mul_f32_e32 v79, v73, v79
	v_mul_f32_e32 v73, v81, v81
	v_fmac_f32_e32 v72, v80, v80
	v_add_f32_e32 v68, v69, v68
	v_add_f32_e32 v68, v72, v68
	v_fmac_f32_e32 v73, v79, v79
	v_add_f32_e32 v69, v73, v68
	v_mov_b32_e32 v82, v69
	v_mov_b32_e32 v254, v69
	s_nop 1
	v_permlane16_swap_b32_e32 v82, v254
	v_lshl_add_u64 v[72:73], v[66:67], 0, v[140:141]
	global_store_dwordx4 v[72:73], v[74:77], off
	v_cvt_pk_bf16_f32 v68, v70, v71
	s_waitcnt lgkmcnt(0)
	v_add_f32_e32 v66, v254, v82
	v_mov_b32_e32 v67, v66
	v_mov_b32_e32 v254, v66
	s_nop 1
	v_permlane32_swap_b32_e32 v67, v254
	v_cvt_pk_bf16_f32 v69, v80, v79
	v_cvt_pk_bf16_f32 v70, v83, v78
	v_cvt_pk_bf16_f32 v71, v84, v81
	global_store_dwordx4 v[72:73], v[68:71], off offset:256
	s_and_saveexec_b64 s[4:5], s[0:1]
	s_cbranch_execz .LBB0_598
	s_waitcnt lgkmcnt(0)
	v_add_f32_e32 v66, v254, v67
	flat_atomic_add_f32 v[114:115], v66 offset:192
; #define GAS __attribute__((address_space(1)))
;     __device__ __forceinline__ void operator()(const Acc& acc, const Unit& u, int wr, int wc, int fr, int fq) const {
;         const int row0 = u.pm * 256 + wr * 64 + fr, col0 = u.pn * 256 + wc * 32 + 8 * fq;
; #pragma unroll
;         for (int ai = 0; ai < 2; ++ai)
; #pragma unroll
;             for (int m = 0; m < 4; ++m) {
;                 const int r = row0 + ai * 128 + m * 16; float ssum = 0.f;
; #pragma unroll
;                 for (int bj = 0; bj < 2; ++bj) {
;                     f32x4 y0, y1; unpack8(*(const GAS u32x4*)(YG + (size_t)r * CH + col0 + bj * 128), y0, y1);
;                     f32x4 z0 = acc[ai][bj][m][0], z1 = acc[ai][bj][m][1];
; #pragma unroll
;                     for (int e = 0; e < 4; ++e) { y0[e] = y0[e] * __builtin_amdgcn_rcpf(1.0f + __expf(-z0[e])); y1[e] = y1[e] * __builtin_amdgcn_rcpf(1.0f + __expf(-z1[e]));
;                         ssum += y0[e] * y0[e] + y1[e] * y1[e]; }
;                     store8_bf16(YCAT + (size_t)r * D + col0 + bj * 128, y0, y1);
;                 }
;                 ssum += __shfl_xor(ssum, 16); ssum += __shfl_xor(ssum, 32);
;                 if (fq == 0) atomicAdd(ssb + r, ssum);
.LBB0_598:
	s_or_b64 exec, exec, s[4:5]
	v_add_u32_e32 v70, 0x80, v142
	v_ashrrev_i32_e32 v71, 31, v70
	s_waitcnt lgkmcnt(0)
	v_lshlrev_b64 v[66:67], 10, v[70:71]
	v_lshl_add_u64 v[66:67], s[52:53], 0, v[66:67]
	v_lshl_add_u64 v[72:73], v[66:67], 0, v[140:141]
	s_waitcnt vmcnt(8)
	s_nop 1
	v_mov_b64_e32 v[66:67], v[190:191]
	v_mov_b64_e32 v[68:69], v[192:193]
	v_mul_f32_e32 v60, 0xbfb8aa3b, v60
	v_mul_f32_e32 v56, 0xbfb8aa3b, v56
	v_mul_f32_e32 v61, 0xbfb8aa3b, v61
	v_mul_f32_e32 v57, 0xbfb8aa3b, v57
	v_mul_f32_e32 v62, 0xbfb8aa3b, v62
	v_mul_f32_e32 v58, 0xbfb8aa3b, v58
	v_mul_f32_e32 v63, 0xbfb8aa3b, v63
	v_mul_f32_e32 v59, 0xbfb8aa3b, v59
	v_exp_f32_e32 v60, v60
	v_exp_f32_e32 v56, v56
	v_exp_f32_e32 v61, v61
	v_exp_f32_e32 v57, v57
	v_exp_f32_e32 v62, v62
	v_exp_f32_e32 v58, v58
	v_exp_f32_e32 v63, v63
	v_exp_f32_e32 v59, v59
	v_add_f32_e32 v60, 1.0, v60
	v_add_f32_e32 v56, 1.0, v56
	v_add_f32_e32 v61, 1.0, v61
	v_add_f32_e32 v57, 1.0, v57
	v_add_f32_e32 v62, 1.0, v62
	v_add_f32_e32 v58, 1.0, v58
	v_add_f32_e32 v63, 1.0, v63
	v_add_f32_e32 v59, 1.0, v59
	v_rcp_f32_e32 v60, v60
	v_rcp_f32_e32 v56, v56
	v_rcp_f32_e32 v61, v61
	v_rcp_f32_e32 v57, v57
	v_rcp_f32_e32 v62, v62
	v_rcp_f32_e32 v58, v58
	v_rcp_f32_e32 v63, v63
	v_rcp_f32_e32 v59, v59
	v_mul_f32_e32 v52, 0xbfb8aa3b, v52
	v_mul_f32_e32 v48, 0xbfb8aa3b, v48
	v_mul_f32_e32 v53, 0xbfb8aa3b, v53
	v_mul_f32_e32 v49, 0xbfb8aa3b, v49
	v_mul_f32_e32 v54, 0xbfb8aa3b, v54
	v_mul_f32_e32 v50, 0xbfb8aa3b, v50
	v_exp_f32_e32 v52, v52
	v_mul_f32_e32 v51, 0xbfb8aa3b, v51
	v_exp_f32_e32 v53, v53
	v_exp_f32_e32 v54, v54
	v_exp_f32_e32 v50, v50
	v_exp_f32_e32 v51, v51
	v_mul_f32_e32 v55, 0xbfb8aa3b, v55
	v_exp_f32_e32 v55, v55
	v_add_f32_e32 v52, 1.0, v52
	v_add_f32_e32 v53, 1.0, v53
	v_add_f32_e32 v54, 1.0, v54
	v_add_f32_e32 v50, 1.0, v50
	v_rcp_f32_e32 v52, v52
	v_add_f32_e32 v51, 1.0, v51
	v_rcp_f32_e32 v53, v53
	v_rcp_f32_e32 v54, v54
	v_rcp_f32_e32 v50, v50
	v_rcp_f32_e32 v51, v51
	v_add_f32_e32 v55, 1.0, v55
	v_rcp_f32_e32 v55, v55
	s_nop 0
	v_lshlrev_b32_e32 v74, 16, v66
	v_and_b32_e32 v66, 0xffff0000, v66
	v_lshlrev_b32_e32 v75, 16, v67
	v_and_b32_e32 v67, 0xffff0000, v67
	v_lshlrev_b32_e32 v76, 16, v68
	v_and_b32_e32 v68, 0xffff0000, v68
	v_lshlrev_b32_e32 v77, 16, v69
	v_and_b32_e32 v69, 0xffff0000, v69
	v_mul_f32_e32 v74, v60, v74
	v_mul_f32_e32 v76, v56, v76
	v_mul_f32_e32 v66, v61, v66
	v_mul_f32_e32 v68, v57, v68
	v_mul_f32_e32 v75, v62, v75
	v_mul_f32_e32 v77, v58, v77
	v_mul_f32_e32 v67, v63, v67
	v_mul_f32_e32 v69, v59, v69
	v_cvt_pk_bf16_f32 v56, v74, v66
	v_cvt_pk_bf16_f32 v57, v75, v67
	v_cvt_pk_bf16_f32 v58, v76, v68
	v_cvt_pk_bf16_f32 v59, v77, v69
	s_nop 1
	v_mov_b64_e32 v[60:61], v[214:215]
	v_mov_b64_e32 v[62:63], v[216:217]
	v_exp_f32_e32 v72, v48
	v_exp_f32_e32 v73, v49
	v_lshlrev_b64 v[48:49], 11, v[70:71]
	v_mul_f32_e32 v68, v68, v68
	v_add_f32_e32 v70, 1.0, v72
	v_mul_f32_e32 v72, v76, v76
	v_add_f32_e32 v71, 1.0, v73
	v_rcp_f32_e32 v70, v70
	v_mul_f32_e32 v73, v77, v77
	v_fmac_f32_e32 v72, v74, v74
	v_fmac_f32_e32 v68, v66, v66
	v_rcp_f32_e32 v71, v71
	v_mul_f32_e32 v69, v69, v69
	v_fmac_f32_e32 v73, v75, v75
	v_add_f32_e32 v66, v72, v68
	v_fmac_f32_e32 v69, v67, v67
	v_add_f32_e32 v66, v73, v66
	v_add_f32_e32 v66, v69, v66
	v_lshl_add_u64 v[48:49], s[58:59], 0, v[48:49]
	s_nop 0
	v_lshlrev_b32_e32 v67, 16, v60
	v_lshlrev_b32_e32 v69, 16, v62
	v_and_b32_e32 v60, 0xffff0000, v60
	v_lshlrev_b32_e32 v68, 16, v61
	v_and_b32_e32 v62, 0xffff0000, v62
	v_lshlrev_b32_e32 v72, 16, v63
	v_mul_f32_e32 v52, v52, v67
	v_mul_f32_e32 v67, v70, v69
	v_and_b32_e32 v63, 0xffff0000, v63
	v_mul_f32_e32 v53, v53, v60
	v_mul_f32_e32 v60, v71, v62
	v_mul_f32_e32 v62, v54, v68
	v_mul_f32_e32 v68, v50, v72
	v_mul_f32_e32 v50, v67, v67
	v_mul_f32_e32 v63, v51, v63
	v_mul_f32_e32 v51, v60, v60
	v_fmac_f32_e32 v50, v52, v52
	v_and_b32_e32 v61, 0xffff0000, v61
	v_mul_f32_e32 v54, v68, v68
	v_fmac_f32_e32 v51, v53, v53
	v_add_f32_e32 v50, v66, v50
	v_mul_f32_e32 v61, v55, v61
	v_mul_f32_e32 v55, v63, v63
	v_fmac_f32_e32 v54, v62, v62
	v_add_f32_e32 v50, v51, v50
	v_add_f32_e32 v50, v54, v50
	v_fmac_f32_e32 v55, v61, v61
	v_add_f32_e32 v51, v55, v50
	v_mov_b32_e32 v66, v51
	v_mov_b32_e32 v254, v51
	s_nop 1
	v_permlane16_swap_b32_e32 v66, v254
	v_lshl_add_u64 v[54:55], v[48:49], 0, v[140:141]
	global_store_dwordx4 v[54:55], v[56:59], off
	v_cvt_pk_bf16_f32 v50, v52, v53
	s_waitcnt lgkmcnt(0)
	v_add_f32_e32 v48, v254, v66
	v_mov_b32_e32 v49, v48
	v_mov_b32_e32 v254, v48
	s_nop 1
	v_permlane32_swap_b32_e32 v49, v254
	v_cvt_pk_bf16_f32 v51, v62, v61
	v_cvt_pk_bf16_f32 v52, v67, v60
	v_cvt_pk_bf16_f32 v53, v68, v63
	global_store_dwordx4 v[54:55], v[50:53], off offset:256
	s_and_saveexec_b64 s[4:5], s[0:1]
	s_cbranch_execz .LBB0_600
	s_waitcnt lgkmcnt(0)
	v_add_f32_e32 v48, v254, v49
	flat_atomic_add_f32 v[114:115], v48 offset:512
; #define GAS __attribute__((address_space(1)))
;     __device__ __forceinline__ void operator()(const Acc& acc, const Unit& u, int wr, int wc, int fr, int fq) const {
;         const int row0 = u.pm * 256 + wr * 64 + fr, col0 = u.pn * 256 + wc * 32 + 8 * fq;
; #pragma unroll
;         for (int ai = 0; ai < 2; ++ai)
; #pragma unroll
;             for (int m = 0; m < 4; ++m) {
;                 const int r = row0 + ai * 128 + m * 16; float ssum = 0.f;
; #pragma unroll
;                 for (int bj = 0; bj < 2; ++bj) {
;                     f32x4 y0, y1; unpack8(*(const GAS u32x4*)(YG + (size_t)r * CH + col0 + bj * 128), y0, y1);
;                     f32x4 z0 = acc[ai][bj][m][0], z1 = acc[ai][bj][m][1];
; #pragma unroll
;                     for (int e = 0; e < 4; ++e) { y0[e] = y0[e] * __builtin_amdgcn_rcpf(1.0f + __expf(-z0[e])); y1[e] = y1[e] * __builtin_amdgcn_rcpf(1.0f + __expf(-z1[e]));
;                         ssum += y0[e] * y0[e] + y1[e] * y1[e]; }
;                     store8_bf16(YCAT + (size_t)r * D + col0 + bj * 128, y0, y1);
;                 }
;                 ssum += __shfl_xor(ssum, 16); ssum += __shfl_xor(ssum, 32);
;                 if (fq == 0) atomicAdd(ssb + r, ssum);
;             }
;     }
.LBB0_600:
	s_or_b64 exec, exec, s[4:5]
	v_add_u32_e32 v52, 0x90, v142
	v_ashrrev_i32_e32 v53, 31, v52
	s_waitcnt lgkmcnt(0)
	v_lshlrev_b64 v[48:49], 10, v[52:53]
	v_lshl_add_u64 v[48:49], s[52:53], 0, v[48:49]
	v_lshl_add_u64 v[54:55], v[48:49], 0, v[140:141]
	s_nop 1
	v_mov_b64_e32 v[48:49], v[218:219]
	v_mov_b64_e32 v[50:51], v[220:221]
	v_mul_f32_e32 v44, 0xbfb8aa3b, v44
	v_mul_f32_e32 v40, 0xbfb8aa3b, v40
	v_mul_f32_e32 v45, 0xbfb8aa3b, v45
	v_mul_f32_e32 v41, 0xbfb8aa3b, v41
	v_mul_f32_e32 v46, 0xbfb8aa3b, v46
	v_mul_f32_e32 v42, 0xbfb8aa3b, v42
	v_mul_f32_e32 v47, 0xbfb8aa3b, v47
	v_mul_f32_e32 v43, 0xbfb8aa3b, v43
	v_exp_f32_e32 v44, v44
	v_exp_f32_e32 v40, v40
	v_exp_f32_e32 v45, v45
	v_exp_f32_e32 v41, v41
	v_exp_f32_e32 v46, v46
	v_exp_f32_e32 v42, v42
	v_exp_f32_e32 v47, v47
	v_exp_f32_e32 v43, v43
	v_add_f32_e32 v44, 1.0, v44
	v_add_f32_e32 v40, 1.0, v40
	v_add_f32_e32 v45, 1.0, v45
	v_add_f32_e32 v41, 1.0, v41
	v_add_f32_e32 v46, 1.0, v46
	v_add_f32_e32 v42, 1.0, v42
	v_add_f32_e32 v47, 1.0, v47
	v_add_f32_e32 v43, 1.0, v43
	v_rcp_f32_e32 v44, v44
	v_rcp_f32_e32 v40, v40
	v_rcp_f32_e32 v45, v45
	v_rcp_f32_e32 v41, v41
	v_rcp_f32_e32 v46, v46
	v_rcp_f32_e32 v42, v42
	v_rcp_f32_e32 v47, v47
	v_rcp_f32_e32 v43, v43
	v_mul_f32_e32 v36, 0xbfb8aa3b, v36
	v_mul_f32_e32 v32, 0xbfb8aa3b, v32
	v_mul_f32_e32 v37, 0xbfb8aa3b, v37
	v_mul_f32_e32 v33, 0xbfb8aa3b, v33
	v_mul_f32_e32 v38, 0xbfb8aa3b, v38
	v_mul_f32_e32 v34, 0xbfb8aa3b, v34
	v_exp_f32_e32 v36, v36
	v_mul_f32_e32 v35, 0xbfb8aa3b, v35
	v_exp_f32_e32 v37, v37
	v_exp_f32_e32 v38, v38
	v_exp_f32_e32 v34, v34
	v_exp_f32_e32 v35, v35
	v_mul_f32_e32 v39, 0xbfb8aa3b, v39
	v_exp_f32_e32 v39, v39
	v_add_f32_e32 v36, 1.0, v36
	v_add_f32_e32 v37, 1.0, v37
	v_add_f32_e32 v38, 1.0, v38
	v_add_f32_e32 v34, 1.0, v34
	v_rcp_f32_e32 v36, v36
	v_add_f32_e32 v35, 1.0, v35
	v_rcp_f32_e32 v37, v37
	v_rcp_f32_e32 v38, v38
	v_rcp_f32_e32 v34, v34
	v_rcp_f32_e32 v35, v35
	v_add_f32_e32 v39, 1.0, v39
	v_rcp_f32_e32 v39, v39
	s_nop 0
	v_lshlrev_b32_e32 v56, 16, v48
	v_and_b32_e32 v48, 0xffff0000, v48
	v_lshlrev_b32_e32 v57, 16, v49
	v_and_b32_e32 v49, 0xffff0000, v49
	v_lshlrev_b32_e32 v58, 16, v50
	v_and_b32_e32 v50, 0xffff0000, v50
	v_lshlrev_b32_e32 v59, 16, v51
	v_and_b32_e32 v51, 0xffff0000, v51
	v_mul_f32_e32 v56, v44, v56
	v_mul_f32_e32 v58, v40, v58
	v_mul_f32_e32 v48, v45, v48
	v_mul_f32_e32 v50, v41, v50
	v_mul_f32_e32 v57, v46, v57
	v_mul_f32_e32 v59, v42, v59
	v_mul_f32_e32 v49, v47, v49
	v_mul_f32_e32 v51, v43, v51
	v_cvt_pk_bf16_f32 v40, v56, v48
	v_cvt_pk_bf16_f32 v41, v57, v49
	v_cvt_pk_bf16_f32 v42, v58, v50
	v_cvt_pk_bf16_f32 v43, v59, v51
	s_nop 1
	v_mov_b64_e32 v[44:45], v[222:223]
	v_mov_b64_e32 v[46:47], v[224:225]
	v_exp_f32_e32 v54, v32
	v_exp_f32_e32 v55, v33
	v_lshlrev_b64 v[32:33], 11, v[52:53]
	v_mul_f32_e32 v50, v50, v50
	v_add_f32_e32 v52, 1.0, v54
	v_mul_f32_e32 v54, v58, v58
	v_add_f32_e32 v53, 1.0, v55
	v_rcp_f32_e32 v52, v52
	v_mul_f32_e32 v55, v59, v59
	v_fmac_f32_e32 v54, v56, v56
	v_fmac_f32_e32 v50, v48, v48
	v_rcp_f32_e32 v53, v53
	v_mul_f32_e32 v51, v51, v51
	v_fmac_f32_e32 v55, v57, v57
	v_add_f32_e32 v48, v54, v50
	v_fmac_f32_e32 v51, v49, v49
	v_add_f32_e32 v48, v55, v48
	v_add_f32_e32 v48, v51, v48
	v_lshl_add_u64 v[32:33], s[58:59], 0, v[32:33]
	s_nop 0
	v_lshlrev_b32_e32 v49, 16, v44
	v_lshlrev_b32_e32 v51, 16, v46
	v_and_b32_e32 v44, 0xffff0000, v44
	v_lshlrev_b32_e32 v50, 16, v45
	v_and_b32_e32 v46, 0xffff0000, v46
	v_lshlrev_b32_e32 v54, 16, v47
	v_mul_f32_e32 v36, v36, v49
	v_mul_f32_e32 v49, v52, v51
	v_and_b32_e32 v47, 0xffff0000, v47
	v_mul_f32_e32 v37, v37, v44
	v_mul_f32_e32 v44, v53, v46
	v_mul_f32_e32 v46, v38, v50
	v_mul_f32_e32 v50, v34, v54
	v_mul_f32_e32 v34, v49, v49
	v_mul_f32_e32 v47, v35, v47
	v_mul_f32_e32 v35, v44, v44
	v_fmac_f32_e32 v34, v36, v36
	v_and_b32_e32 v45, 0xffff0000, v45
	v_mul_f32_e32 v38, v50, v50
	v_fmac_f32_e32 v35, v37, v37
	v_add_f32_e32 v34, v48, v34
	v_mul_f32_e32 v45, v39, v45
	v_mul_f32_e32 v39, v47, v47
	v_fmac_f32_e32 v38, v46, v46
	v_add_f32_e32 v34, v35, v34
	v_add_f32_e32 v34, v38, v34
	v_fmac_f32_e32 v39, v45, v45
	v_add_f32_e32 v35, v39, v34
	v_mov_b32_e32 v48, v35
	v_mov_b32_e32 v254, v35
	s_nop 1
	v_permlane16_swap_b32_e32 v48, v254
	v_lshl_add_u64 v[38:39], v[32:33], 0, v[140:141]
	global_store_dwordx4 v[38:39], v[40:43], off
	v_cvt_pk_bf16_f32 v34, v36, v37
	s_waitcnt lgkmcnt(0)
	v_add_f32_e32 v32, v254, v48
	v_mov_b32_e32 v33, v32
	v_mov_b32_e32 v254, v32
	s_nop 1
	v_permlane32_swap_b32_e32 v33, v254
	v_cvt_pk_bf16_f32 v35, v46, v45
	v_cvt_pk_bf16_f32 v36, v49, v44
	v_cvt_pk_bf16_f32 v37, v50, v47
	global_store_dwordx4 v[38:39], v[34:37], off offset:256
	s_and_saveexec_b64 s[4:5], s[0:1]
	s_cbranch_execz .LBB0_602
	s_waitcnt lgkmcnt(0)
	v_add_f32_e32 v32, v254, v33
	flat_atomic_add_f32 v[114:115], v32 offset:576
; #define GAS __attribute__((address_space(1)))
;     __device__ __forceinline__ void operator()(const Acc& acc, const Unit& u, int wr, int wc, int fr, int fq) const {
;         const int row0 = u.pm * 256 + wr * 64 + fr, col0 = u.pn * 256 + wc * 32 + 8 * fq;
; #pragma unroll
;         for (int ai = 0; ai < 2; ++ai)
; #pragma unroll
;             for (int m = 0; m < 4; ++m) {
;                 const int r = row0 + ai * 128 + m * 16; float ssum = 0.f;
; #pragma unroll
;                 for (int bj = 0; bj < 2; ++bj) {
;                     f32x4 y0, y1; unpack8(*(const GAS u32x4*)(YG + (size_t)r * CH + col0 + bj * 128), y0, y1);
;                     f32x4 z0 = acc[ai][bj][m][0], z1 = acc[ai][bj][m][1];
; #pragma unroll
;                     for (int e = 0; e < 4; ++e) { y0[e] = y0[e] * __builtin_amdgcn_rcpf(1.0f + __expf(-z0[e])); y1[e] = y1[e] * __builtin_amdgcn_rcpf(1.0f + __expf(-z1[e]));
;                         ssum += y0[e] * y0[e] + y1[e] * y1[e]; }
;                     store8_bf16(YCAT + (size_t)r * D + col0 + bj * 128, y0, y1);
;                 }
;                 ssum += __shfl_xor(ssum, 16); ssum += __shfl_xor(ssum, 32);
;                 if (fq == 0) atomicAdd(ssb + r, ssum);
;             }
;     }
.LBB0_602:
	s_or_b64 exec, exec, s[4:5]
	v_add_u32_e32 v36, 0xa0, v142
	v_ashrrev_i32_e32 v37, 31, v36
	s_waitcnt lgkmcnt(0)
	v_lshlrev_b64 v[32:33], 10, v[36:37]
	v_lshl_add_u64 v[32:33], s[52:53], 0, v[32:33]
	v_lshl_add_u64 v[38:39], v[32:33], 0, v[140:141]
	s_nop 1
	v_mov_b64_e32 v[32:33], v[226:227]
	v_mov_b64_e32 v[34:35], v[228:229]
	v_mul_f32_e32 v28, 0xbfb8aa3b, v28
	v_mul_f32_e32 v24, 0xbfb8aa3b, v24
	v_mul_f32_e32 v29, 0xbfb8aa3b, v29
	v_mul_f32_e32 v25, 0xbfb8aa3b, v25
	v_mul_f32_e32 v30, 0xbfb8aa3b, v30
	v_mul_f32_e32 v26, 0xbfb8aa3b, v26
	v_mul_f32_e32 v31, 0xbfb8aa3b, v31
	v_mul_f32_e32 v27, 0xbfb8aa3b, v27
	v_exp_f32_e32 v28, v28
	v_exp_f32_e32 v24, v24
	v_exp_f32_e32 v29, v29
	v_exp_f32_e32 v25, v25
	v_exp_f32_e32 v30, v30
	v_exp_f32_e32 v26, v26
	v_exp_f32_e32 v31, v31
	v_exp_f32_e32 v27, v27
	v_add_f32_e32 v28, 1.0, v28
	v_add_f32_e32 v24, 1.0, v24
	v_add_f32_e32 v29, 1.0, v29
	v_add_f32_e32 v25, 1.0, v25
	v_add_f32_e32 v30, 1.0, v30
	v_add_f32_e32 v26, 1.0, v26
	v_add_f32_e32 v31, 1.0, v31
	v_add_f32_e32 v27, 1.0, v27
	v_rcp_f32_e32 v28, v28
	v_rcp_f32_e32 v24, v24
	v_rcp_f32_e32 v29, v29
	v_rcp_f32_e32 v25, v25
	v_rcp_f32_e32 v30, v30
	v_rcp_f32_e32 v26, v26
	v_rcp_f32_e32 v31, v31
	v_rcp_f32_e32 v27, v27
	v_mul_f32_e32 v20, 0xbfb8aa3b, v20
	v_mul_f32_e32 v16, 0xbfb8aa3b, v16
	v_mul_f32_e32 v21, 0xbfb8aa3b, v21
	v_mul_f32_e32 v17, 0xbfb8aa3b, v17
	v_mul_f32_e32 v22, 0xbfb8aa3b, v22
	v_mul_f32_e32 v18, 0xbfb8aa3b, v18
	v_exp_f32_e32 v20, v20
	v_mul_f32_e32 v19, 0xbfb8aa3b, v19
	v_exp_f32_e32 v21, v21
	v_exp_f32_e32 v22, v22
	v_exp_f32_e32 v18, v18
	v_exp_f32_e32 v19, v19
	v_mul_f32_e32 v23, 0xbfb8aa3b, v23
	v_exp_f32_e32 v23, v23
	v_add_f32_e32 v20, 1.0, v20
	v_add_f32_e32 v21, 1.0, v21
	v_add_f32_e32 v22, 1.0, v22
	v_add_f32_e32 v18, 1.0, v18
	v_rcp_f32_e32 v20, v20
	v_add_f32_e32 v19, 1.0, v19
	v_rcp_f32_e32 v21, v21
	v_rcp_f32_e32 v22, v22
	v_rcp_f32_e32 v18, v18
	v_rcp_f32_e32 v19, v19
	v_add_f32_e32 v23, 1.0, v23
	v_rcp_f32_e32 v23, v23
	s_nop 0
	v_lshlrev_b32_e32 v40, 16, v32
	v_and_b32_e32 v32, 0xffff0000, v32
	v_lshlrev_b32_e32 v41, 16, v33
	v_and_b32_e32 v33, 0xffff0000, v33
	v_lshlrev_b32_e32 v42, 16, v34
	v_and_b32_e32 v34, 0xffff0000, v34
	v_lshlrev_b32_e32 v43, 16, v35
	v_and_b32_e32 v35, 0xffff0000, v35
	v_mul_f32_e32 v40, v28, v40
	v_mul_f32_e32 v42, v24, v42
	v_mul_f32_e32 v32, v29, v32
	v_mul_f32_e32 v34, v25, v34
	v_mul_f32_e32 v41, v30, v41
	v_mul_f32_e32 v43, v26, v43
	v_mul_f32_e32 v33, v31, v33
	v_mul_f32_e32 v35, v27, v35
	v_cvt_pk_bf16_f32 v24, v40, v32
	v_cvt_pk_bf16_f32 v25, v41, v33
	v_cvt_pk_bf16_f32 v26, v42, v34
	v_cvt_pk_bf16_f32 v27, v43, v35
	s_nop 1
	v_mov_b64_e32 v[28:29], v[230:231]
	v_mov_b64_e32 v[30:31], v[232:233]
	v_exp_f32_e32 v38, v16
	v_exp_f32_e32 v39, v17
	v_lshlrev_b64 v[16:17], 11, v[36:37]
	v_mul_f32_e32 v34, v34, v34
	v_add_f32_e32 v36, 1.0, v38
	v_mul_f32_e32 v38, v42, v42
	v_add_f32_e32 v37, 1.0, v39
	v_rcp_f32_e32 v36, v36
	v_mul_f32_e32 v39, v43, v43
	v_fmac_f32_e32 v38, v40, v40
	v_fmac_f32_e32 v34, v32, v32
	v_rcp_f32_e32 v37, v37
	v_mul_f32_e32 v35, v35, v35
	v_fmac_f32_e32 v39, v41, v41
	v_add_f32_e32 v32, v38, v34
	v_fmac_f32_e32 v35, v33, v33
	v_add_f32_e32 v32, v39, v32
	v_add_f32_e32 v32, v35, v32
	v_lshl_add_u64 v[16:17], s[58:59], 0, v[16:17]
	s_nop 0
	v_lshlrev_b32_e32 v33, 16, v28
	v_lshlrev_b32_e32 v35, 16, v30
	v_and_b32_e32 v28, 0xffff0000, v28
	v_lshlrev_b32_e32 v34, 16, v29
	v_and_b32_e32 v30, 0xffff0000, v30
	v_lshlrev_b32_e32 v38, 16, v31
	v_mul_f32_e32 v20, v20, v33
	v_mul_f32_e32 v33, v36, v35
	v_and_b32_e32 v31, 0xffff0000, v31
	v_mul_f32_e32 v21, v21, v28
	v_mul_f32_e32 v28, v37, v30
	v_mul_f32_e32 v30, v22, v34
	v_mul_f32_e32 v34, v18, v38
	v_mul_f32_e32 v18, v33, v33
	v_mul_f32_e32 v31, v19, v31
	v_mul_f32_e32 v19, v28, v28
	v_fmac_f32_e32 v18, v20, v20
	v_and_b32_e32 v29, 0xffff0000, v29
	v_mul_f32_e32 v22, v34, v34
	v_fmac_f32_e32 v19, v21, v21
	v_add_f32_e32 v18, v32, v18
	v_mul_f32_e32 v29, v23, v29
	v_mul_f32_e32 v23, v31, v31
	v_fmac_f32_e32 v22, v30, v30
	v_add_f32_e32 v18, v19, v18
	v_add_f32_e32 v18, v22, v18
	v_fmac_f32_e32 v23, v29, v29
	v_add_f32_e32 v19, v23, v18
	v_mov_b32_e32 v32, v19
	v_mov_b32_e32 v254, v19
	s_nop 1
	v_permlane16_swap_b32_e32 v32, v254
	v_lshl_add_u64 v[22:23], v[16:17], 0, v[140:141]
	global_store_dwordx4 v[22:23], v[24:27], off
	v_cvt_pk_bf16_f32 v18, v20, v21
	s_waitcnt lgkmcnt(0)
	v_add_f32_e32 v16, v254, v32
	v_mov_b32_e32 v17, v16
	v_mov_b32_e32 v254, v16
	s_nop 1
	v_permlane32_swap_b32_e32 v17, v254
	v_cvt_pk_bf16_f32 v19, v30, v29
	v_cvt_pk_bf16_f32 v20, v33, v28
	v_cvt_pk_bf16_f32 v21, v34, v31
	global_store_dwordx4 v[22:23], v[18:21], off offset:256
	s_and_saveexec_b64 s[4:5], s[0:1]
	s_cbranch_execz .LBB0_604
	s_waitcnt lgkmcnt(0)
	v_add_f32_e32 v16, v254, v17
	flat_atomic_add_f32 v[114:115], v16 offset:640
; #define GAS __attribute__((address_space(1)))
;     __device__ __forceinline__ void operator()(const Acc& acc, const Unit& u, int wr, int wc, int fr, int fq) const {
;         const int row0 = u.pm * 256 + wr * 64 + fr, col0 = u.pn * 256 + wc * 32 + 8 * fq;
; #pragma unroll
;         for (int ai = 0; ai < 2; ++ai)
; #pragma unroll
;             for (int m = 0; m < 4; ++m) {
;                 const int r = row0 + ai * 128 + m * 16; float ssum = 0.f;
; #pragma unroll
;                 for (int bj = 0; bj < 2; ++bj) {
;                     f32x4 y0, y1; unpack8(*(const GAS u32x4*)(YG + (size_t)r * CH + col0 + bj * 128), y0, y1);
;                     f32x4 z0 = acc[ai][bj][m][0], z1 = acc[ai][bj][m][1];
; #pragma unroll
;                     for (int e = 0; e < 4; ++e) { y0[e] = y0[e] * __builtin_amdgcn_rcpf(1.0f + __expf(-z0[e])); y1[e] = y1[e] * __builtin_amdgcn_rcpf(1.0f + __expf(-z1[e]));
;                         ssum += y0[e] * y0[e] + y1[e] * y1[e]; }
;                     store8_bf16(YCAT + (size_t)r * D + col0 + bj * 128, y0, y1);
;                 }
;                 ssum += __shfl_xor(ssum, 16); ssum += __shfl_xor(ssum, 32);
;                 if (fq == 0) atomicAdd(ssb + r, ssum);
;             }
;     }
.LBB0_604:
	s_or_b64 exec, exec, s[4:5]
	v_add_u32_e32 v20, 0xb0, v142
	v_ashrrev_i32_e32 v21, 31, v20
	s_waitcnt lgkmcnt(0)
	v_lshlrev_b64 v[16:17], 10, v[20:21]
	v_lshl_add_u64 v[16:17], s[52:53], 0, v[16:17]
	v_lshl_add_u64 v[22:23], v[16:17], 0, v[140:141]
	s_nop 1
	v_mov_b64_e32 v[16:17], v[234:235]
	v_mov_b64_e32 v[18:19], v[236:237]
	v_mul_f32_e32 v12, 0xbfb8aa3b, v12
	v_mul_f32_e32 v8, 0xbfb8aa3b, v8
	v_mul_f32_e32 v13, 0xbfb8aa3b, v13
	v_mul_f32_e32 v9, 0xbfb8aa3b, v9
	v_mul_f32_e32 v14, 0xbfb8aa3b, v14
	v_mul_f32_e32 v10, 0xbfb8aa3b, v10
	v_mul_f32_e32 v15, 0xbfb8aa3b, v15
	v_mul_f32_e32 v11, 0xbfb8aa3b, v11
	v_exp_f32_e32 v12, v12
	v_exp_f32_e32 v8, v8
	v_exp_f32_e32 v13, v13
	v_exp_f32_e32 v9, v9
	v_exp_f32_e32 v14, v14
	v_exp_f32_e32 v10, v10
	v_exp_f32_e32 v15, v15
	v_exp_f32_e32 v11, v11
	v_add_f32_e32 v12, 1.0, v12
	v_add_f32_e32 v8, 1.0, v8
	v_add_f32_e32 v13, 1.0, v13
	v_add_f32_e32 v9, 1.0, v9
	v_add_f32_e32 v14, 1.0, v14
	v_add_f32_e32 v10, 1.0, v10
	v_add_f32_e32 v15, 1.0, v15
	v_add_f32_e32 v11, 1.0, v11
	v_rcp_f32_e32 v12, v12
	v_rcp_f32_e32 v8, v8
	v_rcp_f32_e32 v13, v13
	v_rcp_f32_e32 v9, v9
	v_rcp_f32_e32 v14, v14
	v_rcp_f32_e32 v10, v10
	v_rcp_f32_e32 v15, v15
	v_rcp_f32_e32 v11, v11
	v_mul_f32_e32 v4, 0xbfb8aa3b, v4
	v_mul_f32_e32 v0, 0xbfb8aa3b, v0
	v_mul_f32_e32 v5, 0xbfb8aa3b, v5
	v_mul_f32_e32 v1, 0xbfb8aa3b, v1
	v_mul_f32_e32 v6, 0xbfb8aa3b, v6
	v_mul_f32_e32 v2, 0xbfb8aa3b, v2
	v_exp_f32_e32 v4, v4
	v_mul_f32_e32 v3, 0xbfb8aa3b, v3
	v_exp_f32_e32 v5, v5
	v_exp_f32_e32 v6, v6
	v_exp_f32_e32 v2, v2
	v_exp_f32_e32 v3, v3
	v_mul_f32_e32 v7, 0xbfb8aa3b, v7
	v_exp_f32_e32 v7, v7
	v_add_f32_e32 v4, 1.0, v4
	v_add_f32_e32 v5, 1.0, v5
	v_add_f32_e32 v6, 1.0, v6
	v_add_f32_e32 v2, 1.0, v2
	v_rcp_f32_e32 v4, v4
	v_add_f32_e32 v3, 1.0, v3
	v_rcp_f32_e32 v5, v5
	v_rcp_f32_e32 v6, v6
	v_rcp_f32_e32 v2, v2
	v_rcp_f32_e32 v3, v3
	v_add_f32_e32 v7, 1.0, v7
	v_rcp_f32_e32 v7, v7
	s_nop 0
	v_lshlrev_b32_e32 v24, 16, v16
	v_and_b32_e32 v16, 0xffff0000, v16
	v_lshlrev_b32_e32 v25, 16, v17
	v_and_b32_e32 v17, 0xffff0000, v17
	v_lshlrev_b32_e32 v26, 16, v18
	v_and_b32_e32 v18, 0xffff0000, v18
	v_lshlrev_b32_e32 v27, 16, v19
	v_and_b32_e32 v19, 0xffff0000, v19
	v_mul_f32_e32 v24, v12, v24
	v_mul_f32_e32 v26, v8, v26
	v_mul_f32_e32 v16, v13, v16
	v_mul_f32_e32 v18, v9, v18
	v_mul_f32_e32 v25, v14, v25
	v_mul_f32_e32 v27, v10, v27
	v_mul_f32_e32 v17, v15, v17
	v_mul_f32_e32 v19, v11, v19
	v_cvt_pk_bf16_f32 v8, v24, v16
	v_cvt_pk_bf16_f32 v9, v25, v17
	v_cvt_pk_bf16_f32 v10, v26, v18
	v_cvt_pk_bf16_f32 v11, v27, v19
	s_nop 1
	v_mov_b64_e32 v[12:13], v[238:239]
	v_mov_b64_e32 v[14:15], v[240:241]
	v_exp_f32_e32 v22, v0
	v_exp_f32_e32 v23, v1
	v_lshlrev_b64 v[0:1], 11, v[20:21]
	v_mul_f32_e32 v18, v18, v18
	v_add_f32_e32 v20, 1.0, v22
	v_mul_f32_e32 v22, v26, v26
	v_add_f32_e32 v21, 1.0, v23
	v_rcp_f32_e32 v20, v20
	v_mul_f32_e32 v23, v27, v27
	v_fmac_f32_e32 v22, v24, v24
	v_fmac_f32_e32 v18, v16, v16
	v_rcp_f32_e32 v21, v21
	v_mul_f32_e32 v19, v19, v19
	v_fmac_f32_e32 v23, v25, v25
	v_add_f32_e32 v16, v22, v18
	v_fmac_f32_e32 v19, v17, v17
	v_add_f32_e32 v16, v23, v16
	v_add_f32_e32 v16, v19, v16
	v_lshl_add_u64 v[0:1], s[58:59], 0, v[0:1]
	s_nop 0
	v_lshlrev_b32_e32 v17, 16, v12
	v_lshlrev_b32_e32 v19, 16, v14
	v_and_b32_e32 v12, 0xffff0000, v12
	v_lshlrev_b32_e32 v18, 16, v13
	v_and_b32_e32 v14, 0xffff0000, v14
	v_lshlrev_b32_e32 v22, 16, v15
	v_mul_f32_e32 v4, v4, v17
	v_mul_f32_e32 v17, v20, v19
	v_and_b32_e32 v15, 0xffff0000, v15
	v_mul_f32_e32 v5, v5, v12
	v_mul_f32_e32 v12, v21, v14
	v_mul_f32_e32 v14, v6, v18
	v_mul_f32_e32 v18, v2, v22
	v_mul_f32_e32 v2, v17, v17
	v_mul_f32_e32 v15, v3, v15
	v_mul_f32_e32 v3, v12, v12
	v_fmac_f32_e32 v2, v4, v4
	v_and_b32_e32 v13, 0xffff0000, v13
	v_mul_f32_e32 v6, v18, v18
	v_fmac_f32_e32 v3, v5, v5
	v_add_f32_e32 v2, v16, v2
	v_mul_f32_e32 v13, v7, v13
	v_mul_f32_e32 v7, v15, v15
	v_fmac_f32_e32 v6, v14, v14
	v_add_f32_e32 v2, v3, v2
	v_add_f32_e32 v2, v6, v2
	v_fmac_f32_e32 v7, v13, v13
	v_add_f32_e32 v3, v7, v2
	v_mov_b32_e32 v16, v3
	v_mov_b32_e32 v254, v3
	s_nop 1
	v_permlane16_swap_b32_e32 v16, v254
	v_lshl_add_u64 v[6:7], v[0:1], 0, v[140:141]
	global_store_dwordx4 v[6:7], v[8:11], off
	v_cvt_pk_bf16_f32 v2, v4, v5
	s_waitcnt lgkmcnt(0)
	v_add_f32_e32 v0, v254, v16
	v_mov_b32_e32 v1, v0
	v_mov_b32_e32 v254, v0
	s_nop 1
	v_permlane32_swap_b32_e32 v1, v254
	v_cvt_pk_bf16_f32 v3, v14, v13
	v_cvt_pk_bf16_f32 v4, v17, v12
	v_cvt_pk_bf16_f32 v5, v18, v15
	global_store_dwordx4 v[6:7], v[2:5], off offset:256
	s_and_saveexec_b64 s[4:5], s[0:1]
	s_cbranch_execz .LBB0_606
	s_waitcnt lgkmcnt(0)
	v_add_f32_e32 v0, v254, v1
	flat_atomic_add_f32 v[114:115], v0 offset:704

; #define GAS __attribute__((address_space(1)))
;     __device__ __forceinline__ void operator()(const Acc& acc, const Unit& u, int wr, int wc, int fr, int fq) const {
;         const int row0 = u.pm * 256 + wr * 64 + fr, col0 = u.pn * 256 + wc * 32 + 8 * fq;
; #pragma unroll
;         for (int ai = 0; ai < 2; ++ai)
; #pragma unroll
;             for (int m = 0; m < 4; ++m) {
;                 const int r = row0 + ai * 128 + m * 16; float ssum = 0.f;
; #pragma unroll
;                 for (int bj = 0; bj < 2; ++bj) {
;                     bf16_t* p = XB + (size_t)r * D + col0 + bj * 128;
;                     f32x4 x0, x1; unpack8(*(const GAS u32x4*)p, x0, x1);
;                     x0 += acc[ai][bj][m][0]; x1 += acc[ai][bj][m][1];
; #pragma unroll
;                     for (int e = 0; e < 4; ++e) ssum += x0[e] * x0[e] + x1[e] * x1[e];
;                     store8_bf16(p, x0, x1);
;                 }
;                 ssum += __shfl_xor(ssum, 16); ssum += __shfl_xor(ssum, 32);
;                 if (fq == 0) atomicAdd(ssout + r, ssum);
;             }
;     }
.LBB0_678:
	v_lshl_or_b32 v146, s4, 8, v154
	v_lshlrev_b64 v[66:67], 11, v[144:145]
	v_ashrrev_i32_e32 v147, 31, v146
	v_lshl_add_u64 v[66:67], s[56:57], 0, v[66:67]
	v_lshl_add_u64 v[66:67], v[146:147], 1, v[66:67]
	global_load_dwordx4 v[148:151], v[66:67], off
	global_load_dwordx4 v[160:163], v[66:67], off offset:256
	v_add_co_u32_e32 v192, vcc, 0x8000, v66
	s_nop 1
	v_addc_co_u32_e32 v193, vcc, 0, v67, vcc
	global_load_dwordx4 v[164:167], v[192:193], off
	global_load_dwordx4 v[168:171], v[192:193], off offset:256
	v_add_co_u32_e32 v192, vcc, 0x10000, v66
	s_nop 1
	v_addc_co_u32_e32 v193, vcc, 0, v67, vcc
	global_load_dwordx4 v[172:175], v[192:193], off
	global_load_dwordx4 v[176:179], v[192:193], off offset:256
	v_add_co_u32_e32 v192, vcc, 0x18000, v66
	s_nop 1
	v_addc_co_u32_e32 v193, vcc, 0, v67, vcc
	global_load_dwordx4 v[180:183], v[192:193], off
	global_load_dwordx4 v[184:187], v[192:193], off offset:256
	v_add_co_u32_e32 v192, vcc, 0x40000, v66
	s_nop 1
	v_addc_co_u32_e32 v193, vcc, 0, v67, vcc
	global_load_dwordx4 v[188:191], v[192:193], off
	global_load_dwordx4 v[214:217], v[192:193], off offset:256
	v_add_co_u32_e32 v192, vcc, 0x48000, v66
	s_nop 1
	v_addc_co_u32_e32 v193, vcc, 0, v67, vcc
	global_load_dwordx4 v[218:221], v[192:193], off
	global_load_dwordx4 v[222:225], v[192:193], off offset:256
	v_add_co_u32_e32 v192, vcc, 0x50000, v66
	s_nop 1
	v_addc_co_u32_e32 v193, vcc, 0, v67, vcc
	global_load_dwordx4 v[226:229], v[192:193], off
	global_load_dwordx4 v[230:233], v[192:193], off offset:256
	v_add_co_u32_e32 v192, vcc, 0x58000, v66
	s_nop 1
	v_addc_co_u32_e32 v193, vcc, 0, v67, vcc
	global_load_dwordx4 v[234:237], v[192:193], off
	global_load_dwordx4 v[238:241], v[192:193], off offset:256
	s_waitcnt vmcnt(8)
	v_lshlrev_b32_e32 v156, 16, v148
	v_and_b32_e32 v157, 0xffff0000, v148
	v_lshlrev_b32_e32 v148, 16, v149
	v_and_b32_e32 v149, 0xffff0000, v149
	v_lshlrev_b32_e32 v158, 16, v150
	v_and_b32_e32 v159, 0xffff0000, v150
	v_lshlrev_b32_e32 v150, 16, v151
	v_and_b32_e32 v151, 0xffff0000, v151
	v_pk_add_f32 v[130:131], v[130:131], v[148:149]
	v_pk_add_f32 v[148:149], v[126:127], v[150:151]
	v_pk_add_f32 v[126:127], v[124:125], v[158:159]
	v_pk_add_f32 v[128:129], v[128:129], v[156:157]
	v_mul_f32_e32 v64, v126, v126
	v_mul_f32_e32 v124, v127, v127
	v_fmac_f32_e32 v64, v128, v128
	v_fmac_f32_e32 v124, v129, v129
	v_add_f32_e32 v64, v64, v124
	v_mul_f32_e32 v124, v148, v148
	v_fmac_f32_e32 v124, v130, v130
	v_add_f32_e32 v64, v124, v64
	v_mul_f32_e32 v124, v149, v149
	v_fmac_f32_e32 v124, v131, v131
	v_add_f32_e32 v64, v124, v64
	v_cvt_pk_bf16_f32 v124, v128, v129
	v_cvt_pk_bf16_f32 v125, v130, v131
	v_cvt_pk_bf16_f32 v126, v126, v127
	v_cvt_pk_bf16_f32 v127, v148, v149
	global_store_dwordx4 v[66:67], v[124:127], off
	s_nop 1
	v_mov_b64_e32 v[124:125], v[160:161]
	v_mov_b64_e32 v[126:127], v[162:163]
	s_nop 0
	v_lshlrev_b32_e32 v128, 16, v124
	v_and_b32_e32 v129, 0xffff0000, v124
	v_lshlrev_b32_e32 v124, 16, v125
	v_and_b32_e32 v125, 0xffff0000, v125
	v_lshlrev_b32_e32 v130, 16, v126
	v_and_b32_e32 v131, 0xffff0000, v126
	v_lshlrev_b32_e32 v126, 16, v127
	v_and_b32_e32 v127, 0xffff0000, v127
	v_pk_add_f32 v[122:123], v[122:123], v[124:125]
	v_pk_add_f32 v[124:125], v[118:119], v[126:127]
	v_pk_add_f32 v[118:119], v[116:117], v[130:131]
	v_pk_add_f32 v[120:121], v[120:121], v[128:129]
	v_mul_f32_e32 v116, v118, v118
	v_fmac_f32_e32 v116, v120, v120
	v_add_f32_e32 v64, v64, v116
	v_mul_f32_e32 v116, v119, v119
	v_fmac_f32_e32 v116, v121, v121
	v_add_f32_e32 v64, v116, v64
	v_mul_f32_e32 v116, v124, v124
	v_fmac_f32_e32 v116, v122, v122
	v_add_f32_e32 v64, v116, v64
	v_mul_f32_e32 v116, v125, v125
	v_fmac_f32_e32 v116, v123, v123
	v_add_f32_e32 v126, v116, v64
	v_cvt_pk_bf16_f32 v116, v120, v121
	v_cvt_pk_bf16_f32 v117, v122, v123
	v_cvt_pk_bf16_f32 v118, v118, v119
	v_cvt_pk_bf16_f32 v119, v124, v125
	global_store_dwordx4 v[66:67], v[116:119], off offset:256
	v_xor_b32_e32 v64, 16, v246
	s_nop 0
	v_add_u32_e32 v116, 64, v247
	v_cmp_lt_i32_e32 vcc, v64, v116
	s_nop 1
	v_cndmask_b32_e32 v64, v246, v64, vcc
	v_lshlrev_b32_e32 v64, 2, v64
	v_mov_b32_e32 v117, v126
	v_mov_b32_e32 v254, v126
	s_nop 1
	v_permlane16_swap_b32_e32 v117, v254
	s_waitcnt lgkmcnt(0)
	v_add_f32_e32 v119, v254, v117
	v_xor_b32_e32 v117, 32, v246
	v_cmp_lt_i32_e32 vcc, v117, v116
	s_nop 1
	v_cndmask_b32_e32 v116, v246, v117, vcc
	v_lshlrev_b32_e32 v118, 2, v116
	v_mov_b32_e32 v120, v119
	v_mov_b32_e32 v254, v119
	s_nop 1
	v_permlane32_swap_b32_e32 v120, v254
	v_lshl_add_u64 v[116:117], v[144:145], 2, s[58:59]
	s_and_saveexec_b64 s[4:5], s[0:1]
	v_readlane_b32 s96, v255, 38
	v_readlane_b32 s97, v255, 39
	s_mov_b64 s[10:11], 0x40000
	s_cbranch_execz .LBB0_680
	s_waitcnt lgkmcnt(0)
	v_add_f32_e32 v119, v254, v120
	flat_atomic_add_f32 v[116:117], v119
; #define GAS __attribute__((address_space(1)))
;     __device__ __forceinline__ void operator()(const Acc& acc, const Unit& u, int wr, int wc, int fr, int fq) const {
;         const int row0 = u.pm * 256 + wr * 64 + fr, col0 = u.pn * 256 + wc * 32 + 8 * fq;
; #pragma unroll
;         for (int ai = 0; ai < 2; ++ai)
; #pragma unroll
;             for (int m = 0; m < 4; ++m) {
;                 const int r = row0 + ai * 128 + m * 16; float ssum = 0.f;
; #pragma unroll
;                 for (int bj = 0; bj < 2; ++bj) {
;                     bf16_t* p = XB + (size_t)r * D + col0 + bj * 128;
;                     f32x4 x0, x1; unpack8(*(const GAS u32x4*)p, x0, x1);
;                     x0 += acc[ai][bj][m][0]; x1 += acc[ai][bj][m][1];
; #pragma unroll
;                     for (int e = 0; e < 4; ++e) ssum += x0[e] * x0[e] + x1[e] * x1[e];
;                     store8_bf16(p, x0, x1);
;                 }
;                 ssum += __shfl_xor(ssum, 16); ssum += __shfl_xor(ssum, 32);
;                 if (fq == 0) atomicAdd(ssout + r, ssum);
;             }
;     }
.LBB0_680:
	s_or_b64 exec, exec, s[4:5]
	s_waitcnt lgkmcnt(0)
	v_or_b32_e32 v120, 16, v144
	v_ashrrev_i32_e32 v121, 31, v120
	v_lshlrev_b64 v[120:121], 11, v[120:121]
	v_lshl_add_u64 v[120:121], s[56:57], 0, v[120:121]
	v_lshl_add_u64 v[124:125], v[146:147], 1, v[120:121]
	s_nop 1
	v_mov_b64_e32 v[120:121], v[164:165]
	v_mov_b64_e32 v[122:123], v[166:167]
	s_nop 0
	v_lshlrev_b32_e32 v126, 16, v120
	v_and_b32_e32 v127, 0xffff0000, v120
	v_lshlrev_b32_e32 v120, 16, v121
	v_and_b32_e32 v121, 0xffff0000, v121
	v_lshlrev_b32_e32 v128, 16, v122
	v_and_b32_e32 v129, 0xffff0000, v122
	v_lshlrev_b32_e32 v122, 16, v123
	v_and_b32_e32 v123, 0xffff0000, v123
	v_pk_add_f32 v[120:121], v[114:115], v[120:121]
	v_pk_add_f32 v[126:127], v[112:113], v[126:127]
	v_pk_add_f32 v[122:123], v[110:111], v[122:123]
	v_pk_add_f32 v[128:129], v[108:109], v[128:129]
	v_cvt_pk_bf16_f32 v108, v126, v127
	v_cvt_pk_bf16_f32 v109, v120, v121
	s_nop 0
	v_cvt_pk_bf16_f32 v110, v128, v129
	v_cvt_pk_bf16_f32 v111, v122, v123
	s_nop 1
	v_mov_b64_e32 v[112:113], v[168:169]
	v_mov_b64_e32 v[114:115], v[170:171]
	v_mul_f32_e32 v119, v128, v128
	v_mul_f32_e32 v128, v129, v129
	v_mul_f32_e32 v122, v122, v122
	v_fmac_f32_e32 v119, v126, v126
	v_fmac_f32_e32 v128, v127, v127
	v_mul_f32_e32 v123, v123, v123
	v_fmac_f32_e32 v122, v120, v120
	v_add_f32_e32 v119, v119, v128
	v_fmac_f32_e32 v123, v121, v121
	v_add_f32_e32 v119, v122, v119
	v_add_f32_e32 v119, v123, v119
	global_store_dwordx4 v[124:125], v[108:111], off
	s_nop 0
	v_lshlrev_b32_e32 v120, 16, v112
	v_and_b32_e32 v121, 0xffff0000, v112
	v_lshlrev_b32_e32 v112, 16, v113
	v_and_b32_e32 v113, 0xffff0000, v113
	v_lshlrev_b32_e32 v122, 16, v114
	v_and_b32_e32 v123, 0xffff0000, v114
	v_lshlrev_b32_e32 v114, 16, v115
	v_and_b32_e32 v115, 0xffff0000, v115
	v_pk_add_f32 v[106:107], v[106:107], v[112:113]
	v_pk_add_f32 v[112:113], v[102:103], v[114:115]
	v_pk_add_f32 v[114:115], v[100:101], v[122:123]
	v_pk_add_f32 v[104:105], v[104:105], v[120:121]
	v_mul_f32_e32 v100, v114, v114
	v_mul_f32_e32 v101, v115, v115
	v_fmac_f32_e32 v100, v104, v104
	v_mul_f32_e32 v102, v112, v112
	v_fmac_f32_e32 v101, v105, v105
	v_add_f32_e32 v100, v119, v100
	v_mul_f32_e32 v103, v113, v113
	v_fmac_f32_e32 v102, v106, v106
	v_add_f32_e32 v100, v101, v100
	v_add_f32_e32 v100, v102, v100
	v_fmac_f32_e32 v103, v107, v107
	v_add_f32_e32 v100, v103, v100
	v_mov_b32_e32 v101, v100
	v_mov_b32_e32 v254, v100
	s_nop 1
	v_permlane16_swap_b32_e32 v101, v254
	v_cvt_pk_bf16_f32 v102, v104, v105
	v_cvt_pk_bf16_f32 v103, v106, v107
	v_cvt_pk_bf16_f32 v104, v114, v115
	v_cvt_pk_bf16_f32 v105, v112, v113
	s_waitcnt lgkmcnt(0)
	v_add_f32_e32 v100, v254, v101
	v_mov_b32_e32 v101, v100
	v_mov_b32_e32 v254, v100
	s_nop 1
	v_permlane32_swap_b32_e32 v101, v254
	global_store_dwordx4 v[124:125], v[102:105], off offset:256
	s_and_saveexec_b64 s[4:5], s[0:1]
	s_cbranch_execz .LBB0_682
	s_waitcnt lgkmcnt(0)
	v_add_f32_e32 v100, v254, v101
	flat_atomic_add_f32 v[116:117], v100 offset:64
.LBB0_682:
	s_or_b64 exec, exec, s[4:5]
	v_or_b32_e32 v100, 32, v144
	s_waitcnt lgkmcnt(0)
	v_ashrrev_i32_e32 v101, 31, v100
	v_lshlrev_b64 v[100:101], 11, v[100:101]
	v_lshl_add_u64 v[100:101], s[56:57], 0, v[100:101]
	v_lshl_add_u64 v[104:105], v[146:147], 1, v[100:101]
	s_nop 1
	v_mov_b64_e32 v[100:101], v[172:173]
	v_mov_b64_e32 v[102:103], v[174:175]
	s_nop 0
	v_lshlrev_b32_e32 v106, 16, v100
	v_and_b32_e32 v107, 0xffff0000, v100
	v_lshlrev_b32_e32 v100, 16, v101
	v_and_b32_e32 v101, 0xffff0000, v101
	v_lshlrev_b32_e32 v108, 16, v102
	v_and_b32_e32 v109, 0xffff0000, v102
	v_lshlrev_b32_e32 v102, 16, v103
	v_and_b32_e32 v103, 0xffff0000, v103
	v_pk_add_f32 v[100:101], v[98:99], v[100:101]
	v_pk_add_f32 v[106:107], v[96:97], v[106:107]
	v_pk_add_f32 v[102:103], v[94:95], v[102:103]
	v_pk_add_f32 v[108:109], v[92:93], v[108:109]
	v_cvt_pk_bf16_f32 v92, v106, v107
	v_cvt_pk_bf16_f32 v93, v100, v101
	s_nop 0
	v_cvt_pk_bf16_f32 v94, v108, v109
	v_cvt_pk_bf16_f32 v95, v102, v103
	s_nop 1
	v_mov_b64_e32 v[96:97], v[176:177]
	v_mov_b64_e32 v[98:99], v[178:179]
	v_mul_f32_e32 v108, v108, v108
	v_mul_f32_e32 v109, v109, v109
	v_mul_f32_e32 v102, v102, v102
	v_fmac_f32_e32 v108, v106, v106
	v_fmac_f32_e32 v109, v107, v107
	v_mul_f32_e32 v103, v103, v103
	v_fmac_f32_e32 v102, v100, v100
	v_add_f32_e32 v100, v108, v109
	v_fmac_f32_e32 v103, v101, v101
	v_add_f32_e32 v100, v102, v100
	v_add_f32_e32 v106, v103, v100
	global_store_dwordx4 v[104:105], v[92:95], off
	s_nop 0
	v_lshlrev_b32_e32 v100, 16, v96
	v_and_b32_e32 v101, 0xffff0000, v96
	v_lshlrev_b32_e32 v96, 16, v97
	v_and_b32_e32 v97, 0xffff0000, v97
	v_lshlrev_b32_e32 v102, 16, v98
	v_and_b32_e32 v103, 0xffff0000, v98
	v_lshlrev_b32_e32 v98, 16, v99
	v_and_b32_e32 v99, 0xffff0000, v99
	v_pk_add_f32 v[90:91], v[90:91], v[96:97]
	v_pk_add_f32 v[96:97], v[86:87], v[98:99]
	v_pk_add_f32 v[98:99], v[84:85], v[102:103]
	v_pk_add_f32 v[88:89], v[88:89], v[100:101]
	v_mul_f32_e32 v84, v98, v98
	v_mul_f32_e32 v85, v99, v99
	v_fmac_f32_e32 v84, v88, v88
	v_mul_f32_e32 v86, v96, v96
	v_fmac_f32_e32 v85, v89, v89
	v_add_f32_e32 v84, v106, v84
	v_mul_f32_e32 v87, v97, v97
	v_fmac_f32_e32 v86, v90, v90
	v_add_f32_e32 v84, v85, v84
	v_add_f32_e32 v84, v86, v84
	v_fmac_f32_e32 v87, v91, v91
	v_add_f32_e32 v84, v87, v84
	v_mov_b32_e32 v85, v84
	v_mov_b32_e32 v254, v84
	s_nop 1
	v_permlane16_swap_b32_e32 v85, v254
	v_cvt_pk_bf16_f32 v86, v88, v89
	v_cvt_pk_bf16_f32 v87, v90, v91
	v_cvt_pk_bf16_f32 v88, v98, v99
	v_cvt_pk_bf16_f32 v89, v96, v97
	s_waitcnt lgkmcnt(0)
	v_add_f32_e32 v84, v254, v85
	v_mov_b32_e32 v85, v84
	v_mov_b32_e32 v254, v84
	s_nop 1
	v_permlane32_swap_b32_e32 v85, v254
	global_store_dwordx4 v[104:105], v[86:89], off offset:256
	s_and_saveexec_b64 s[4:5], s[0:1]
	s_cbranch_execz .LBB0_684
	s_waitcnt lgkmcnt(0)
	v_add_f32_e32 v84, v254, v85
	flat_atomic_add_f32 v[116:117], v84 offset:128
; #define GAS __attribute__((address_space(1)))
;     __device__ __forceinline__ void operator()(const Acc& acc, const Unit& u, int wr, int wc, int fr, int fq) const {
;         const int row0 = u.pm * 256 + wr * 64 + fr, col0 = u.pn * 256 + wc * 32 + 8 * fq;
; #pragma unroll
;         for (int ai = 0; ai < 2; ++ai)
; #pragma unroll
;             for (int m = 0; m < 4; ++m) {
;                 const int r = row0 + ai * 128 + m * 16; float ssum = 0.f;
; #pragma unroll
;                 for (int bj = 0; bj < 2; ++bj) {
;                     bf16_t* p = XB + (size_t)r * D + col0 + bj * 128;
;                     f32x4 x0, x1; unpack8(*(const GAS u32x4*)p, x0, x1);
;                     x0 += acc[ai][bj][m][0]; x1 += acc[ai][bj][m][1];
; #pragma unroll
;                     for (int e = 0; e < 4; ++e) ssum += x0[e] * x0[e] + x1[e] * x1[e];
;                     store8_bf16(p, x0, x1);
;                 }
;                 ssum += __shfl_xor(ssum, 16); ssum += __shfl_xor(ssum, 32);
;                 if (fq == 0) atomicAdd(ssout + r, ssum);
;             }
;     }
.LBB0_684:
	s_or_b64 exec, exec, s[4:5]
	v_or_b32_e32 v84, 48, v144
	s_waitcnt lgkmcnt(0)
	v_ashrrev_i32_e32 v85, 31, v84
	v_lshlrev_b64 v[84:85], 11, v[84:85]
	v_lshl_add_u64 v[84:85], s[56:57], 0, v[84:85]
	v_lshl_add_u64 v[88:89], v[146:147], 1, v[84:85]
	s_nop 1
	v_mov_b64_e32 v[84:85], v[180:181]
	v_mov_b64_e32 v[86:87], v[182:183]
	s_nop 0
	v_lshlrev_b32_e32 v90, 16, v84
	v_and_b32_e32 v91, 0xffff0000, v84
	v_lshlrev_b32_e32 v84, 16, v85
	v_and_b32_e32 v85, 0xffff0000, v85
	v_lshlrev_b32_e32 v92, 16, v86
	v_and_b32_e32 v93, 0xffff0000, v86
	v_lshlrev_b32_e32 v86, 16, v87
	v_and_b32_e32 v87, 0xffff0000, v87
	v_pk_add_f32 v[84:85], v[82:83], v[84:85]
	v_pk_add_f32 v[90:91], v[80:81], v[90:91]
	v_pk_add_f32 v[86:87], v[78:79], v[86:87]
	v_pk_add_f32 v[92:93], v[76:77], v[92:93]
	v_cvt_pk_bf16_f32 v76, v90, v91
	v_cvt_pk_bf16_f32 v77, v84, v85
	s_nop 0
	v_cvt_pk_bf16_f32 v78, v92, v93
	v_cvt_pk_bf16_f32 v79, v86, v87
	s_nop 1
	v_mov_b64_e32 v[80:81], v[184:185]
	v_mov_b64_e32 v[82:83], v[186:187]
	v_mul_f32_e32 v92, v92, v92
	v_mul_f32_e32 v93, v93, v93
	v_mul_f32_e32 v86, v86, v86
	v_fmac_f32_e32 v92, v90, v90
	v_fmac_f32_e32 v93, v91, v91
	v_mul_f32_e32 v87, v87, v87
	v_fmac_f32_e32 v86, v84, v84
	v_add_f32_e32 v84, v92, v93
	v_fmac_f32_e32 v87, v85, v85
	v_add_f32_e32 v84, v86, v84
	v_add_f32_e32 v90, v87, v84
	global_store_dwordx4 v[88:89], v[76:79], off
	s_nop 0
	v_lshlrev_b32_e32 v84, 16, v80
	v_and_b32_e32 v85, 0xffff0000, v80
	v_lshlrev_b32_e32 v80, 16, v81
	v_and_b32_e32 v81, 0xffff0000, v81
	v_lshlrev_b32_e32 v86, 16, v82
	v_and_b32_e32 v87, 0xffff0000, v82
	v_lshlrev_b32_e32 v82, 16, v83
	v_and_b32_e32 v83, 0xffff0000, v83
	v_pk_add_f32 v[74:75], v[74:75], v[80:81]
	v_pk_add_f32 v[80:81], v[70:71], v[82:83]
	v_pk_add_f32 v[82:83], v[68:69], v[86:87]
	v_pk_add_f32 v[72:73], v[72:73], v[84:85]
	v_mul_f32_e32 v68, v82, v82
	v_mul_f32_e32 v69, v83, v83
	v_fmac_f32_e32 v68, v72, v72
	v_mul_f32_e32 v70, v80, v80
	v_fmac_f32_e32 v69, v73, v73
	v_add_f32_e32 v68, v90, v68
	v_mul_f32_e32 v71, v81, v81
	v_fmac_f32_e32 v70, v74, v74
	v_add_f32_e32 v68, v69, v68
	v_add_f32_e32 v68, v70, v68
	v_fmac_f32_e32 v71, v75, v75
	v_add_f32_e32 v68, v71, v68
	v_mov_b32_e32 v69, v68
	v_mov_b32_e32 v254, v68
	s_nop 1
	v_permlane16_swap_b32_e32 v69, v254
	v_cvt_pk_bf16_f32 v70, v72, v73
	v_cvt_pk_bf16_f32 v71, v74, v75
	v_cvt_pk_bf16_f32 v72, v82, v83
	v_cvt_pk_bf16_f32 v73, v80, v81
	s_waitcnt lgkmcnt(0)
	v_add_f32_e32 v68, v254, v69
	v_mov_b32_e32 v69, v68
	v_mov_b32_e32 v254, v68
	s_nop 1
	v_permlane32_swap_b32_e32 v69, v254
	global_store_dwordx4 v[88:89], v[70:73], off offset:256
	s_and_saveexec_b64 s[4:5], s[0:1]
	s_cbranch_execz .LBB0_686
	s_waitcnt lgkmcnt(0)
	v_add_f32_e32 v68, v254, v69
	flat_atomic_add_f32 v[116:117], v68 offset:192
.LBB0_686:
	s_or_b64 exec, exec, s[4:5]
	v_add_co_u32_e32 v72, vcc, 0x40000, v66
	v_lshl_add_u64 v[74:75], v[66:67], 0, s[10:11]
	s_nop 0
	v_addc_co_u32_e32 v73, vcc, 0, v67, vcc
	s_waitcnt lgkmcnt(0)
	s_waitcnt vmcnt(8)
	s_nop 1
	v_mov_b64_e32 v[68:69], v[188:189]
	v_mov_b64_e32 v[70:71], v[190:191]
	s_nop 0
	v_lshlrev_b32_e32 v76, 16, v68
	v_and_b32_e32 v77, 0xffff0000, v68
	v_lshlrev_b32_e32 v68, 16, v69
	v_and_b32_e32 v69, 0xffff0000, v69
	v_lshlrev_b32_e32 v78, 16, v70
	v_and_b32_e32 v79, 0xffff0000, v70
	v_lshlrev_b32_e32 v70, 16, v71
	v_and_b32_e32 v71, 0xffff0000, v71
	v_pk_add_f32 v[68:69], v[62:63], v[68:69]
	v_pk_add_f32 v[76:77], v[60:61], v[76:77]
	v_pk_add_f32 v[70:71], v[58:59], v[70:71]
	v_pk_add_f32 v[78:79], v[56:57], v[78:79]
	v_cvt_pk_bf16_f32 v56, v76, v77
	v_cvt_pk_bf16_f32 v57, v68, v69
	s_nop 0
	v_cvt_pk_bf16_f32 v58, v78, v79
	v_cvt_pk_bf16_f32 v59, v70, v71
	s_nop 1
	v_mov_b64_e32 v[60:61], v[214:215]
	v_mov_b64_e32 v[62:63], v[216:217]
	v_mul_f32_e32 v78, v78, v78
	v_mul_f32_e32 v79, v79, v79
	v_mul_f32_e32 v70, v70, v70
	v_fmac_f32_e32 v78, v76, v76
	v_fmac_f32_e32 v79, v77, v77
	v_mul_f32_e32 v71, v71, v71
	v_fmac_f32_e32 v70, v68, v68
	v_add_f32_e32 v68, v78, v79
	v_fmac_f32_e32 v71, v69, v69
	v_add_f32_e32 v68, v70, v68
	v_add_f32_e32 v76, v71, v68
	global_store_dwordx4 v[72:73], v[56:59], off
	s_nop 0
	v_lshlrev_b32_e32 v68, 16, v60
	v_and_b32_e32 v69, 0xffff0000, v60
	v_lshlrev_b32_e32 v60, 16, v61
	v_and_b32_e32 v61, 0xffff0000, v61
	v_lshlrev_b32_e32 v70, 16, v62
	v_and_b32_e32 v71, 0xffff0000, v62
	v_lshlrev_b32_e32 v62, 16, v63
	v_and_b32_e32 v63, 0xffff0000, v63
	v_pk_add_f32 v[54:55], v[54:55], v[60:61]
	v_pk_add_f32 v[60:61], v[50:51], v[62:63]
	v_pk_add_f32 v[62:63], v[48:49], v[70:71]
	v_pk_add_f32 v[52:53], v[52:53], v[68:69]
	v_mul_f32_e32 v48, v62, v62
	v_mul_f32_e32 v49, v63, v63
	v_fmac_f32_e32 v48, v52, v52
	v_mul_f32_e32 v50, v60, v60
	v_fmac_f32_e32 v49, v53, v53
	v_add_f32_e32 v48, v76, v48
	v_mul_f32_e32 v51, v61, v61
	v_fmac_f32_e32 v50, v54, v54
	v_add_f32_e32 v48, v49, v48
	v_add_f32_e32 v48, v50, v48
	v_fmac_f32_e32 v51, v55, v55
	v_add_f32_e32 v48, v51, v48
	v_mov_b32_e32 v49, v48
	v_mov_b32_e32 v254, v48
	s_nop 1
	v_permlane16_swap_b32_e32 v49, v254
	v_cvt_pk_bf16_f32 v50, v52, v53
	v_cvt_pk_bf16_f32 v51, v54, v55
	v_cvt_pk_bf16_f32 v52, v62, v63
	v_cvt_pk_bf16_f32 v53, v60, v61
	s_waitcnt lgkmcnt(0)
	v_add_f32_e32 v48, v254, v49
	v_mov_b32_e32 v49, v48
	v_mov_b32_e32 v254, v48
	s_nop 1
	v_permlane32_swap_b32_e32 v49, v254
	global_store_dwordx4 v[74:75], v[50:53], off offset:256
	s_and_saveexec_b64 s[4:5], s[0:1]
	s_cbranch_execz .LBB0_688
	s_waitcnt lgkmcnt(0)
	v_add_f32_e32 v48, v254, v49
	flat_atomic_add_f32 v[116:117], v48 offset:512
; #define GAS __attribute__((address_space(1)))
;     __device__ __forceinline__ void operator()(const Acc& acc, const Unit& u, int wr, int wc, int fr, int fq) const {
;         const int row0 = u.pm * 256 + wr * 64 + fr, col0 = u.pn * 256 + wc * 32 + 8 * fq;
; #pragma unroll
;         for (int ai = 0; ai < 2; ++ai)
; #pragma unroll
;             for (int m = 0; m < 4; ++m) {
;                 const int r = row0 + ai * 128 + m * 16; float ssum = 0.f;
; #pragma unroll
;                 for (int bj = 0; bj < 2; ++bj) {
;                     bf16_t* p = XB + (size_t)r * D + col0 + bj * 128;
;                     f32x4 x0, x1; unpack8(*(const GAS u32x4*)p, x0, x1);
;                     x0 += acc[ai][bj][m][0]; x1 += acc[ai][bj][m][1];
; #pragma unroll
;                     for (int e = 0; e < 4; ++e) ssum += x0[e] * x0[e] + x1[e] * x1[e];
;                     store8_bf16(p, x0, x1);
;                 }
;                 ssum += __shfl_xor(ssum, 16); ssum += __shfl_xor(ssum, 32);
;                 if (fq == 0) atomicAdd(ssout + r, ssum);
;             }
;     }
.LBB0_688:
	s_or_b64 exec, exec, s[4:5]
	v_add_co_u32_e32 v52, vcc, 0x48000, v66
	s_mov_b64 s[4:5], 0x48000
	s_nop 0
	v_addc_co_u32_e32 v53, vcc, 0, v67, vcc
	s_waitcnt lgkmcnt(0)
	s_nop 1
	v_mov_b64_e32 v[48:49], v[218:219]
	v_mov_b64_e32 v[50:51], v[220:221]
	v_lshl_add_u64 v[54:55], v[66:67], 0, s[4:5]
	s_nop 0
	v_lshlrev_b32_e32 v56, 16, v48
	v_and_b32_e32 v57, 0xffff0000, v48
	v_lshlrev_b32_e32 v48, 16, v49
	v_and_b32_e32 v49, 0xffff0000, v49
	v_lshlrev_b32_e32 v58, 16, v50
	v_and_b32_e32 v59, 0xffff0000, v50
	v_lshlrev_b32_e32 v50, 16, v51
	v_and_b32_e32 v51, 0xffff0000, v51
	v_pk_add_f32 v[48:49], v[46:47], v[48:49]
	v_pk_add_f32 v[56:57], v[44:45], v[56:57]
	v_pk_add_f32 v[50:51], v[42:43], v[50:51]
	v_pk_add_f32 v[58:59], v[40:41], v[58:59]
	v_cvt_pk_bf16_f32 v40, v56, v57
	v_cvt_pk_bf16_f32 v41, v48, v49
	s_nop 0
	v_cvt_pk_bf16_f32 v42, v58, v59
	v_cvt_pk_bf16_f32 v43, v50, v51
	s_nop 1
	v_mov_b64_e32 v[44:45], v[222:223]
	v_mov_b64_e32 v[46:47], v[224:225]
	v_mul_f32_e32 v58, v58, v58
	v_mul_f32_e32 v59, v59, v59
	v_mul_f32_e32 v50, v50, v50
	v_fmac_f32_e32 v58, v56, v56
	v_fmac_f32_e32 v59, v57, v57
	v_mul_f32_e32 v51, v51, v51
	v_fmac_f32_e32 v50, v48, v48
	v_add_f32_e32 v48, v58, v59
	v_fmac_f32_e32 v51, v49, v49
	v_add_f32_e32 v48, v50, v48
	v_add_f32_e32 v56, v51, v48
	global_store_dwordx4 v[52:53], v[40:43], off
	s_nop 0
	v_lshlrev_b32_e32 v48, 16, v44
	v_and_b32_e32 v49, 0xffff0000, v44
	v_lshlrev_b32_e32 v44, 16, v45
	v_and_b32_e32 v45, 0xffff0000, v45
	v_lshlrev_b32_e32 v50, 16, v46
	v_and_b32_e32 v51, 0xffff0000, v46
	v_lshlrev_b32_e32 v46, 16, v47
	v_and_b32_e32 v47, 0xffff0000, v47
	v_pk_add_f32 v[38:39], v[38:39], v[44:45]
	v_pk_add_f32 v[44:45], v[34:35], v[46:47]
	v_pk_add_f32 v[46:47], v[32:33], v[50:51]
	v_pk_add_f32 v[36:37], v[36:37], v[48:49]
	v_mul_f32_e32 v32, v46, v46
	v_mul_f32_e32 v33, v47, v47
	v_fmac_f32_e32 v32, v36, v36
	v_mul_f32_e32 v34, v44, v44
	v_fmac_f32_e32 v33, v37, v37
	v_add_f32_e32 v32, v56, v32
	v_mul_f32_e32 v35, v45, v45
	v_fmac_f32_e32 v34, v38, v38
	v_add_f32_e32 v32, v33, v32
	v_add_f32_e32 v32, v34, v32
	v_fmac_f32_e32 v35, v39, v39
	v_add_f32_e32 v32, v35, v32
	v_mov_b32_e32 v33, v32
	v_mov_b32_e32 v254, v32
	s_nop 1
	v_permlane16_swap_b32_e32 v33, v254
	v_cvt_pk_bf16_f32 v34, v36, v37
	v_cvt_pk_bf16_f32 v35, v38, v39
	v_cvt_pk_bf16_f32 v36, v46, v47
	v_cvt_pk_bf16_f32 v37, v44, v45
	s_waitcnt lgkmcnt(0)
	v_add_f32_e32 v32, v254, v33
	v_mov_b32_e32 v33, v32
	v_mov_b32_e32 v254, v32
	s_nop 1
	v_permlane32_swap_b32_e32 v33, v254
	global_store_dwordx4 v[54:55], v[34:37], off offset:256
	s_and_saveexec_b64 s[4:5], s[0:1]
	s_cbranch_execz .LBB0_690
	s_waitcnt lgkmcnt(0)
	v_add_f32_e32 v32, v254, v33
	flat_atomic_add_f32 v[116:117], v32 offset:576
; #define GAS __attribute__((address_space(1)))
;     __device__ __forceinline__ void operator()(const Acc& acc, const Unit& u, int wr, int wc, int fr, int fq) const {
;         const int row0 = u.pm * 256 + wr * 64 + fr, col0 = u.pn * 256 + wc * 32 + 8 * fq;
; #pragma unroll
;         for (int ai = 0; ai < 2; ++ai)
; #pragma unroll
;             for (int m = 0; m < 4; ++m) {
;                 const int r = row0 + ai * 128 + m * 16; float ssum = 0.f;
; #pragma unroll
;                 for (int bj = 0; bj < 2; ++bj) {
;                     bf16_t* p = XB + (size_t)r * D + col0 + bj * 128;
;                     f32x4 x0, x1; unpack8(*(const GAS u32x4*)p, x0, x1);
;                     x0 += acc[ai][bj][m][0]; x1 += acc[ai][bj][m][1];
; #pragma unroll
;                     for (int e = 0; e < 4; ++e) ssum += x0[e] * x0[e] + x1[e] * x1[e];
;                     store8_bf16(p, x0, x1);
;                 }
;                 ssum += __shfl_xor(ssum, 16); ssum += __shfl_xor(ssum, 32);
;                 if (fq == 0) atomicAdd(ssout + r, ssum);
;             }
;     }
.LBB0_690:
	s_or_b64 exec, exec, s[4:5]
	v_add_co_u32_e32 v36, vcc, 0x50000, v66
	s_mov_b64 s[4:5], 0x50000
	s_nop 0
	v_addc_co_u32_e32 v37, vcc, 0, v67, vcc
	s_waitcnt lgkmcnt(0)
	s_nop 1
	v_mov_b64_e32 v[32:33], v[226:227]
	v_mov_b64_e32 v[34:35], v[228:229]
	v_lshl_add_u64 v[38:39], v[66:67], 0, s[4:5]
	s_nop 0
	v_lshlrev_b32_e32 v40, 16, v32
	v_and_b32_e32 v41, 0xffff0000, v32
	v_lshlrev_b32_e32 v32, 16, v33
	v_and_b32_e32 v33, 0xffff0000, v33
	v_lshlrev_b32_e32 v42, 16, v34
	v_and_b32_e32 v43, 0xffff0000, v34
	v_lshlrev_b32_e32 v34, 16, v35
	v_and_b32_e32 v35, 0xffff0000, v35
	v_pk_add_f32 v[32:33], v[30:31], v[32:33]
	v_pk_add_f32 v[40:41], v[28:29], v[40:41]
	v_pk_add_f32 v[34:35], v[26:27], v[34:35]
	v_pk_add_f32 v[42:43], v[24:25], v[42:43]
	v_cvt_pk_bf16_f32 v24, v40, v41
	v_cvt_pk_bf16_f32 v25, v32, v33
	s_nop 0
	v_cvt_pk_bf16_f32 v26, v42, v43
	v_cvt_pk_bf16_f32 v27, v34, v35
	s_nop 1
	v_mov_b64_e32 v[28:29], v[230:231]
	v_mov_b64_e32 v[30:31], v[232:233]
	v_mul_f32_e32 v42, v42, v42
	v_mul_f32_e32 v43, v43, v43
	v_mul_f32_e32 v34, v34, v34
	v_fmac_f32_e32 v42, v40, v40
	v_fmac_f32_e32 v43, v41, v41
	v_mul_f32_e32 v35, v35, v35
	v_fmac_f32_e32 v34, v32, v32
	v_add_f32_e32 v32, v42, v43
	v_fmac_f32_e32 v35, v33, v33
	v_add_f32_e32 v32, v34, v32
	v_add_f32_e32 v40, v35, v32
	global_store_dwordx4 v[36:37], v[24:27], off
	s_nop 0
	v_lshlrev_b32_e32 v32, 16, v28
	v_and_b32_e32 v33, 0xffff0000, v28
	v_lshlrev_b32_e32 v28, 16, v29
	v_and_b32_e32 v29, 0xffff0000, v29
	v_lshlrev_b32_e32 v34, 16, v30
	v_and_b32_e32 v35, 0xffff0000, v30
	v_lshlrev_b32_e32 v30, 16, v31
	v_and_b32_e32 v31, 0xffff0000, v31
	v_pk_add_f32 v[22:23], v[22:23], v[28:29]
	v_pk_add_f32 v[28:29], v[18:19], v[30:31]
	v_pk_add_f32 v[30:31], v[16:17], v[34:35]
	v_pk_add_f32 v[20:21], v[20:21], v[32:33]
	v_mul_f32_e32 v16, v30, v30
	v_mul_f32_e32 v17, v31, v31
	v_fmac_f32_e32 v16, v20, v20
	v_mul_f32_e32 v18, v28, v28
	v_fmac_f32_e32 v17, v21, v21
	v_add_f32_e32 v16, v40, v16
	v_mul_f32_e32 v19, v29, v29
	v_fmac_f32_e32 v18, v22, v22
	v_add_f32_e32 v16, v17, v16
	v_add_f32_e32 v16, v18, v16
	v_fmac_f32_e32 v19, v23, v23
	v_add_f32_e32 v16, v19, v16
	v_mov_b32_e32 v17, v16
	v_mov_b32_e32 v254, v16
	s_nop 1
	v_permlane16_swap_b32_e32 v17, v254
	v_cvt_pk_bf16_f32 v18, v20, v21
	v_cvt_pk_bf16_f32 v19, v22, v23
	v_cvt_pk_bf16_f32 v20, v30, v31
	v_cvt_pk_bf16_f32 v21, v28, v29
	s_waitcnt lgkmcnt(0)
	v_add_f32_e32 v16, v254, v17
	v_mov_b32_e32 v17, v16
	v_mov_b32_e32 v254, v16
	s_nop 1
	v_permlane32_swap_b32_e32 v17, v254
	global_store_dwordx4 v[38:39], v[18:21], off offset:256
	s_and_saveexec_b64 s[4:5], s[0:1]
	s_cbranch_execz .LBB0_692
	s_waitcnt lgkmcnt(0)
	v_add_f32_e32 v16, v254, v17
	flat_atomic_add_f32 v[116:117], v16 offset:640
.LBB0_692:
	s_or_b64 exec, exec, s[4:5]
	v_add_co_u32_e32 v20, vcc, 0x58000, v66
	s_mov_b64 s[4:5], 0x58000
	s_nop 0
	v_addc_co_u32_e32 v21, vcc, 0, v67, vcc
	s_waitcnt lgkmcnt(0)
	s_nop 1
	v_mov_b64_e32 v[16:17], v[234:235]
	v_mov_b64_e32 v[18:19], v[236:237]
	v_lshl_add_u64 v[22:23], v[66:67], 0, s[4:5]
	s_nop 0
	v_lshlrev_b32_e32 v24, 16, v16
	v_and_b32_e32 v25, 0xffff0000, v16
	v_lshlrev_b32_e32 v16, 16, v17
	v_and_b32_e32 v17, 0xffff0000, v17
	v_lshlrev_b32_e32 v26, 16, v18
	v_and_b32_e32 v27, 0xffff0000, v18
	v_lshlrev_b32_e32 v18, 16, v19
	v_and_b32_e32 v19, 0xffff0000, v19
	v_pk_add_f32 v[16:17], v[14:15], v[16:17]
	v_pk_add_f32 v[24:25], v[12:13], v[24:25]
	v_pk_add_f32 v[18:19], v[10:11], v[18:19]
	v_pk_add_f32 v[26:27], v[8:9], v[26:27]
	v_cvt_pk_bf16_f32 v8, v24, v25
	v_cvt_pk_bf16_f32 v9, v16, v17
	s_nop 0
	v_cvt_pk_bf16_f32 v10, v26, v27
	v_cvt_pk_bf16_f32 v11, v18, v19
	s_nop 1
	v_mov_b64_e32 v[12:13], v[238:239]
	v_mov_b64_e32 v[14:15], v[240:241]
	v_mul_f32_e32 v26, v26, v26
	v_mul_f32_e32 v27, v27, v27
	v_mul_f32_e32 v18, v18, v18
	v_fmac_f32_e32 v26, v24, v24
	v_fmac_f32_e32 v27, v25, v25
	v_mul_f32_e32 v19, v19, v19
	v_fmac_f32_e32 v18, v16, v16
	v_add_f32_e32 v16, v26, v27
	v_fmac_f32_e32 v19, v17, v17
	v_add_f32_e32 v16, v18, v16
	v_add_f32_e32 v24, v19, v16
	global_store_dwordx4 v[20:21], v[8:11], off
	s_nop 0
	v_lshlrev_b32_e32 v16, 16, v12
	v_and_b32_e32 v17, 0xffff0000, v12
	v_lshlrev_b32_e32 v12, 16, v13
	v_and_b32_e32 v13, 0xffff0000, v13
	v_lshlrev_b32_e32 v18, 16, v14
	v_and_b32_e32 v19, 0xffff0000, v14
	v_lshlrev_b32_e32 v14, 16, v15
	v_and_b32_e32 v15, 0xffff0000, v15
	v_pk_add_f32 v[6:7], v[6:7], v[12:13]
	v_pk_add_f32 v[12:13], v[2:3], v[14:15]
	v_pk_add_f32 v[14:15], v[0:1], v[18:19]
	v_pk_add_f32 v[4:5], v[4:5], v[16:17]
	v_mul_f32_e32 v0, v14, v14
	v_mul_f32_e32 v1, v15, v15
	v_fmac_f32_e32 v0, v4, v4
	v_mul_f32_e32 v2, v12, v12
	v_fmac_f32_e32 v1, v5, v5
	v_add_f32_e32 v0, v24, v0
	v_mul_f32_e32 v3, v13, v13
	v_fmac_f32_e32 v2, v6, v6
	v_add_f32_e32 v0, v1, v0
	v_add_f32_e32 v0, v2, v0
	v_fmac_f32_e32 v3, v7, v7
	v_add_f32_e32 v0, v3, v0
	v_mov_b32_e32 v1, v0
	v_mov_b32_e32 v254, v0
	s_nop 1
	v_permlane16_swap_b32_e32 v1, v254
	v_cvt_pk_bf16_f32 v2, v4, v5
	v_cvt_pk_bf16_f32 v3, v6, v7
	v_cvt_pk_bf16_f32 v4, v14, v15
	v_cvt_pk_bf16_f32 v5, v12, v13
	s_waitcnt lgkmcnt(0)
	v_add_f32_e32 v0, v254, v1
	v_mov_b32_e32 v1, v0
	v_mov_b32_e32 v254, v0
	s_nop 1
	v_permlane32_swap_b32_e32 v1, v254
	global_store_dwordx4 v[22:23], v[2:5], off offset:256
	s_and_saveexec_b64 s[4:5], s[0:1]
	s_cbranch_execz .LBB0_694
	s_waitcnt lgkmcnt(0)
	v_add_f32_e32 v0, v254, v1
	flat_atomic_add_f32 v[116:117], v0 offset:704

; #define PG8_WAIT_V(n) asm volatile("s_waitcnt vmcnt(" #n ")" ::: "memory")
;     __device__ bool next(int i, Unit& u) const {
;         const long L = (long)i * G + c; if (L >= nwg) return false;
;         int wgid = (int)L; { const int q = nwg / NXCD, r = nwg % NXCD, xcd = wgid % NXCD, off = wgid / NXCD; wgid = (xcd < r ? xcd * (q + 1) : r * (q + 1) + (xcd - r) * q) + off; }
;         const int nig = WGM * nN, gid = wgid / nig, fm = gid * WGM, gsz = (nM - fm) < WGM ? (nM - fm) : WGM;
;         u.pm = fm + ((wgid % nig) % gsz); u.pn = (wgid % nig) / gsz; u.ko = 0; return true;
;     }
; template <class Epi, bool SP2, class Sched>
; __device__ __forceinline__ void gemm_phase(LAS unsigned char* lds, const Gemm g, const Sched& S, const Epi& E) {
;     ...
;     const int wid = __builtin_amdgcn_readfirstlane(tid >> 6), lane = tid & 63, wr = wid >> 2, wc = wid & 3, fr = lane & 15, fq = lane >> 4;
;     const int K = g.K, nt = K / BK;
;     unsigned voffA[2], voffB[2];
; #pragma unroll
;     for (int i = 0; i < 2; ++i) { int R, C; stage_rc(tid * 16 + i * 8192, R, C); const int Rb = Epi::PERM ? ((R & ~31) + perm32(R & 31)) : R;
;         voffA[i] = (unsigned)(R * g.lda + C) * 2u; voffB[i] = (unsigned)(Rb * g.ldb + C) * 2u; }
;     const size_t kstep = (size_t)(BK * 2);
;     const size_t hstep = (size_t)HALF * g.lda * 2, hstepB = (size_t)HALF * g.ldb * 2;
;     const size_t tstep = 2 * hstep, tstepB = 2 * hstepB;
;     const unsigned ldsw = (unsigned)wid * 1024u;
;     const int aoff = lds_byte(wr * 64 + fr, fq * 8), boff = lds_byte(wc * 32 + fr, fq * 8);
;     ...
;     Unit cur, nxt; int ui = 0;
;     if (!S.next(0, cur)) return;
;     f32x4 acc[2][2][4][2];
; #pragma unroll
;     for (int a = 0; a < 2; ++a)
; #pragma unroll
;         for (int b = 0; b < 2; ++b)
; #pragma unroll
;             for (int m = 0; m < 4; ++m)
; #pragma unroll
;                 for (int n = 0; n < 2; ++n) acc[a][b][m][n] = (f32x4){0.f, 0.f, 0.f, 0.f};
;     bf16x8 At[4][2], B0[2][2], B1[2][2];
;     const char* cA = (const char*)g.A + (size_t)cur.pm * tstep + cur.ko; const char* cB = (const char*)g.Bt + (size_t)cur.pn * tstepB + cur.ko;
;     if constexpr (SP2) {
;         PG8_STAGE(PG8_SB(0, 0), cB, voffB); PG8_STAGE(PG8_SB(0, 1), cB + hstepB, voffB); PG8_STAGE(PG8_SA(0, 0), cA, voffA); PG8_STAGE(PG8_SA(0, 1), cA + hstep, voffA);
;         if (wr == 1) PG8_BAR;
;         PG8_WAIT_V(2); PG8_BAR;
.LBB0_774:
	s_or_b64 exec, exec, s[0:1]
	s_mov_b64 s[0:1], s[74:75]
	s_mov_b32 s8, s83
	s_mov_b32 s18, s14
	s_mov_b32 s9, s90
	v_mov_b32_e32 v14, v242
	s_waitcnt lgkmcnt(0)
	s_barrier
	s_cmpk_gt_i32 s8, 0x40f
	v_readfirstlane_b32 s5, v14
	s_cbranch_scc1 .LBB0_790
	v_lshlrev_b32_e32 v0, 4, v14
	v_add_u32_e32 v1, 0x2000, v0
	v_ashrrev_i32_e32 v2, 31, v1
	v_lshrrev_b32_e32 v2, 22, v2
	v_add_u32_e32 v2, v1, v2
	v_ashrrev_i32_e32 v8, 10, v2
	v_mul_i32_i24_e32 v2, 0x400, v8
	v_sub_u32_e32 v1, v1, v2
	v_lshrrev_b32_e32 v2, 4, v1
	s_mul_i32 s3, s18, 0x1f00000
	v_bitop3_b32 v1, v2, v1, 32 bitop3:0x6c
	s_mul_hi_i32 s2, s18, 0x1f00000
	s_add_u32 s3, s0, s3
	v_ashrrev_i32_e32 v2, 31, v1
	s_addc_u32 s2, s1, s2
	v_lshrrev_b32_e32 v2, 26, v2
	s_add_u32 s62, s0, 0x4200000
	v_add_u32_e32 v2, v1, v2
	v_lshlrev_b32_e32 v3, 3, v8
	s_addc_u32 s64, s1, 0
	v_ashrrev_i32_e32 v9, 6, v2
	v_and_b32_e32 v3, -16, v3
	s_add_u32 s65, s3, 0xa80000
	v_add_u32_e32 v3, v9, v3
	s_addc_u32 s68, s2, 0
	v_and_b32_e32 v4, 3, v9
	s_mov_b32 s2, 0x1fffe0
	v_lshrrev_b32_e32 v5, 2, v3
	v_lshlrev_b32_e32 v6, 1, v3
	v_and_b32_e32 v2, 0xc0, v2
	v_and_or_b32 v4, v3, s2, v4
	v_and_b32_e32 v5, 4, v5
	v_and_b32_e32 v6, 24, v6
	v_sub_u32_e32 v1, v1, v2
	v_or3_b32 v4, v4, v5, v6
	v_lshlrev_b32_e32 v5, 5, v8
	v_ashrrev_i16_sdwa v1, v244, sext(v1) dst_sel:DWORD dst_unused:UNUSED_PAD src0_sel:DWORD src1_sel:BYTE_0
	v_and_b32_e32 v5, 32, v5
	v_bfe_i32 v10, v1, 0, 16
	v_add_lshl_u32 v1, v5, v10, 1
	v_lshl_add_u32 v130, v4, 11, v1
	v_lshl_add_u32 v132, v3, 11, v1
	v_bfe_i32 v1, v14, 27, 1
	v_lshrrev_b32_e32 v1, 22, v1
	v_add_u32_e32 v1, v0, v1
	v_and_b32_e32 v1, 0xfffffc00, v1
	v_sub_u32_e32 v0, v0, v1
	v_lshrrev_b32_e32 v1, 4, v0
	v_ashrrev_i32_e32 v2, 31, v14
	v_bitop3_b32 v0, v1, v0, 32 bitop3:0x6c
	v_lshrrev_b32_e32 v2, 26, v2
	v_ashrrev_i32_e32 v1, 31, v0
	v_add_u32_e32 v2, v14, v2
	v_lshrrev_b32_e32 v1, 26, v1
	v_ashrrev_i32_e32 v12, 6, v2
	v_add_u32_e32 v1, v0, v1
	v_lshlrev_b32_e32 v2, 3, v12
	v_ashrrev_i32_e32 v11, 6, v1
	v_and_b32_e32 v2, -16, v2
	v_add_u32_e32 v2, v11, v2
	v_and_b32_e32 v3, 3, v11
	s_ashr_i32 s72, s8, 31
	v_and_or_b32 v3, v2, s2, v3
	s_lshr_b32 s2, s72, 29
	s_add_i32 s2, s8, s2
	s_ashr_i32 s6, s5, 6
	s_ashr_i32 s3, s2, 3
	s_and_b32 s2, s2, -8
	s_ashr_i32 s7, s5, 8
	s_lshl_b32 s69, s6, 10
	s_sub_i32 s2, s8, s2
	s_cmp_lt_i32 s2, 0
	s_movk_i32 s4, 0x80
	s_cselect_b32 s4, s4, 0x80
	s_mul_i32 s2, s2, s4
	s_sub_i32 s3, 0x7f, s3
	s_add_i32 s2, s2, s3
	s_ashr_i32 s3, s2, 31
	s_lshr_b32 s3, s3, 27
	v_lshrrev_b32_e32 v4, 2, v2
	v_lshlrev_b32_e32 v5, 1, v2
	v_and_b32_e32 v1, 0xc0, v1
	s_add_i32 s3, s2, s3
	v_and_b32_e32 v4, 4, v4
	v_and_b32_e32 v5, 24, v5
	v_sub_u32_e32 v0, v0, v1
	s_ashr_i32 s4, s3, 5
	v_or3_b32 v3, v3, v4, v5
	v_lshlrev_b32_e32 v4, 5, v12
	v_ashrrev_i16_sdwa v0, v244, sext(v0) dst_sel:DWORD dst_unused:UNUSED_PAD src0_sel:DWORD src1_sel:BYTE_0
	s_lshl_b32 s10, s4, 3
	v_and_b32_e32 v4, 32, v4
	v_bfe_i32 v13, v0, 0, 16
	s_sub_i32 s4, 0x104, s10
	v_add_lshl_u32 v0, v4, v13, 1
	s_min_u32 s11, s4, 8
	s_andn2_b32 s3, s3, 31
	v_lshl_add_u32 v64, v3, 11, v0
	s_sub_i32 s12, s2, s3
	v_cvt_f32_ubyte0_e32 v3, s11
	v_cvt_f32_i32_e32 v1, s12
	v_rcp_iflag_f32_e32 v4, v3
	v_lshl_add_u32 v134, v2, 11, v0
	s_ashr_i32 s2, s12, 30
	s_or_b32 s4, s2, 1
	v_mul_f32_e32 v0, v1, v4
	v_trunc_f32_e32 v0, v0
	v_fma_f32 v1, -v0, v3, v1
	v_cvt_i32_f32_e32 v0, v0
	v_cmp_ge_f32_e64 s[2:3], |v1|, v3
	s_and_b64 s[2:3], s[2:3], exec
	s_cselect_b32 s2, s4, 0
	v_readfirstlane_b32 s3, v0
	s_add_i32 s4, s3, s2
	s_mul_i32 s2, s4, s11
	s_sub_i32 s2, s12, s2
	s_sext_i32_i8 s2, s2
	s_add_i32 s16, s10, s2
	s_ashr_i32 s17, s16, 31
	s_bfe_i64 s[10:11], s[4:5], 0x80000
	s_lshl_b64 s[2:3], s[16:17], 19
	s_lshl_b64 s[10:11], s[10:11], 19
	s_add_u32 s10, s65, s10
	s_addc_u32 s11, s68, s11
	s_add_i32 s12, s69, 0
	s_add_i32 m0, s12, 0x10000
	v_mov_b32_e32 v131, v65
	global_load_lds_dwordx4 v64, s[10:11]
	s_add_i32 m0, s12, 0x12000
	s_add_u32 s14, s10, 0x40000
	global_load_lds_dwordx4 v130, s[10:11]
	s_addc_u32 s15, s11, 0
	s_add_i32 m0, s12, 0x14000
	v_mov_b32_e32 v135, v65
	global_load_lds_dwordx4 v64, s[14:15]
	s_add_i32 m0, s12, 0x16000
	s_add_u32 s88, s62, s2
	s_addc_u32 s89, s64, s3
	s_add_i32 s13, s12, 0x2000
	global_load_lds_dwordx4 v130, s[14:15]
	s_mov_b32 m0, s12
	s_add_u32 s2, s88, 0x40000
	global_load_lds_dwordx4 v134, s[88:89]
	s_mov_b32 m0, s13
	s_addc_u32 s3, s89, 0
	s_add_i32 s14, s12, 0x4000
	global_load_lds_dwordx4 v132, s[88:89]
	s_mov_b32 m0, s14
	s_add_i32 s15, s12, 0x6000
	global_load_lds_dwordx4 v134, s[2:3]
	s_mov_b32 m0, s15
	v_mov_b32_e32 v133, v65
	global_load_lds_dwordx4 v132, s[2:3]
	s_cmp_eq_u32 s7, 1
	v_lshl_add_u64 v[6:7], s[10:11], 0, v[64:65]
	v_lshl_add_u64 v[4:5], s[10:11], 0, v[130:131]
	v_lshl_add_u64 v[0:1], s[88:89], 0, v[134:135]
	s_cselect_b64 s[2:3], -1, 0
	s_cmp_lg_u32 s7, 1
	v_lshl_add_u64 v[2:3], s[88:89], 0, v[132:133]
	s_cbranch_scc1 .LBB0_777
	s_barrier

;     __device__ bool next(int i, Unit& u) const {
;         const long L = (long)i * G + c; if (L >= nwg) return false;
;         int wgid = (int)L; { const int q = nwg / NXCD, r = nwg % NXCD, xcd = wgid % NXCD, off = wgid / NXCD; wgid = (xcd < r ? xcd * (q + 1) : r * (q + 1) + (xcd - r) * q) + off; }
;         const int nig = WGM * nN, gid = wgid / nig, fm = gid * WGM, gsz = (nM - fm) < WGM ? (nM - fm) : WGM;
;         u.pm = fm + ((wgid % nig) % gsz); u.pn = (wgid % nig) / gsz; u.ko = 0; return true;
;     }
; template <class Epi, bool SP2, class Sched>
; __device__ __forceinline__ void gemm_phase(LAS unsigned char* lds, const Gemm g, const Sched& S, const Epi& E) {
;     ...
;         const bool has_next = S.next(ui + 1, nxt);
;         const char* nA = has_next ? (const char*)g.A + (size_t)nxt.pm * tstep + nxt.ko : cA; const char* nB = has_next ? (const char*)g.Bt + (size_t)nxt.pn * tstepB + nxt.ko : cB;
.LBB0_780:
	s_add_i32 s33, s33, 1
	s_mul_i32 s0, s33, s19
	s_mul_hi_u32 s1, s33, s9
	s_add_i32 s1, s1, s0
	s_mul_i32 s0, s33, s9
	s_add_u32 s6, s0, s8
	s_addc_u32 s7, s1, s72
	v_cmp_gt_i64_e32 vcc, s[6:7], v[204:205]
	v_cmp_lt_i64_e64 s[0:1], s[6:7], v[202:203]
	s_cbranch_vccnz .LBB0_782
	s_ashr_i32 s7, s6, 31
	s_lshr_b32 s7, s7, 29
	s_add_i32 s7, s6, s7
	s_ashr_i32 s20, s7, 3
	s_and_b32 s7, s7, -8
	s_sub_i32 s6, s6, s7
	s_cmp_lt_i32 s6, 0
	s_movk_i32 s7, 0x80
	s_cselect_b32 s7, s7, 0x80
	s_mul_i32 s6, s6, s7
	s_sub_i32 s20, 0x7f, s20
	s_add_i32 s6, s6, s20
	s_mul_i32 s7, s33, s9
	s_add_i32 s7, s7, s8
	s_cmpk_lt_i32 s7, 0x400
	s_cselect_b32 s6, s6, s7
	s_ashr_i32 s7, s6, 31
	s_lshr_b32 s7, s7, 27
	s_add_i32 s7, s6, s7
	s_ashr_i32 s20, s7, 5
	s_lshl_b32 s20, s20, 3
	s_sub_i32 s21, 0x104, s20
	s_min_i32 s21, s21, 8
	s_abs_i32 s22, s21
	v_cvt_f32_u32_e32 v0, s22
	s_sub_i32 s24, 0, s22
	s_andn2_b32 s7, s7, 31
	s_sub_i32 s6, s6, s7
	v_rcp_iflag_f32_e32 v0, v0
	s_abs_i32 s7, s6
	s_xor_b32 s23, s6, s21
	s_ashr_i32 s23, s23, 31
	v_mul_f32_e32 v0, 0x4f7ffffe, v0
	v_cvt_u32_f32_e32 v0, v0
	s_nop 0
	v_readfirstlane_b32 s25, v0
	s_mul_i32 s24, s24, s25
	s_mul_hi_u32 s24, s25, s24
	s_add_i32 s25, s25, s24
	s_mul_hi_u32 s24, s7, s25
	s_mul_i32 s25, s24, s22
	s_sub_i32 s7, s7, s25
	s_add_i32 s58, s24, 1
	s_sub_i32 s25, s7, s22
	s_cmp_ge_u32 s7, s22
	s_cselect_b32 s24, s58, s24
	s_cselect_b32 s7, s25, s7
	s_add_i32 s25, s24, 1
	s_cmp_ge_u32 s7, s22
	s_cselect_b32 s7, s25, s24
	s_xor_b32 s7, s7, s23
	s_sub_i32 s58, s7, s23
	s_mul_i32 s7, s58, s21
	s_sub_i32 s6, s6, s7
	s_mov_b32 s25, 0x40000
	s_add_i32 s60, s20, s6

; __device__ __forceinline__ void attn_phase(unsigned char* ws, int l, LAS unsigned char* lds, int G, int bid) {
;     ...
;     for (int u = bid; u < NU; u += G) {
;         int qrow0, nq, ldv; const bf16_t* Kp; const bf16_t* Vp; int h;
;         if (u < NB * 32) { const int b = u >> 5; h = (u >> 3) & 3; const int qt = u & 7; qrow0 = b * SEQ + qt * 256; nq = 256;
;             Kp = (const bf16_t*)(ws + WS_KB) + (size_t)l * TM * D + (size_t)(b * NMEM) * D + h * 256; Vp = (const bf16_t*)(ws + WS_VT) + (size_t)l * D * TM + (size_t)(h * 256) * TM + b * NMEM; ldv = TM; }
;         else { const int i = u - NB * 32, b = i >> 2; h = i & 3; qrow0 = TP + b * DSEQ; nq = DSEQ;
;             Kp = (const bf16_t*)(ws + WS_KC) + (size_t)l * TMS * D + (size_t)(b * NMEM) * D + h * 256; Vp = (const bf16_t*)(ws + WS_VTC) + (size_t)l * D * TMS + (size_t)(h * 256) * TMS + b * NMEM; ldv = TMS; }
.LBB0_869:
	s_and_b32 s12, s17, 7
	s_lshl_b32 s12, s12, 7
	s_lshr_b32 s8, s17, 3
	s_or_b32 s12, s12, s8
	s_cmpk_gt_i32 s17, 0x3ff
	s_mov_b64 s[6:7], -1
	s_cbranch_scc0 .LBB0_871
	s_add_i32 s4, s17, 0xfffffc00
	s_lshr_b32 s4, s4, 2
	s_lshl_b32 s5, s4, 6
	s_lshl_b32 s62, s4, 8
	s_add_i32 s9, s5, 0x10000
	s_mov_b64 s[6:7], 0
	s_mov_b64 s[4:5], s[62:63]
.LBB0_871:
	s_andn2_b64 vcc, exec, s[6:7]
	s_xor_b64 s[0:1], s[0:1], -1
	s_cbranch_vccnz .LBB0_873
	s_ashr_i32 s4, s12, 5
	s_lshl_b32 s5, s4, 11
	s_lshl_b32 s6, s12, 8
	s_and_b32 s6, s6, 0x700
	s_lshl_b32 s4, s4, 8
	s_lshr_b32 s10, s12, 3
	s_or_b32 s9, s5, s6
	s_ashr_i32 s5, s4, 31
	s_movk_i32 s12, 0x100
	s_movk_i32 s8, 0x2000
	s_mov_b64 s[60:61], 14
	s_mov_b64 s[6:7], s[84:85]
	s_mov_b64 s[88:89], s[86:87]
	s_branch .LBB0_874

; #define LAS __attribute__((address_space(3)))
; #define GAS __attribute__((address_space(1)))
; __device__ __forceinline__ void attn_phase(unsigned char* ws, int l, LAS unsigned char* lds, int G, int bid) {
;     ...
;         u32x4 vpre[16];
;         const int vc = t2 & 31, vr = t2 >> 5;
;         { const unsigned off = (unsigned)((vr * ldv + vc * 8) * 2); const char* vb = (const char*)Vp;
; #pragma unroll
;           for (int i = 0; i < 16; ++i) vpre[i] = *(const GAS u32x4*)(vb + (size_t)(16 * i) * ldv * 2 + off); }
;         __syncthreads();
;         {
;             LAS unsigned char* ld0 = lds + vr * VST + vc * 16;
; #pragma unroll
;             for (int i = 0; i < 16; ++i) { LAS u32x2* d = (LAS u32x2*)(ld0 + 16 * i * VST); d[0] = (u32x2){vpre[i].x, vpre[i].y}; d[1] = (u32x2){vpre[i].z, vpre[i].w}; }
;         }
;         __syncthreads();
;         {
;             const int un = u + G; have = un < NU;
;             if (have) { const char* kb = (const char*)attn_kptr(ws, l, un); const unsigned off = (unsigned)((vr * D + vc * 8) * 2);
; #pragma unroll
;                 for (int i = 0; i < 16; ++i) kpre[i] = *(const GAS u32x4*)(kb + (size_t)(16 * i) * D * 2 + off); }
.LBB0_882:
	s_lshl_b64 s[6:7], s[62:63], s60
	s_add_u32 s6, s88, s6
	s_addc_u32 s7, s89, s7
	s_lshl_b64 s[4:5], s[4:5], 1
	s_add_u32 s4, s6, s4
	s_addc_u32 s5, s7, s5
	v_mul_lo_u32 v2, s8, v252
	v_lshl_or_b32 v64, v2, 1, v253
	s_lshl_b32 s6, s8, 5
	v_lshl_add_u64 v[30:31], s[4:5], 0, v[64:65]
	s_mov_b32 s7, s63
	v_lshl_add_u64 v[6:7], v[30:31], 0, s[6:7]
	global_load_dwordx4 v[2:5], v64, s[4:5]
	s_add_i32 s17, s17, s16
	global_load_dwordx4 v[6:9], v[6:7], off
	s_lshl_b32 s4, s8, 6
	s_mov_b32 s5, s63
	v_lshl_add_u64 v[10:11], v[30:31], 0, s[4:5]
	s_mul_i32 s4, s8, 0x60
	global_load_dwordx4 v[10:13], v[10:11], off
	v_lshl_add_u64 v[14:15], v[30:31], 0, s[4:5]
	s_lshl_b32 s4, s8, 7
	global_load_dwordx4 v[14:17], v[14:15], off
	v_lshl_add_u64 v[18:19], v[30:31], 0, s[4:5]
	s_mul_i32 s4, s8, 0xa0
	global_load_dwordx4 v[18:21], v[18:19], off
	v_lshl_add_u64 v[22:23], v[30:31], 0, s[4:5]
	s_mul_i32 s4, s8, 0xc0
	global_load_dwordx4 v[22:25], v[22:23], off
	v_lshl_add_u64 v[26:27], v[30:31], 0, s[4:5]
	s_mul_i32 s4, s8, 0xe0
	global_load_dwordx4 v[26:29], v[26:27], off
	v_lshl_add_u64 v[34:35], v[30:31], 0, s[4:5]
	s_lshl_b32 s4, s8, 8
	global_load_dwordx4 v[34:37], v[34:35], off
	v_lshl_add_u64 v[38:39], v[30:31], 0, s[4:5]
	s_mul_i32 s4, s8, 0x120
	global_load_dwordx4 v[38:41], v[38:39], off
	v_lshl_add_u64 v[42:43], v[30:31], 0, s[4:5]
	s_mul_i32 s4, s8, 0x140
	global_load_dwordx4 v[42:45], v[42:43], off
	v_lshl_add_u64 v[46:47], v[30:31], 0, s[4:5]
	s_mul_i32 s4, s8, 0x160
	global_load_dwordx4 v[46:49], v[46:47], off
	v_lshl_add_u64 v[50:51], v[30:31], 0, s[4:5]
	s_mul_i32 s4, s8, 0x180
	global_load_dwordx4 v[50:53], v[50:51], off
	v_lshl_add_u64 v[54:55], v[30:31], 0, s[4:5]
	s_mul_i32 s4, s8, 0x1a0
	global_load_dwordx4 v[54:57], v[54:55], off
	v_lshl_add_u64 v[58:59], v[30:31], 0, s[4:5]
	s_mul_i32 s4, s8, 0x1c0
	global_load_dwordx4 v[58:61], v[58:59], off
	v_lshl_add_u64 v[62:63], v[30:31], 0, s[4:5]
	s_mul_i32 s4, s8, 0x1e0
	global_load_dwordx4 v[118:121], v[62:63], off
	v_lshl_add_u64 v[30:31], v[30:31], 0, s[4:5]
	global_load_dwordx4 v[122:125], v[30:31], off
	s_movk_i32 s4, 0x208
	v_mul_lo_u32 v30, v252, s4
	v_add3_u32 v30, 0, v30, v253
	s_barrier
	s_cmpk_gt_i32 s17, 0x43f
	s_cselect_b64 s[60:61], -1, 0
	s_and_b64 vcc, exec, s[60:61]
	v_mov_b32_e32 v68, 0
	v_mov_b32_e32 v67, 0
	v_mov_b32_e32 v66, 0
	v_mov_b32_e32 v193, 0
	v_mov_b32_e32 v192, 0
	v_mov_b32_e32 v191, 0
	v_mov_b32_e32 v190, 0
	v_mov_b32_e32 v189, 0
	v_mov_b32_e32 v188, 0
	v_mov_b32_e32 v187, 0
	v_mov_b32_e32 v186, 0
	v_mov_b32_e32 v181, 0
	v_mov_b32_e32 v180, 0
	v_mov_b32_e32 v179, 0
	v_mov_b32_e32 v178, 0
	v_mov_b32_e32 v177, 0
	v_mov_b32_e32 v176, 0
	v_mov_b32_e32 v175, 0
	v_mov_b32_e32 v174, 0
	v_mov_b32_e32 v173, 0
	v_mov_b32_e32 v172, 0
	v_mov_b32_e32 v171, 0
	v_mov_b32_e32 v170, 0
	v_mov_b32_e32 v169, 0
	v_mov_b32_e32 v168, 0
	s_waitcnt vmcnt(15)
	ds_write2_b64 v30, v[2:3], v[4:5] offset1:1
	v_add_u32_e32 v2, 0x2080, v30
	s_waitcnt vmcnt(14)
	ds_write2_b64 v2, v[6:7], v[8:9] offset1:1
	v_add_u32_e32 v2, 0x4100, v30
	v_mov_b32_e32 v167, 0
	v_mov_b32_e32 v166, 0
	v_mov_b32_e32 v165, 0
	s_waitcnt vmcnt(13)
	ds_write2_b64 v2, v[10:11], v[12:13] offset1:1
	v_add_u32_e32 v2, 0x6180, v30
	v_mov_b32_e32 v164, 0
	s_waitcnt vmcnt(12)
	ds_write2_b64 v2, v[14:15], v[16:17] offset1:1
	v_add_u32_e32 v2, 0x8200, v30
	v_mov_b32_e32 v163, 0
	s_waitcnt vmcnt(11)
	ds_write2_b64 v2, v[18:19], v[20:21] offset1:1
	v_add_u32_e32 v2, 0xa280, v30
	v_mov_b32_e32 v162, 0
	s_waitcnt vmcnt(10)
	ds_write2_b64 v2, v[22:23], v[24:25] offset1:1
	v_add_u32_e32 v2, 0xc300, v30
	v_mov_b32_e32 v161, 0
	s_waitcnt vmcnt(9)
	ds_write2_b64 v2, v[26:27], v[28:29] offset1:1
	v_add_u32_e32 v2, 0xe380, v30
	v_mov_b32_e32 v160, 0
	s_waitcnt vmcnt(8)
	ds_write2_b64 v2, v[34:35], v[36:37] offset1:1
	v_add_u32_e32 v2, 0x10400, v30
	v_mov_b32_e32 v159, 0
	s_waitcnt vmcnt(7)
	ds_write2_b64 v2, v[38:39], v[40:41] offset1:1
	v_add_u32_e32 v2, 0x12480, v30
	v_mov_b32_e32 v158, 0
	s_waitcnt vmcnt(6)
	ds_write2_b64 v2, v[42:43], v[44:45] offset1:1
	v_add_u32_e32 v2, 0x14500, v30
	v_mov_b32_e32 v153, 0
	s_waitcnt vmcnt(5)
	ds_write2_b64 v2, v[46:47], v[48:49] offset1:1
	v_add_u32_e32 v2, 0x16580, v30
	v_mov_b32_e32 v152, 0
	s_waitcnt vmcnt(4)
	ds_write2_b64 v2, v[50:51], v[52:53] offset1:1
	v_add_u32_e32 v2, 0x18600, v30
	v_mov_b32_e32 v151, 0
	s_waitcnt vmcnt(3)
	ds_write2_b64 v2, v[54:55], v[56:57] offset1:1
	v_add_u32_e32 v2, 0x1a680, v30
	v_mov_b32_e32 v150, 0
	s_waitcnt vmcnt(2)
	ds_write2_b64 v2, v[58:59], v[60:61] offset1:1
	v_add_u32_e32 v2, 0x1c700, v30
	v_mov_b32_e32 v141, 0
	s_waitcnt vmcnt(1)
	ds_write2_b64 v2, v[118:119], v[120:121] offset1:1
	v_add_u32_e32 v2, 0x1e780, v30
	s_waitcnt vmcnt(0)
	ds_write2_b64 v2, v[122:123], v[124:125] offset1:1
	v_mov_b32_e32 v140, 0
	v_mov_b32_e32 v139, 0
	v_mov_b32_e32 v138, 0
	v_mov_b32_e32 v137, 0
	v_mov_b32_e32 v136, 0
	v_mov_b32_e32 v135, 0
	v_mov_b32_e32 v134, 0
	v_mov_b32_e32 v129, 0
	v_mov_b32_e32 v128, 0
	v_mov_b32_e32 v127, 0
	v_mov_b32_e32 v126, 0
	v_mov_b32_e32 v125, 0
	v_mov_b32_e32 v124, 0
	v_mov_b32_e32 v123, 0
	v_mov_b32_e32 v122, 0
	v_mov_b32_e32 v121, 0
	v_mov_b32_e32 v120, 0
	v_mov_b32_e32 v119, 0
	v_mov_b32_e32 v118, 0
	v_mov_b32_e32 v145, 0
	v_mov_b32_e32 v144, 0
	v_mov_b32_e32 v143, 0
	v_mov_b32_e32 v142, 0
	s_waitcnt lgkmcnt(0)
	s_barrier
	s_cbranch_vccnz .LBB0_888
	s_mov_b32 s9, s17
	s_cmpk_gt_i32 s17, 0x3ff
	s_mov_b64 s[6:7], -1
	s_cbranch_scc0 .LBB0_885
	s_and_b32 s4, s69, 0x7fffff00
	s_add_i32 s4, s4, 0xffff0000
	s_mov_b32 s5, s63
	s_mov_b64 s[6:7], 0
; #define GAS __attribute__((address_space(1)))
; __device__ __forceinline__ const bf16_t* attn_kptr(unsigned char* ws, int l, int u) {
;     if (u < NB * 32) { const int b = u >> 5, h = (u >> 3) & 3; return (const bf16_t*)(ws + WS_KB) + (size_t)l * TM * D + (size_t)(b * NMEM) * D + h * 256; }
;     const int i = u - NB * 32, b = i >> 2, h = i & 3; return (const bf16_t*)(ws + WS_KC) + (size_t)l * TMS * D + (size_t)(b * NMEM) * D + h * 256;
; }
; __device__ __forceinline__ void attn_phase(unsigned char* ws, int l, LAS unsigned char* lds, int G, int bid) {
;     ...
;             const int un = u + G; have = un < NU;
;             if (have) { const char* kb = (const char*)attn_kptr(ws, l, un); const unsigned off = (unsigned)((vr * D + vc * 8) * 2);
; #pragma unroll
;                 for (int i = 0; i < 16; ++i) kpre[i] = *(const GAS u32x4*)(kb + (size_t)(16 * i) * D * 2 + off); }
;             else {
; #pragma unroll
;                 for (int i = 0; i < 16; ++i) kpre[i] = (u32x4){0u, 0u, 0u, 0u}; }
.LBB0_885:
	s_mov_b32 s8, 8
	s_andn2_b64 vcc, exec, s[6:7]
	s_mov_b64 s[6:7], s[56:57]
	s_cbranch_vccnz .LBB0_887
	s_and_b32 s9, s17, 7
	s_lshl_b32 s9, s9, 7
	s_lshr_b32 s4, s17, 3
	s_or_b32 s9, s9, s4
	s_lshl_b32 s4, s9, 3
	s_and_b32 s4, s4, 0xffffff00
	s_ashr_i32 s5, s4, 31
	s_mov_b32 s8, 5
	s_mov_b64 s[6:7], s[84:85]
.LBB0_887:
	s_lshl_b64 s[4:5], s[4:5], 11
	s_add_u32 s4, s6, s4
	s_addc_u32 s5, s7, s5
	s_lshl_b32 s6, s9, s8
	s_and_b32 s6, s6, 0x300
	s_lshl_b32 s6, s6, 1
	s_add_u32 s4, s4, s6
	s_addc_u32 s5, s5, 0
	v_mov_b32_e32 v217, v65
	v_lshl_add_u64 v[2:3], s[4:5], 0, v[216:217]
	v_add_co_u32_e32 v4, vcc, s15, v2
	s_mov_b32 s6, 0x48000
	s_nop 0
	v_addc_co_u32_e32 v5, vcc, 0, v3, vcc
	v_add_co_u32_e32 v6, vcc, s13, v2
	s_nop 1
	v_addc_co_u32_e32 v7, vcc, 0, v3, vcc
	global_load_dwordx4 v[118:121], v[4:5], off
	global_load_dwordx4 v[122:125], v[6:7], off
	v_add_co_u32_e32 v4, vcc, s14, v2
	s_nop 1
	v_addc_co_u32_e32 v5, vcc, 0, v3, vcc
	v_add_co_u32_e32 v6, vcc, s20, v2
	s_nop 1
	v_addc_co_u32_e32 v7, vcc, 0, v3, vcc
	global_load_dwordx4 v[126:129], v[4:5], off
	global_load_dwordx4 v[134:137], v[6:7], off
	v_add_co_u32_e32 v4, vcc, s21, v2
	s_nop 1
	v_addc_co_u32_e32 v5, vcc, 0, v3, vcc
	v_add_co_u32_e32 v6, vcc, s22, v2
	s_nop 1
	v_addc_co_u32_e32 v7, vcc, 0, v3, vcc
	global_load_dwordx4 v[138:141], v[4:5], off
	global_load_dwordx4 v[150:153], v[6:7], off
	v_add_co_u32_e32 v4, vcc, s23, v2
	s_nop 1
	v_addc_co_u32_e32 v5, vcc, 0, v3, vcc
	v_add_co_u32_e32 v6, vcc, s19, v2
	s_nop 1
	v_addc_co_u32_e32 v7, vcc, 0, v3, vcc
	global_load_dwordx4 v[158:161], v[4:5], off
	global_load_dwordx4 v[162:165], v[6:7], off
	v_add_co_u32_e32 v4, vcc, s6, v2
	s_mov_b32 s6, 0x50000
	s_nop 0
	v_addc_co_u32_e32 v5, vcc, 0, v3, vcc
	v_add_co_u32_e32 v6, vcc, s6, v2
	s_mov_b32 s6, 0x58000
	s_nop 0
	v_addc_co_u32_e32 v7, vcc, 0, v3, vcc
	global_load_dwordx4 v[166:169], v[4:5], off
	global_load_dwordx4 v[170:173], v[6:7], off
	v_add_co_u32_e32 v4, vcc, s6, v2
	s_mov_b32 s6, 0x60000
	s_nop 0
	v_addc_co_u32_e32 v5, vcc, 0, v3, vcc
	v_add_co_u32_e32 v6, vcc, s6, v2
	s_mov_b32 s6, 0x68000
	s_nop 0
	v_addc_co_u32_e32 v7, vcc, 0, v3, vcc
	global_load_dwordx4 v[174:177], v[4:5], off
	global_load_dwordx4 v[178:181], v[6:7], off
	v_add_co_u32_e32 v4, vcc, s6, v2
	s_mov_b32 s6, 0x70000
	s_nop 0
	v_addc_co_u32_e32 v5, vcc, 0, v3, vcc
	v_add_co_u32_e32 v6, vcc, s6, v2
	s_mov_b32 s6, 0x78000
	s_nop 0
	v_addc_co_u32_e32 v7, vcc, 0, v3, vcc
	v_add_co_u32_e32 v2, vcc, s6, v2
	global_load_dwordx4 v[186:189], v[4:5], off
	global_load_dwordx4 v[190:193], v[6:7], off
	v_addc_co_u32_e32 v3, vcc, 0, v3, vcc
	global_load_dwordx4 v[142:145], v216, s[4:5]
	global_load_dwordx4 v[66:69], v[2:3], off

;     __device__ bool next(int i, Unit& u) const {
;         const long L = (long)i * G + c; if (L >= nwg) return false;
;         int wgid = (int)L; { const int q = nwg / NXCD, r = nwg % NXCD, xcd = wgid % NXCD, off = wgid / NXCD; wgid = (xcd < r ? xcd * (q + 1) : r * (q + 1) + (xcd - r) * q) + off; }
;         const int nig = WGM * nN, gid = wgid / nig, fm = gid * WGM, gsz = (nM - fm) < WGM ? (nM - fm) : WGM;
;         u.pm = fm + ((wgid % nig) % gsz); u.pn = (wgid % nig) / gsz; u.ko = 0; return true;
;     }
.LBB0_944:
	s_or_b64 exec, exec, s[0:1]
	s_mov_b32 s8, s90
	s_mov_b64 s[0:1], s[74:75]
	s_mov_b32 s9, s83
	s_mov_b32 s5, s14
	s_waitcnt lgkmcnt(0)
	s_barrier
	v_mov_b32_e32 v8, v242
	s_cmpk_lt_i32 s9, 0x410
	s_cselect_b64 s[2:3], -1, 0
	s_cmpk_gt_i32 s9, 0x40f
	v_readfirstlane_b32 s4, v8
	s_cbranch_scc1 .LBB0_946
	s_ashr_i32 s6, s9, 31
	s_lshr_b32 s6, s6, 29
	s_add_i32 s6, s9, s6
	s_ashr_i32 s7, s6, 3
	s_and_b32 s6, s6, -8
	s_sub_i32 s6, s9, s6
	s_cmp_lt_i32 s6, 0
	s_movk_i32 s10, 0x80
	s_cselect_b32 s10, s10, 0x80
	s_mul_i32 s6, s6, s10
	s_sub_i32 s7, 0x7f, s7
	s_add_i32 s6, s6, s7
	s_ashr_i32 s7, s6, 31
	s_lshr_b32 s7, s7, 27
	s_add_i32 s7, s6, s7
	s_ashr_i32 s10, s7, 5
	s_lshl_b32 s10, s10, 3
	s_sub_i32 s11, 0x104, s10
	s_min_u32 s11, s11, 8
	s_andn2_b32 s7, s7, 31
	s_sub_i32 s12, s6, s7
	v_cvt_f32_ubyte0_e32 v1, s11
	v_cvt_f32_i32_e32 v0, s12
	v_rcp_iflag_f32_e32 v2, v1
	s_ashr_i32 s6, s12, 30
	s_or_b32 s13, s6, 1
	v_mul_f32_e32 v2, v0, v2
	v_trunc_f32_e32 v2, v2
	v_fma_f32 v0, -v2, v1, v0
	v_cvt_i32_f32_e32 v2, v2
	v_cmp_ge_f32_e64 s[6:7], |v0|, v1
	s_and_b64 s[6:7], s[6:7], exec
	s_cselect_b32 s6, s13, 0
	v_readfirstlane_b32 s7, v2
	s_add_i32 s6, s7, s6
	s_sext_i32_i8 s16, s6
	s_mul_i32 s6, s6, s11
	s_sub_i32 s6, s12, s6
	s_sext_i32_i8 s6, s6
	s_add_i32 s90, s10, s6

;     __device__ bool next(int i, Unit& u) const {
;         const long L = (long)i * G + c; if (L >= nwg) return false;
;         int wgid = (int)L; { const int q = nwg / NXCD, r = nwg % NXCD, xcd = wgid % NXCD, off = wgid / NXCD; wgid = (xcd < r ? xcd * (q + 1) : r * (q + 1) + (xcd - r) * q) + off; }
;         const int nig = WGM * nN, gid = wgid / nig, fm = gid * WGM, gsz = (nM - fm) < WGM ? (nM - fm) : WGM;
;         u.pm = fm + ((wgid % nig) % gsz); u.pn = (wgid % nig) / gsz; u.ko = 0; return true;
;     }
; template <class Epi, bool SP2, class Sched>
; __device__ __forceinline__ void gemm_phase(LAS unsigned char* lds, const Gemm g, const Sched& S, const Epi& E) {
;     ...
;         const bool has_next = S.next(ui + 1, nxt);
;         const char* nA = has_next ? (const char*)g.A + (size_t)nxt.pm * tstep + nxt.ko : cA; const char* nB = has_next ? (const char*)g.Bt + (size_t)nxt.pn * tstepB + nxt.ko : cB;
.LBB0_952:
	s_add_i32 s33, s33, 1
	s_mul_i32 s2, s33, s69
	s_mul_hi_u32 s3, s33, s8
	s_add_i32 s3, s3, s2
	s_mul_i32 s2, s33, s8
	s_add_u32 s86, s2, s9
	s_addc_u32 s87, s3, s72
	v_cmp_gt_i64_e32 vcc, s[86:87], v[204:205]
	v_cmp_lt_i64_e64 s[2:3], s[86:87], v[202:203]
	s_cbranch_vccnz .LBB0_954
	s_ashr_i32 s4, s86, 31
	s_lshr_b32 s4, s4, 29
	s_add_i32 s4, s86, s4
	s_ashr_i32 s5, s4, 3
	s_and_b32 s4, s4, -8
	s_sub_i32 s4, s86, s4
	s_cmp_lt_i32 s4, 0
	s_movk_i32 s20, 0x80
	s_cselect_b32 s20, s20, 0x80
	s_mul_i32 s4, s4, s20
	s_sub_i32 s5, 0x7f, s5
	s_add_i32 s4, s4, s5
	s_cmpk_lt_i32 s86, 0x400
	s_cselect_b32 s4, s4, s86
	s_ashr_i32 s5, s4, 31
	s_lshr_b32 s5, s5, 27
	s_add_i32 s5, s4, s5
	s_ashr_i32 s20, s5, 5
	s_lshl_b32 s20, s20, 3
	s_sub_i32 s21, 0x104, s20
	s_min_i32 s21, s21, 8
	s_abs_i32 s22, s21
	v_cvt_f32_u32_e32 v0, s22
	s_sub_i32 s24, 0, s22
	s_andn2_b32 s5, s5, 31
	s_sub_i32 s5, s4, s5
	v_rcp_iflag_f32_e32 v0, v0
	s_abs_i32 s4, s5
	s_xor_b32 s23, s5, s21
	s_ashr_i32 s23, s23, 31
	v_mul_f32_e32 v0, 0x4f7ffffe, v0
	v_cvt_u32_f32_e32 v0, v0
	s_nop 0
	v_readfirstlane_b32 s25, v0
	s_mul_i32 s24, s24, s25
	s_mul_hi_u32 s24, s25, s24
	s_add_i32 s25, s25, s24
	s_mul_hi_u32 s24, s4, s25
	s_mul_i32 s25, s24, s22
	s_sub_i32 s4, s4, s25
	s_add_i32 s73, s24, 1
	s_sub_i32 s25, s4, s22
	s_cmp_ge_u32 s4, s22
	s_cselect_b32 s24, s73, s24
	s_cselect_b32 s4, s25, s4
	s_add_i32 s25, s24, 1
	s_cmp_ge_u32 s4, s22
	s_cselect_b32 s4, s25, s24
	s_xor_b32 s4, s4, s23
	s_sub_i32 s4, s4, s23
	s_mul_i32 s21, s4, s21
	s_sub_i32 s5, s5, s21
	s_add_i32 s84, s20, s5

; #define GAS __attribute__((address_space(1)))
;     __device__ __forceinline__ void operator()(const Acc& acc, const Unit& u, int wr, int wc, int fr, int fq) const {
;         const int row0 = u.pm * 256 + wr * 64 + fr, col0 = u.pn * 256 + wc * 32 + 8 * fq;
; #pragma unroll
;         for (int ai = 0; ai < 2; ++ai)
; #pragma unroll
;             for (int m = 0; m < 4; ++m) {
;                 const int r = row0 + ai * 128 + m * 16; float ssum = 0.f;
; #pragma unroll
;                 for (int bj = 0; bj < 2; ++bj) {
;                     bf16_t* p = XB + (size_t)r * D + col0 + bj * 128;
;                     f32x4 x0, x1; unpack8(*(const GAS u32x4*)p, x0, x1);
;                     x0 += acc[ai][bj][m][0]; x1 += acc[ai][bj][m][1];
; #pragma unroll
;                     for (int e = 0; e < 4; ++e) ssum += x0[e] * x0[e] + x1[e] * x1[e];
;                     store8_bf16(p, x0, x1);
;                 }
;                 ssum += __shfl_xor(ssum, 16); ssum += __shfl_xor(ssum, 32);
;                 if (fq == 0) atomicAdd(ssout + r, ssum);
;             }
;     }
.LBB0_958:
	v_lshl_add_u32 v144, s90, 8, v146
	v_ashrrev_i32_e32 v145, 31, v144
	v_lshl_or_b32 v142, s16, 8, v148
	v_lshlrev_b64 v[140:141], 11, v[144:145]
	v_ashrrev_i32_e32 v143, 31, v142
	v_lshl_add_u64 v[140:141], s[56:57], 0, v[140:141]
	v_lshl_add_u64 v[140:141], v[142:143], 1, v[140:141]
	global_load_dwordx4 v[150:153], v[140:141], off
	global_load_dwordx4 v[158:161], v[140:141], off offset:256
	v_add_co_u32_e32 v238, vcc, 0x8000, v140
	s_nop 1
	v_addc_co_u32_e32 v239, vcc, 0, v141, vcc
	global_load_dwordx4 v[162:165], v[238:239], off
	global_load_dwordx4 v[166:169], v[238:239], off offset:256
	v_add_co_u32_e32 v238, vcc, 0x10000, v140
	s_nop 1
	v_addc_co_u32_e32 v239, vcc, 0, v141, vcc
	global_load_dwordx4 v[170:173], v[238:239], off
	global_load_dwordx4 v[174:177], v[238:239], off offset:256
	v_add_co_u32_e32 v238, vcc, 0x18000, v140
	s_nop 1
	v_addc_co_u32_e32 v239, vcc, 0, v141, vcc
	global_load_dwordx4 v[178:181], v[238:239], off
	global_load_dwordx4 v[182:185], v[238:239], off offset:256
	v_add_co_u32_e32 v238, vcc, 0x40000, v140
	s_nop 1
	v_addc_co_u32_e32 v239, vcc, 0, v141, vcc
	global_load_dwordx4 v[186:189], v[238:239], off
	global_load_dwordx4 v[190:193], v[238:239], off offset:256
	v_add_co_u32_e32 v238, vcc, 0x48000, v140
	s_nop 1
	v_addc_co_u32_e32 v239, vcc, 0, v141, vcc
	global_load_dwordx4 v[214:217], v[238:239], off
	global_load_dwordx4 v[218:221], v[238:239], off offset:256
	v_add_co_u32_e32 v238, vcc, 0x50000, v140
	s_nop 1
	v_addc_co_u32_e32 v239, vcc, 0, v141, vcc
	global_load_dwordx4 v[222:225], v[238:239], off
	global_load_dwordx4 v[226:229], v[238:239], off offset:256
	v_add_co_u32_e32 v238, vcc, 0x58000, v140
	s_nop 1
	v_addc_co_u32_e32 v239, vcc, 0, v141, vcc
	global_load_dwordx4 v[230:233], v[238:239], off
	global_load_dwordx4 v[234:237], v[238:239], off offset:256
	s_waitcnt vmcnt(8)
	v_lshlrev_b32_e32 v154, 16, v150
	v_and_b32_e32 v155, 0xffff0000, v150
	v_lshlrev_b32_e32 v150, 16, v151
	v_and_b32_e32 v151, 0xffff0000, v151
	v_lshlrev_b32_e32 v156, 16, v152
	v_and_b32_e32 v157, 0xffff0000, v152
	v_lshlrev_b32_e32 v152, 16, v153
	v_and_b32_e32 v153, 0xffff0000, v153
	v_pk_add_f32 v[128:129], v[128:129], v[150:151]
	v_pk_add_f32 v[150:151], v[124:125], v[152:153]
	v_pk_add_f32 v[124:125], v[122:123], v[156:157]
	v_pk_add_f32 v[126:127], v[126:127], v[154:155]
	v_mul_f32_e32 v122, v124, v124
	v_mul_f32_e32 v123, v125, v125
	v_fmac_f32_e32 v122, v126, v126
	v_fmac_f32_e32 v123, v127, v127
	v_add_f32_e32 v122, v122, v123
	v_mul_f32_e32 v123, v150, v150
	v_fmac_f32_e32 v123, v128, v128
	v_add_f32_e32 v122, v123, v122
	v_mul_f32_e32 v123, v151, v151
	v_fmac_f32_e32 v123, v129, v129
	v_add_f32_e32 v152, v123, v122
	v_cvt_pk_bf16_f32 v122, v126, v127
	v_cvt_pk_bf16_f32 v123, v128, v129
	v_cvt_pk_bf16_f32 v124, v124, v125
	v_cvt_pk_bf16_f32 v125, v150, v151
	global_store_dwordx4 v[140:141], v[122:125], off
	s_nop 1
	v_mov_b64_e32 v[122:123], v[158:159]
	v_mov_b64_e32 v[124:125], v[160:161]
	s_nop 0
	v_lshlrev_b32_e32 v126, 16, v122
	v_and_b32_e32 v127, 0xffff0000, v122
	v_lshlrev_b32_e32 v122, 16, v123
	v_and_b32_e32 v123, 0xffff0000, v123
	v_lshlrev_b32_e32 v128, 16, v124
	v_and_b32_e32 v129, 0xffff0000, v124
	v_lshlrev_b32_e32 v124, 16, v125
	v_and_b32_e32 v125, 0xffff0000, v125
	v_pk_add_f32 v[120:121], v[120:121], v[122:123]
	v_pk_add_f32 v[122:123], v[116:117], v[124:125]
	v_pk_add_f32 v[116:117], v[114:115], v[128:129]
	v_pk_add_f32 v[118:119], v[118:119], v[126:127]
	v_mul_f32_e32 v114, v116, v116
	v_fmac_f32_e32 v114, v118, v118
	v_mul_f32_e32 v115, v117, v117
	v_add_f32_e32 v114, v152, v114
	v_fmac_f32_e32 v115, v119, v119
	v_add_f32_e32 v114, v115, v114
	v_mul_f32_e32 v115, v122, v122
	v_fmac_f32_e32 v115, v120, v120
	v_add_f32_e32 v114, v115, v114
	v_mul_f32_e32 v115, v123, v123
	v_fmac_f32_e32 v115, v121, v121
	v_add_f32_e32 v124, v115, v114
	v_cvt_pk_bf16_f32 v114, v118, v119
	v_cvt_pk_bf16_f32 v115, v120, v121
	v_cvt_pk_bf16_f32 v116, v116, v117
	v_cvt_pk_bf16_f32 v117, v122, v123
	global_store_dwordx4 v[140:141], v[114:117], off offset:256
	s_nop 1
	v_xor_b32_e32 v114, 16, v246
	v_add_u32_e32 v115, 64, v247
	v_cmp_lt_i32_e32 vcc, v114, v115
	s_nop 1
	v_cndmask_b32_e32 v114, v246, v114, vcc
	v_lshlrev_b32_e32 v116, 2, v114
	v_mov_b32_e32 v114, v124
	v_mov_b32_e32 v254, v124
	s_nop 1
	v_permlane16_swap_b32_e32 v114, v254
	s_waitcnt lgkmcnt(0)
	v_add_f32_e32 v118, v254, v114
	v_xor_b32_e32 v114, 32, v246
	v_cmp_lt_i32_e32 vcc, v114, v115
	s_nop 1
	v_cndmask_b32_e32 v114, v246, v114, vcc
	v_lshlrev_b32_e32 v117, 2, v114
	v_mov_b32_e32 v119, v118
	v_mov_b32_e32 v254, v118
	s_nop 1
	v_permlane32_swap_b32_e32 v119, v254
	v_lshl_add_u64 v[114:115], v[144:145], 2, s[58:59]
	s_and_saveexec_b64 s[6:7], s[0:1]
	s_cbranch_execz .LBB0_960
	s_waitcnt lgkmcnt(0)
	v_add_f32_e32 v118, v254, v119
	flat_atomic_add_f32 v[114:115], v118
; #define GAS __attribute__((address_space(1)))
;     __device__ __forceinline__ void operator()(const Acc& acc, const Unit& u, int wr, int wc, int fr, int fq) const {
;         const int row0 = u.pm * 256 + wr * 64 + fr, col0 = u.pn * 256 + wc * 32 + 8 * fq;
; #pragma unroll
;         for (int ai = 0; ai < 2; ++ai)
; #pragma unroll
;             for (int m = 0; m < 4; ++m) {
;                 const int r = row0 + ai * 128 + m * 16; float ssum = 0.f;
; #pragma unroll
;                 for (int bj = 0; bj < 2; ++bj) {
;                     bf16_t* p = XB + (size_t)r * D + col0 + bj * 128;
;                     f32x4 x0, x1; unpack8(*(const GAS u32x4*)p, x0, x1);
;                     x0 += acc[ai][bj][m][0]; x1 += acc[ai][bj][m][1];
; #pragma unroll
;                     for (int e = 0; e < 4; ++e) ssum += x0[e] * x0[e] + x1[e] * x1[e];
;                     store8_bf16(p, x0, x1);
;                 }
;                 ssum += __shfl_xor(ssum, 16); ssum += __shfl_xor(ssum, 32);
;                 if (fq == 0) atomicAdd(ssout + r, ssum);
;             }
;     }
.LBB0_960:
	s_or_b64 exec, exec, s[6:7]
	v_or_b32_e32 v118, 16, v144
	s_waitcnt lgkmcnt(0)
	v_ashrrev_i32_e32 v119, 31, v118
	v_lshlrev_b64 v[118:119], 11, v[118:119]
	v_lshl_add_u64 v[118:119], s[56:57], 0, v[118:119]
	v_lshl_add_u64 v[122:123], v[142:143], 1, v[118:119]
	s_nop 1
	v_mov_b64_e32 v[118:119], v[162:163]
	v_mov_b64_e32 v[120:121], v[164:165]
	s_nop 0
	v_lshlrev_b32_e32 v124, 16, v118
	v_and_b32_e32 v125, 0xffff0000, v118
	v_lshlrev_b32_e32 v118, 16, v119
	v_and_b32_e32 v119, 0xffff0000, v119
	v_lshlrev_b32_e32 v126, 16, v120
	v_and_b32_e32 v127, 0xffff0000, v120
	v_lshlrev_b32_e32 v120, 16, v121
	v_and_b32_e32 v121, 0xffff0000, v121
	v_pk_add_f32 v[118:119], v[112:113], v[118:119]
	v_pk_add_f32 v[124:125], v[110:111], v[124:125]
	v_pk_add_f32 v[120:121], v[108:109], v[120:121]
	v_pk_add_f32 v[126:127], v[106:107], v[126:127]
	v_cvt_pk_bf16_f32 v106, v124, v125
	v_cvt_pk_bf16_f32 v107, v118, v119
	s_nop 0
	v_cvt_pk_bf16_f32 v108, v126, v127
	v_cvt_pk_bf16_f32 v109, v120, v121
	s_nop 1
	v_mov_b64_e32 v[110:111], v[166:167]
	v_mov_b64_e32 v[112:113], v[168:169]
	v_mul_f32_e32 v126, v126, v126
	v_mul_f32_e32 v127, v127, v127
	v_mul_f32_e32 v120, v120, v120
	v_fmac_f32_e32 v126, v124, v124
	v_fmac_f32_e32 v127, v125, v125
	v_mul_f32_e32 v121, v121, v121
	v_fmac_f32_e32 v120, v118, v118
	v_add_f32_e32 v118, v126, v127
	v_fmac_f32_e32 v121, v119, v119
	v_add_f32_e32 v118, v120, v118
	v_add_f32_e32 v124, v121, v118
	global_store_dwordx4 v[122:123], v[106:109], off
	s_nop 0
	v_lshlrev_b32_e32 v118, 16, v110
	v_and_b32_e32 v119, 0xffff0000, v110
	v_lshlrev_b32_e32 v110, 16, v111
	v_and_b32_e32 v111, 0xffff0000, v111
	v_lshlrev_b32_e32 v120, 16, v112
	v_and_b32_e32 v121, 0xffff0000, v112
	v_lshlrev_b32_e32 v112, 16, v113
	v_and_b32_e32 v113, 0xffff0000, v113
	v_pk_add_f32 v[104:105], v[104:105], v[110:111]
	v_pk_add_f32 v[110:111], v[100:101], v[112:113]
	v_pk_add_f32 v[112:113], v[98:99], v[120:121]
	v_pk_add_f32 v[102:103], v[102:103], v[118:119]
	v_mul_f32_e32 v98, v112, v112
	v_mul_f32_e32 v99, v113, v113
	v_fmac_f32_e32 v98, v102, v102
	v_mul_f32_e32 v100, v110, v110
	v_fmac_f32_e32 v99, v103, v103
	v_add_f32_e32 v98, v124, v98
	v_mul_f32_e32 v101, v111, v111
	v_fmac_f32_e32 v100, v104, v104
	v_add_f32_e32 v98, v99, v98
	v_add_f32_e32 v98, v100, v98
	v_fmac_f32_e32 v101, v105, v105
	v_add_f32_e32 v98, v101, v98
	v_mov_b32_e32 v99, v98
	v_mov_b32_e32 v254, v98
	s_nop 1
	v_permlane16_swap_b32_e32 v99, v254
	v_cvt_pk_bf16_f32 v100, v102, v103
	v_cvt_pk_bf16_f32 v101, v104, v105
	v_cvt_pk_bf16_f32 v102, v112, v113
	v_cvt_pk_bf16_f32 v103, v110, v111
	s_waitcnt lgkmcnt(0)
	v_add_f32_e32 v98, v254, v99
	v_mov_b32_e32 v99, v98
	v_mov_b32_e32 v254, v98
	s_nop 1
	v_permlane32_swap_b32_e32 v99, v254
	global_store_dwordx4 v[122:123], v[100:103], off offset:256
	s_and_saveexec_b64 s[6:7], s[0:1]
	s_cbranch_execz .LBB0_962
	s_waitcnt lgkmcnt(0)
	v_add_f32_e32 v98, v254, v99
	flat_atomic_add_f32 v[114:115], v98 offset:64
.LBB0_962:
	s_or_b64 exec, exec, s[6:7]
	v_or_b32_e32 v98, 32, v144
	s_waitcnt lgkmcnt(0)
	v_ashrrev_i32_e32 v99, 31, v98
	v_lshlrev_b64 v[98:99], 11, v[98:99]
	v_lshl_add_u64 v[98:99], s[56:57], 0, v[98:99]
	v_lshl_add_u64 v[102:103], v[142:143], 1, v[98:99]
	s_nop 1
	v_mov_b64_e32 v[98:99], v[170:171]
	v_mov_b64_e32 v[100:101], v[172:173]
	s_nop 0
	v_lshlrev_b32_e32 v104, 16, v98
	v_and_b32_e32 v105, 0xffff0000, v98
	v_lshlrev_b32_e32 v98, 16, v99
	v_and_b32_e32 v99, 0xffff0000, v99
	v_lshlrev_b32_e32 v106, 16, v100
	v_and_b32_e32 v107, 0xffff0000, v100
	v_lshlrev_b32_e32 v100, 16, v101
	v_and_b32_e32 v101, 0xffff0000, v101
	v_pk_add_f32 v[98:99], v[96:97], v[98:99]
	v_pk_add_f32 v[104:105], v[94:95], v[104:105]
	v_pk_add_f32 v[100:101], v[92:93], v[100:101]
	v_pk_add_f32 v[106:107], v[90:91], v[106:107]
	v_cvt_pk_bf16_f32 v90, v104, v105
	v_cvt_pk_bf16_f32 v91, v98, v99
	s_nop 0
	v_cvt_pk_bf16_f32 v92, v106, v107
	v_cvt_pk_bf16_f32 v93, v100, v101
	s_nop 1
	v_mov_b64_e32 v[94:95], v[174:175]
	v_mov_b64_e32 v[96:97], v[176:177]
	v_mul_f32_e32 v106, v106, v106
	v_mul_f32_e32 v107, v107, v107
	v_mul_f32_e32 v100, v100, v100
	v_fmac_f32_e32 v106, v104, v104
	v_fmac_f32_e32 v107, v105, v105
	v_mul_f32_e32 v101, v101, v101
	v_fmac_f32_e32 v100, v98, v98
	v_add_f32_e32 v98, v106, v107
	v_fmac_f32_e32 v101, v99, v99
	v_add_f32_e32 v98, v100, v98
	v_add_f32_e32 v104, v101, v98
	global_store_dwordx4 v[102:103], v[90:93], off
	s_nop 0
	v_lshlrev_b32_e32 v98, 16, v94
	v_and_b32_e32 v99, 0xffff0000, v94
	v_lshlrev_b32_e32 v94, 16, v95
	v_and_b32_e32 v95, 0xffff0000, v95
	v_lshlrev_b32_e32 v100, 16, v96
	v_and_b32_e32 v101, 0xffff0000, v96
	v_lshlrev_b32_e32 v96, 16, v97
	v_and_b32_e32 v97, 0xffff0000, v97
	v_pk_add_f32 v[88:89], v[88:89], v[94:95]
	v_pk_add_f32 v[94:95], v[84:85], v[96:97]
	v_pk_add_f32 v[96:97], v[82:83], v[100:101]
	v_pk_add_f32 v[86:87], v[86:87], v[98:99]
	v_mul_f32_e32 v82, v96, v96
	v_mul_f32_e32 v83, v97, v97
	v_fmac_f32_e32 v82, v86, v86
	v_mul_f32_e32 v84, v94, v94
	v_fmac_f32_e32 v83, v87, v87
	v_add_f32_e32 v82, v104, v82
	v_mul_f32_e32 v85, v95, v95
	v_fmac_f32_e32 v84, v88, v88
	v_add_f32_e32 v82, v83, v82
	v_add_f32_e32 v82, v84, v82
	v_fmac_f32_e32 v85, v89, v89
	v_add_f32_e32 v82, v85, v82
	v_mov_b32_e32 v83, v82
	v_mov_b32_e32 v254, v82
	s_nop 1
	v_permlane16_swap_b32_e32 v83, v254
	v_cvt_pk_bf16_f32 v84, v86, v87
	v_cvt_pk_bf16_f32 v85, v88, v89
	v_cvt_pk_bf16_f32 v86, v96, v97
	v_cvt_pk_bf16_f32 v87, v94, v95
	s_waitcnt lgkmcnt(0)
	v_add_f32_e32 v82, v254, v83
	v_mov_b32_e32 v83, v82
	v_mov_b32_e32 v254, v82
	s_nop 1
	v_permlane32_swap_b32_e32 v83, v254
	global_store_dwordx4 v[102:103], v[84:87], off offset:256
	s_and_saveexec_b64 s[6:7], s[0:1]
	s_cbranch_execz .LBB0_964
	s_waitcnt lgkmcnt(0)
	v_add_f32_e32 v82, v254, v83
	flat_atomic_add_f32 v[114:115], v82 offset:128
; #define GAS __attribute__((address_space(1)))
;     __device__ __forceinline__ void operator()(const Acc& acc, const Unit& u, int wr, int wc, int fr, int fq) const {
;         const int row0 = u.pm * 256 + wr * 64 + fr, col0 = u.pn * 256 + wc * 32 + 8 * fq;
; #pragma unroll
;         for (int ai = 0; ai < 2; ++ai)
; #pragma unroll
;             for (int m = 0; m < 4; ++m) {
;                 const int r = row0 + ai * 128 + m * 16; float ssum = 0.f;
; #pragma unroll
;                 for (int bj = 0; bj < 2; ++bj) {
;                     bf16_t* p = XB + (size_t)r * D + col0 + bj * 128;
;                     f32x4 x0, x1; unpack8(*(const GAS u32x4*)p, x0, x1);
;                     x0 += acc[ai][bj][m][0]; x1 += acc[ai][bj][m][1];
; #pragma unroll
;                     for (int e = 0; e < 4; ++e) ssum += x0[e] * x0[e] + x1[e] * x1[e];
;                     store8_bf16(p, x0, x1);
;                 }
;                 ssum += __shfl_xor(ssum, 16); ssum += __shfl_xor(ssum, 32);
;                 if (fq == 0) atomicAdd(ssout + r, ssum);
;             }
;     }
.LBB0_964:
	s_or_b64 exec, exec, s[6:7]
	v_or_b32_e32 v82, 48, v144
	s_waitcnt lgkmcnt(0)
	v_ashrrev_i32_e32 v83, 31, v82
	v_lshlrev_b64 v[82:83], 11, v[82:83]
	v_lshl_add_u64 v[82:83], s[56:57], 0, v[82:83]
	v_lshl_add_u64 v[86:87], v[142:143], 1, v[82:83]
	s_nop 1
	v_mov_b64_e32 v[82:83], v[178:179]
	v_mov_b64_e32 v[84:85], v[180:181]
	s_nop 0
	v_lshlrev_b32_e32 v88, 16, v82
	v_and_b32_e32 v89, 0xffff0000, v82
	v_lshlrev_b32_e32 v82, 16, v83
	v_and_b32_e32 v83, 0xffff0000, v83
	v_lshlrev_b32_e32 v90, 16, v84
	v_and_b32_e32 v91, 0xffff0000, v84
	v_lshlrev_b32_e32 v84, 16, v85
	v_and_b32_e32 v85, 0xffff0000, v85
	v_pk_add_f32 v[82:83], v[80:81], v[82:83]
	v_pk_add_f32 v[88:89], v[78:79], v[88:89]
	v_pk_add_f32 v[84:85], v[76:77], v[84:85]
	v_pk_add_f32 v[90:91], v[74:75], v[90:91]
	v_cvt_pk_bf16_f32 v74, v88, v89
	v_cvt_pk_bf16_f32 v75, v82, v83
	s_nop 0
	v_cvt_pk_bf16_f32 v76, v90, v91
	v_cvt_pk_bf16_f32 v77, v84, v85
	s_nop 1
	v_mov_b64_e32 v[78:79], v[182:183]
	v_mov_b64_e32 v[80:81], v[184:185]
	v_mul_f32_e32 v90, v90, v90
	v_mul_f32_e32 v91, v91, v91
	v_mul_f32_e32 v84, v84, v84
	v_fmac_f32_e32 v90, v88, v88
	v_fmac_f32_e32 v91, v89, v89
	v_mul_f32_e32 v85, v85, v85
	v_fmac_f32_e32 v84, v82, v82
	v_add_f32_e32 v82, v90, v91
	v_fmac_f32_e32 v85, v83, v83
	v_add_f32_e32 v82, v84, v82
	v_add_f32_e32 v88, v85, v82
	global_store_dwordx4 v[86:87], v[74:77], off
	s_nop 0
	v_lshlrev_b32_e32 v82, 16, v78
	v_and_b32_e32 v83, 0xffff0000, v78
	v_lshlrev_b32_e32 v78, 16, v79
	v_and_b32_e32 v79, 0xffff0000, v79
	v_lshlrev_b32_e32 v84, 16, v80
	v_and_b32_e32 v85, 0xffff0000, v80
	v_lshlrev_b32_e32 v80, 16, v81
	v_and_b32_e32 v81, 0xffff0000, v81
	v_pk_add_f32 v[72:73], v[72:73], v[78:79]
	v_pk_add_f32 v[78:79], v[68:69], v[80:81]
	v_pk_add_f32 v[80:81], v[66:67], v[84:85]
	v_pk_add_f32 v[70:71], v[70:71], v[82:83]
	v_mul_f32_e32 v66, v80, v80
	v_mul_f32_e32 v67, v81, v81
	v_fmac_f32_e32 v66, v70, v70
	v_mul_f32_e32 v68, v78, v78
	v_fmac_f32_e32 v67, v71, v71
	v_add_f32_e32 v66, v88, v66
	v_mul_f32_e32 v69, v79, v79
	v_fmac_f32_e32 v68, v72, v72
	v_add_f32_e32 v66, v67, v66
	v_add_f32_e32 v66, v68, v66
	v_fmac_f32_e32 v69, v73, v73
	v_add_f32_e32 v66, v69, v66
	v_mov_b32_e32 v67, v66
	v_mov_b32_e32 v254, v66
	s_nop 1
	v_permlane16_swap_b32_e32 v67, v254
	v_cvt_pk_bf16_f32 v68, v70, v71
	v_cvt_pk_bf16_f32 v69, v72, v73
	v_cvt_pk_bf16_f32 v70, v80, v81
	v_cvt_pk_bf16_f32 v71, v78, v79
	s_waitcnt lgkmcnt(0)
	v_add_f32_e32 v66, v254, v67
	v_mov_b32_e32 v67, v66
	v_mov_b32_e32 v254, v66
	s_nop 1
	v_permlane32_swap_b32_e32 v67, v254
	global_store_dwordx4 v[86:87], v[68:71], off offset:256
	s_and_saveexec_b64 s[6:7], s[0:1]
	s_cbranch_execz .LBB0_966
	s_waitcnt lgkmcnt(0)
	v_add_f32_e32 v66, v254, v67
	flat_atomic_add_f32 v[114:115], v66 offset:192
.LBB0_966:
	s_or_b64 exec, exec, s[6:7]
	v_add_co_u32_e32 v70, vcc, 0x40000, v140
	v_lshl_add_u64 v[72:73], v[140:141], 0, s[94:95]
	s_nop 0
	v_addc_co_u32_e32 v71, vcc, 0, v141, vcc
	s_waitcnt lgkmcnt(0)
	s_waitcnt vmcnt(8)
	s_nop 1
	v_mov_b64_e32 v[66:67], v[186:187]
	v_mov_b64_e32 v[68:69], v[188:189]
	s_nop 0
	v_lshlrev_b32_e32 v74, 16, v66
	v_and_b32_e32 v75, 0xffff0000, v66
	v_lshlrev_b32_e32 v66, 16, v67
	v_and_b32_e32 v67, 0xffff0000, v67
	v_lshlrev_b32_e32 v76, 16, v68
	v_and_b32_e32 v77, 0xffff0000, v68
	v_lshlrev_b32_e32 v68, 16, v69
	v_and_b32_e32 v69, 0xffff0000, v69
	v_pk_add_f32 v[66:67], v[62:63], v[66:67]
	v_pk_add_f32 v[74:75], v[60:61], v[74:75]
	v_pk_add_f32 v[68:69], v[58:59], v[68:69]
	v_pk_add_f32 v[76:77], v[56:57], v[76:77]
	v_cvt_pk_bf16_f32 v56, v74, v75
	v_cvt_pk_bf16_f32 v57, v66, v67
	s_nop 0
	v_cvt_pk_bf16_f32 v58, v76, v77
	v_cvt_pk_bf16_f32 v59, v68, v69
	s_nop 1
	v_mov_b64_e32 v[60:61], v[190:191]
	v_mov_b64_e32 v[62:63], v[192:193]
	v_mul_f32_e32 v76, v76, v76
	v_mul_f32_e32 v77, v77, v77
	v_mul_f32_e32 v68, v68, v68
	v_fmac_f32_e32 v76, v74, v74
	v_fmac_f32_e32 v77, v75, v75
	v_mul_f32_e32 v69, v69, v69
	v_fmac_f32_e32 v68, v66, v66
	v_add_f32_e32 v66, v76, v77
	v_fmac_f32_e32 v69, v67, v67
	v_add_f32_e32 v66, v68, v66
	v_add_f32_e32 v74, v69, v66
	global_store_dwordx4 v[70:71], v[56:59], off
	s_nop 0
	v_lshlrev_b32_e32 v66, 16, v60
	v_and_b32_e32 v67, 0xffff0000, v60
	v_lshlrev_b32_e32 v60, 16, v61
	v_and_b32_e32 v61, 0xffff0000, v61
	v_lshlrev_b32_e32 v68, 16, v62
	v_and_b32_e32 v69, 0xffff0000, v62
	v_lshlrev_b32_e32 v62, 16, v63
	v_and_b32_e32 v63, 0xffff0000, v63
	v_pk_add_f32 v[54:55], v[54:55], v[60:61]
	v_pk_add_f32 v[60:61], v[50:51], v[62:63]
	v_pk_add_f32 v[62:63], v[48:49], v[68:69]
	v_pk_add_f32 v[52:53], v[52:53], v[66:67]
	v_mul_f32_e32 v48, v62, v62
	v_mul_f32_e32 v49, v63, v63
	v_fmac_f32_e32 v48, v52, v52
	v_mul_f32_e32 v50, v60, v60
	v_fmac_f32_e32 v49, v53, v53
	v_add_f32_e32 v48, v74, v48
	v_mul_f32_e32 v51, v61, v61
	v_fmac_f32_e32 v50, v54, v54
	v_add_f32_e32 v48, v49, v48
	v_add_f32_e32 v48, v50, v48
	v_fmac_f32_e32 v51, v55, v55
	v_add_f32_e32 v48, v51, v48
	v_mov_b32_e32 v49, v48
	v_mov_b32_e32 v254, v48
	s_nop 1
	v_permlane16_swap_b32_e32 v49, v254
	v_cvt_pk_bf16_f32 v50, v52, v53
	v_cvt_pk_bf16_f32 v51, v54, v55
	v_cvt_pk_bf16_f32 v52, v62, v63
	v_cvt_pk_bf16_f32 v53, v60, v61
	s_waitcnt lgkmcnt(0)
	v_add_f32_e32 v48, v254, v49
	v_mov_b32_e32 v49, v48
	v_mov_b32_e32 v254, v48
	s_nop 1
	v_permlane32_swap_b32_e32 v49, v254
	global_store_dwordx4 v[72:73], v[50:53], off offset:256
	s_and_saveexec_b64 s[6:7], s[0:1]
	s_cbranch_execz .LBB0_968
	s_waitcnt lgkmcnt(0)
	v_add_f32_e32 v48, v254, v49
	flat_atomic_add_f32 v[114:115], v48 offset:512
; #define GAS __attribute__((address_space(1)))
;     __device__ __forceinline__ void operator()(const Acc& acc, const Unit& u, int wr, int wc, int fr, int fq) const {
;         const int row0 = u.pm * 256 + wr * 64 + fr, col0 = u.pn * 256 + wc * 32 + 8 * fq;
; #pragma unroll
;         for (int ai = 0; ai < 2; ++ai)
; #pragma unroll
;             for (int m = 0; m < 4; ++m) {
;                 const int r = row0 + ai * 128 + m * 16; float ssum = 0.f;
; #pragma unroll
;                 for (int bj = 0; bj < 2; ++bj) {
;                     bf16_t* p = XB + (size_t)r * D + col0 + bj * 128;
;                     f32x4 x0, x1; unpack8(*(const GAS u32x4*)p, x0, x1);
;                     x0 += acc[ai][bj][m][0]; x1 += acc[ai][bj][m][1];
; #pragma unroll
;                     for (int e = 0; e < 4; ++e) ssum += x0[e] * x0[e] + x1[e] * x1[e];
;                     store8_bf16(p, x0, x1);
;                 }
;                 ssum += __shfl_xor(ssum, 16); ssum += __shfl_xor(ssum, 32);
;                 if (fq == 0) atomicAdd(ssout + r, ssum);
;             }
;     }
.LBB0_968:
	s_or_b64 exec, exec, s[6:7]
	v_add_co_u32_e32 v52, vcc, 0x48000, v140
	s_mov_b64 s[6:7], 0x48000
	s_nop 0
	v_addc_co_u32_e32 v53, vcc, 0, v141, vcc
	s_waitcnt lgkmcnt(0)
	s_nop 1
	v_mov_b64_e32 v[48:49], v[214:215]
	v_mov_b64_e32 v[50:51], v[216:217]
	v_lshl_add_u64 v[54:55], v[140:141], 0, s[6:7]
	s_nop 0
	v_lshlrev_b32_e32 v56, 16, v48
	v_and_b32_e32 v57, 0xffff0000, v48
	v_lshlrev_b32_e32 v48, 16, v49
	v_and_b32_e32 v49, 0xffff0000, v49
	v_lshlrev_b32_e32 v58, 16, v50
	v_and_b32_e32 v59, 0xffff0000, v50
	v_lshlrev_b32_e32 v50, 16, v51
	v_and_b32_e32 v51, 0xffff0000, v51
	v_pk_add_f32 v[48:49], v[46:47], v[48:49]
	v_pk_add_f32 v[56:57], v[44:45], v[56:57]
	v_pk_add_f32 v[50:51], v[42:43], v[50:51]
	v_pk_add_f32 v[58:59], v[40:41], v[58:59]
	v_cvt_pk_bf16_f32 v40, v56, v57
	v_cvt_pk_bf16_f32 v41, v48, v49
	s_nop 0
	v_cvt_pk_bf16_f32 v42, v58, v59
	v_cvt_pk_bf16_f32 v43, v50, v51
	s_nop 1
	v_mov_b64_e32 v[44:45], v[218:219]
	v_mov_b64_e32 v[46:47], v[220:221]
	v_mul_f32_e32 v58, v58, v58
	v_mul_f32_e32 v59, v59, v59
	v_mul_f32_e32 v50, v50, v50
	v_fmac_f32_e32 v58, v56, v56
	v_fmac_f32_e32 v59, v57, v57
	v_mul_f32_e32 v51, v51, v51
	v_fmac_f32_e32 v50, v48, v48
	v_add_f32_e32 v48, v58, v59
	v_fmac_f32_e32 v51, v49, v49
	v_add_f32_e32 v48, v50, v48
	v_add_f32_e32 v56, v51, v48
	global_store_dwordx4 v[52:53], v[40:43], off
	s_nop 0
	v_lshlrev_b32_e32 v48, 16, v44
	v_and_b32_e32 v49, 0xffff0000, v44
	v_lshlrev_b32_e32 v44, 16, v45
	v_and_b32_e32 v45, 0xffff0000, v45
	v_lshlrev_b32_e32 v50, 16, v46
	v_and_b32_e32 v51, 0xffff0000, v46
	v_lshlrev_b32_e32 v46, 16, v47
	v_and_b32_e32 v47, 0xffff0000, v47
	v_pk_add_f32 v[38:39], v[38:39], v[44:45]
	v_pk_add_f32 v[44:45], v[34:35], v[46:47]
	v_pk_add_f32 v[46:47], v[32:33], v[50:51]
	v_pk_add_f32 v[36:37], v[36:37], v[48:49]
	v_mul_f32_e32 v32, v46, v46
	v_mul_f32_e32 v33, v47, v47
	v_fmac_f32_e32 v32, v36, v36
	v_mul_f32_e32 v34, v44, v44
	v_fmac_f32_e32 v33, v37, v37
	v_add_f32_e32 v32, v56, v32
	v_mul_f32_e32 v35, v45, v45
	v_fmac_f32_e32 v34, v38, v38
	v_add_f32_e32 v32, v33, v32
	v_add_f32_e32 v32, v34, v32
	v_fmac_f32_e32 v35, v39, v39
	v_add_f32_e32 v32, v35, v32
	v_mov_b32_e32 v33, v32
	v_mov_b32_e32 v254, v32
	s_nop 1
	v_permlane16_swap_b32_e32 v33, v254
	v_cvt_pk_bf16_f32 v34, v36, v37
	v_cvt_pk_bf16_f32 v35, v38, v39
	v_cvt_pk_bf16_f32 v36, v46, v47
	v_cvt_pk_bf16_f32 v37, v44, v45
	s_waitcnt lgkmcnt(0)
	v_add_f32_e32 v32, v254, v33
	v_mov_b32_e32 v33, v32
	v_mov_b32_e32 v254, v32
	s_nop 1
	v_permlane32_swap_b32_e32 v33, v254
	global_store_dwordx4 v[54:55], v[34:37], off offset:256
	s_and_saveexec_b64 s[6:7], s[0:1]
	s_cbranch_execz .LBB0_970
	s_waitcnt lgkmcnt(0)
	v_add_f32_e32 v32, v254, v33
	flat_atomic_add_f32 v[114:115], v32 offset:576
; #define GAS __attribute__((address_space(1)))
;     __device__ __forceinline__ void operator()(const Acc& acc, const Unit& u, int wr, int wc, int fr, int fq) const {
;         const int row0 = u.pm * 256 + wr * 64 + fr, col0 = u.pn * 256 + wc * 32 + 8 * fq;
; #pragma unroll
;         for (int ai = 0; ai < 2; ++ai)
; #pragma unroll
;             for (int m = 0; m < 4; ++m) {
;                 const int r = row0 + ai * 128 + m * 16; float ssum = 0.f;
; #pragma unroll
;                 for (int bj = 0; bj < 2; ++bj) {
;                     bf16_t* p = XB + (size_t)r * D + col0 + bj * 128;
;                     f32x4 x0, x1; unpack8(*(const GAS u32x4*)p, x0, x1);
;                     x0 += acc[ai][bj][m][0]; x1 += acc[ai][bj][m][1];
; #pragma unroll
;                     for (int e = 0; e < 4; ++e) ssum += x0[e] * x0[e] + x1[e] * x1[e];
;                     store8_bf16(p, x0, x1);
;                 }
;                 ssum += __shfl_xor(ssum, 16); ssum += __shfl_xor(ssum, 32);
;                 if (fq == 0) atomicAdd(ssout + r, ssum);
;             }
;     }
.LBB0_970:
	s_or_b64 exec, exec, s[6:7]
	v_add_co_u32_e32 v36, vcc, 0x50000, v140
	s_mov_b64 s[6:7], 0x50000
	s_nop 0
	v_addc_co_u32_e32 v37, vcc, 0, v141, vcc
	s_waitcnt lgkmcnt(0)
	s_nop 1
	v_mov_b64_e32 v[32:33], v[222:223]
	v_mov_b64_e32 v[34:35], v[224:225]
	v_lshl_add_u64 v[38:39], v[140:141], 0, s[6:7]
	s_nop 0
	v_lshlrev_b32_e32 v40, 16, v32
	v_and_b32_e32 v41, 0xffff0000, v32
	v_lshlrev_b32_e32 v32, 16, v33
	v_and_b32_e32 v33, 0xffff0000, v33
	v_lshlrev_b32_e32 v42, 16, v34
	v_and_b32_e32 v43, 0xffff0000, v34
	v_lshlrev_b32_e32 v34, 16, v35
	v_and_b32_e32 v35, 0xffff0000, v35
	v_pk_add_f32 v[32:33], v[30:31], v[32:33]
	v_pk_add_f32 v[40:41], v[28:29], v[40:41]
	v_pk_add_f32 v[34:35], v[26:27], v[34:35]
	v_pk_add_f32 v[42:43], v[24:25], v[42:43]
	v_cvt_pk_bf16_f32 v24, v40, v41
	v_cvt_pk_bf16_f32 v25, v32, v33
	s_nop 0
	v_cvt_pk_bf16_f32 v26, v42, v43
	v_cvt_pk_bf16_f32 v27, v34, v35
	s_nop 1
	v_mov_b64_e32 v[28:29], v[226:227]
	v_mov_b64_e32 v[30:31], v[228:229]
	v_mul_f32_e32 v42, v42, v42
	v_mul_f32_e32 v43, v43, v43
	v_mul_f32_e32 v34, v34, v34
	v_fmac_f32_e32 v42, v40, v40
	v_fmac_f32_e32 v43, v41, v41
	v_mul_f32_e32 v35, v35, v35
	v_fmac_f32_e32 v34, v32, v32
	v_add_f32_e32 v32, v42, v43
	v_fmac_f32_e32 v35, v33, v33
	v_add_f32_e32 v32, v34, v32
	v_add_f32_e32 v40, v35, v32
	global_store_dwordx4 v[36:37], v[24:27], off
	s_nop 0
	v_lshlrev_b32_e32 v32, 16, v28
	v_and_b32_e32 v33, 0xffff0000, v28
	v_lshlrev_b32_e32 v28, 16, v29
	v_and_b32_e32 v29, 0xffff0000, v29
	v_lshlrev_b32_e32 v34, 16, v30
	v_and_b32_e32 v35, 0xffff0000, v30
	v_lshlrev_b32_e32 v30, 16, v31
	v_and_b32_e32 v31, 0xffff0000, v31
	v_pk_add_f32 v[22:23], v[22:23], v[28:29]
	v_pk_add_f32 v[28:29], v[18:19], v[30:31]
	v_pk_add_f32 v[30:31], v[16:17], v[34:35]
	v_pk_add_f32 v[20:21], v[20:21], v[32:33]
	v_mul_f32_e32 v16, v30, v30
	v_mul_f32_e32 v17, v31, v31
	v_fmac_f32_e32 v16, v20, v20
	v_mul_f32_e32 v18, v28, v28
	v_fmac_f32_e32 v17, v21, v21
	v_add_f32_e32 v16, v40, v16
	v_mul_f32_e32 v19, v29, v29
	v_fmac_f32_e32 v18, v22, v22
	v_add_f32_e32 v16, v17, v16
	v_add_f32_e32 v16, v18, v16
	v_fmac_f32_e32 v19, v23, v23
	v_add_f32_e32 v16, v19, v16
	v_mov_b32_e32 v17, v16
	v_mov_b32_e32 v254, v16
	s_nop 1
	v_permlane16_swap_b32_e32 v17, v254
	v_cvt_pk_bf16_f32 v18, v20, v21
	v_cvt_pk_bf16_f32 v19, v22, v23
	v_cvt_pk_bf16_f32 v20, v30, v31
	v_cvt_pk_bf16_f32 v21, v28, v29
	s_waitcnt lgkmcnt(0)
	v_add_f32_e32 v16, v254, v17
	v_mov_b32_e32 v17, v16
	v_mov_b32_e32 v254, v16
	s_nop 1
	v_permlane32_swap_b32_e32 v17, v254
	global_store_dwordx4 v[38:39], v[18:21], off offset:256
	s_and_saveexec_b64 s[6:7], s[0:1]
	s_cbranch_execz .LBB0_972
	s_waitcnt lgkmcnt(0)
	v_add_f32_e32 v16, v254, v17
	flat_atomic_add_f32 v[114:115], v16 offset:640
.LBB0_972:
	s_or_b64 exec, exec, s[6:7]
	v_add_co_u32_e32 v20, vcc, 0x58000, v140
	s_mov_b64 s[6:7], 0x58000
	s_nop 0
	v_addc_co_u32_e32 v21, vcc, 0, v141, vcc
	s_waitcnt lgkmcnt(0)
	s_nop 1
	v_mov_b64_e32 v[16:17], v[230:231]
	v_mov_b64_e32 v[18:19], v[232:233]
	v_lshl_add_u64 v[22:23], v[140:141], 0, s[6:7]
	s_nop 0
	v_lshlrev_b32_e32 v24, 16, v16
	v_and_b32_e32 v25, 0xffff0000, v16
	v_lshlrev_b32_e32 v16, 16, v17
	v_and_b32_e32 v17, 0xffff0000, v17
	v_lshlrev_b32_e32 v26, 16, v18
	v_and_b32_e32 v27, 0xffff0000, v18
	v_lshlrev_b32_e32 v18, 16, v19
	v_and_b32_e32 v19, 0xffff0000, v19
	v_pk_add_f32 v[16:17], v[14:15], v[16:17]
	v_pk_add_f32 v[24:25], v[12:13], v[24:25]
	v_pk_add_f32 v[18:19], v[10:11], v[18:19]
	v_pk_add_f32 v[26:27], v[8:9], v[26:27]
	v_cvt_pk_bf16_f32 v8, v24, v25
	v_cvt_pk_bf16_f32 v9, v16, v17
	s_nop 0
	v_cvt_pk_bf16_f32 v10, v26, v27
	v_cvt_pk_bf16_f32 v11, v18, v19
	s_nop 1
	v_mov_b64_e32 v[12:13], v[234:235]
	v_mov_b64_e32 v[14:15], v[236:237]
	v_mul_f32_e32 v26, v26, v26
	v_mul_f32_e32 v27, v27, v27
	v_mul_f32_e32 v18, v18, v18
	v_fmac_f32_e32 v26, v24, v24
	v_fmac_f32_e32 v27, v25, v25
	v_mul_f32_e32 v19, v19, v19
	v_fmac_f32_e32 v18, v16, v16
	v_add_f32_e32 v16, v26, v27
	v_fmac_f32_e32 v19, v17, v17
	v_add_f32_e32 v16, v18, v16
	v_add_f32_e32 v24, v19, v16
	global_store_dwordx4 v[20:21], v[8:11], off
	s_nop 0
	v_lshlrev_b32_e32 v16, 16, v12
	v_and_b32_e32 v17, 0xffff0000, v12
	v_lshlrev_b32_e32 v12, 16, v13
	v_and_b32_e32 v13, 0xffff0000, v13
	v_lshlrev_b32_e32 v18, 16, v14
	v_and_b32_e32 v19, 0xffff0000, v14
	v_lshlrev_b32_e32 v14, 16, v15
	v_and_b32_e32 v15, 0xffff0000, v15
	v_pk_add_f32 v[6:7], v[6:7], v[12:13]
	v_pk_add_f32 v[12:13], v[2:3], v[14:15]
	v_pk_add_f32 v[14:15], v[0:1], v[18:19]
	v_pk_add_f32 v[4:5], v[4:5], v[16:17]
	v_mul_f32_e32 v0, v14, v14
	v_mul_f32_e32 v1, v15, v15
	v_fmac_f32_e32 v0, v4, v4
	v_mul_f32_e32 v2, v12, v12
	v_fmac_f32_e32 v1, v5, v5
	v_add_f32_e32 v0, v24, v0
	v_mul_f32_e32 v3, v13, v13
	v_fmac_f32_e32 v2, v6, v6
	v_add_f32_e32 v0, v1, v0
	v_add_f32_e32 v0, v2, v0
	v_fmac_f32_e32 v3, v7, v7
	v_add_f32_e32 v0, v3, v0
	v_mov_b32_e32 v1, v0
	v_mov_b32_e32 v254, v0
	s_nop 1
	v_permlane16_swap_b32_e32 v1, v254
	v_cvt_pk_bf16_f32 v2, v4, v5
	v_cvt_pk_bf16_f32 v3, v6, v7
	v_cvt_pk_bf16_f32 v4, v14, v15
	v_cvt_pk_bf16_f32 v5, v12, v13
	s_waitcnt lgkmcnt(0)
	v_add_f32_e32 v0, v254, v1
	v_mov_b32_e32 v1, v0
	v_mov_b32_e32 v254, v0
	s_nop 1
	v_permlane32_swap_b32_e32 v1, v254
	global_store_dwordx4 v[22:23], v[2:5], off offset:256
	s_and_saveexec_b64 s[6:7], s[0:1]
	s_cbranch_execz .LBB0_974
	s_waitcnt lgkmcnt(0)
	v_add_f32_e32 v0, v254, v1
	flat_atomic_add_f32 v[114:115], v0 offset:704

; #define GAS __attribute__((address_space(1)))
;     __device__ __forceinline__ void operator()(const Acc& acc, const Unit& u, int wr, int wc, int fr, int fq) const {
;         const int row0 = u.pm * 256 + wr * 64 + fr, col0 = u.pn * 256 + wc * 32 + 8 * fq;
; #pragma unroll
;         for (int ai = 0; ai < 2; ++ai)
; #pragma unroll
;             for (int m = 0; m < 4; ++m) {
;                 const int r = row0 + ai * 128 + m * 16; float ssum = 0.f;
; #pragma unroll
;                 for (int bj = 0; bj < 2; ++bj) {
;                     bf16_t* p = XB + (size_t)r * D + col0 + bj * 128;
;                     f32x4 x0, x1; unpack8(*(const GAS u32x4*)p, x0, x1);
;                     x0 += acc[ai][bj][m][0]; x1 += acc[ai][bj][m][1];
; #pragma unroll
;                     for (int e = 0; e < 4; ++e) ssum += x0[e] * x0[e] + x1[e] * x1[e];
;                     store8_bf16(p, x0, x1);
;                 }
;                 ssum += __shfl_xor(ssum, 16); ssum += __shfl_xor(ssum, 32);
;                 if (fq == 0) atomicAdd(ssout + r, ssum);
;             }
;     }
.LBB0_1121:
	v_lshl_add_u32 v144, s16, 8, v146
	v_ashrrev_i32_e32 v145, 31, v144
	v_lshl_or_b32 v142, s90, 8, v148
	v_lshlrev_b64 v[140:141], 11, v[144:145]
	v_ashrrev_i32_e32 v143, 31, v142
	v_lshl_add_u64 v[140:141], s[56:57], 0, v[140:141]
	v_lshl_add_u64 v[140:141], v[142:143], 1, v[140:141]
	global_load_dwordx4 v[150:153], v[140:141], off
	global_load_dwordx4 v[158:161], v[140:141], off offset:256
	v_add_co_u32_e32 v238, vcc, 0x8000, v140
	s_nop 1
	v_addc_co_u32_e32 v239, vcc, 0, v141, vcc
	global_load_dwordx4 v[162:165], v[238:239], off
	global_load_dwordx4 v[166:169], v[238:239], off offset:256
	v_add_co_u32_e32 v238, vcc, 0x10000, v140
	s_nop 1
	v_addc_co_u32_e32 v239, vcc, 0, v141, vcc
	global_load_dwordx4 v[170:173], v[238:239], off
	global_load_dwordx4 v[174:177], v[238:239], off offset:256
	v_add_co_u32_e32 v238, vcc, 0x18000, v140
	s_nop 1
	v_addc_co_u32_e32 v239, vcc, 0, v141, vcc
	global_load_dwordx4 v[178:181], v[238:239], off
	global_load_dwordx4 v[182:185], v[238:239], off offset:256
	v_add_co_u32_e32 v238, vcc, 0x40000, v140
	s_nop 1
	v_addc_co_u32_e32 v239, vcc, 0, v141, vcc
	global_load_dwordx4 v[186:189], v[238:239], off
	global_load_dwordx4 v[190:193], v[238:239], off offset:256
	v_add_co_u32_e32 v238, vcc, 0x48000, v140
	s_nop 1
	v_addc_co_u32_e32 v239, vcc, 0, v141, vcc
	global_load_dwordx4 v[214:217], v[238:239], off
	global_load_dwordx4 v[218:221], v[238:239], off offset:256
	v_add_co_u32_e32 v238, vcc, 0x50000, v140
	s_nop 1
	v_addc_co_u32_e32 v239, vcc, 0, v141, vcc
	global_load_dwordx4 v[222:225], v[238:239], off
	global_load_dwordx4 v[226:229], v[238:239], off offset:256
	v_add_co_u32_e32 v238, vcc, 0x58000, v140
	s_nop 1
	v_addc_co_u32_e32 v239, vcc, 0, v141, vcc
	global_load_dwordx4 v[230:233], v[238:239], off
	global_load_dwordx4 v[234:237], v[238:239], off offset:256
	s_waitcnt vmcnt(8)
	v_lshlrev_b32_e32 v154, 16, v150
	v_and_b32_e32 v155, 0xffff0000, v150
	v_lshlrev_b32_e32 v150, 16, v151
	v_and_b32_e32 v151, 0xffff0000, v151
	v_lshlrev_b32_e32 v156, 16, v152
	v_and_b32_e32 v157, 0xffff0000, v152
	v_lshlrev_b32_e32 v152, 16, v153
	v_and_b32_e32 v153, 0xffff0000, v153
	v_pk_add_f32 v[128:129], v[128:129], v[150:151]
	v_pk_add_f32 v[150:151], v[124:125], v[152:153]
	v_pk_add_f32 v[124:125], v[122:123], v[156:157]
	v_pk_add_f32 v[126:127], v[126:127], v[154:155]
	v_mul_f32_e32 v122, v124, v124
	v_mul_f32_e32 v123, v125, v125
	v_fmac_f32_e32 v122, v126, v126
	v_fmac_f32_e32 v123, v127, v127
	v_add_f32_e32 v122, v122, v123
	v_mul_f32_e32 v123, v150, v150
	v_fmac_f32_e32 v123, v128, v128
	v_add_f32_e32 v122, v123, v122
	v_mul_f32_e32 v123, v151, v151
	v_fmac_f32_e32 v123, v129, v129
	v_add_f32_e32 v152, v123, v122
	v_cvt_pk_bf16_f32 v122, v126, v127
	v_cvt_pk_bf16_f32 v123, v128, v129
	v_cvt_pk_bf16_f32 v124, v124, v125
	v_cvt_pk_bf16_f32 v125, v150, v151
	global_store_dwordx4 v[140:141], v[122:125], off
	s_nop 1
	v_mov_b64_e32 v[122:123], v[158:159]
	v_mov_b64_e32 v[124:125], v[160:161]
	s_nop 0
	v_lshlrev_b32_e32 v126, 16, v122
	v_and_b32_e32 v127, 0xffff0000, v122
	v_lshlrev_b32_e32 v122, 16, v123
	v_and_b32_e32 v123, 0xffff0000, v123
	v_lshlrev_b32_e32 v128, 16, v124
	v_and_b32_e32 v129, 0xffff0000, v124
	v_lshlrev_b32_e32 v124, 16, v125
	v_and_b32_e32 v125, 0xffff0000, v125
	v_pk_add_f32 v[120:121], v[120:121], v[122:123]
	v_pk_add_f32 v[122:123], v[116:117], v[124:125]
	v_pk_add_f32 v[116:117], v[114:115], v[128:129]
	v_pk_add_f32 v[118:119], v[118:119], v[126:127]
	v_mul_f32_e32 v114, v116, v116
	v_fmac_f32_e32 v114, v118, v118
	v_mul_f32_e32 v115, v117, v117
	v_add_f32_e32 v114, v152, v114
	v_fmac_f32_e32 v115, v119, v119
	v_add_f32_e32 v114, v115, v114
	v_mul_f32_e32 v115, v122, v122
	v_fmac_f32_e32 v115, v120, v120
	v_add_f32_e32 v114, v115, v114
	v_mul_f32_e32 v115, v123, v123
	v_fmac_f32_e32 v115, v121, v121
	v_add_f32_e32 v124, v115, v114
	v_cvt_pk_bf16_f32 v114, v118, v119
	v_cvt_pk_bf16_f32 v115, v120, v121
	v_cvt_pk_bf16_f32 v116, v116, v117
	v_cvt_pk_bf16_f32 v117, v122, v123
	global_store_dwordx4 v[140:141], v[114:117], off offset:256
	s_nop 1
	v_xor_b32_e32 v114, 16, v246
	v_add_u32_e32 v115, 64, v247
	v_cmp_lt_i32_e32 vcc, v114, v115
	s_nop 1
	v_cndmask_b32_e32 v114, v246, v114, vcc
	v_lshlrev_b32_e32 v116, 2, v114
	v_mov_b32_e32 v114, v124
	v_mov_b32_e32 v254, v124
	s_nop 1
	v_permlane16_swap_b32_e32 v114, v254
	s_waitcnt lgkmcnt(0)
	v_add_f32_e32 v118, v254, v114
	v_xor_b32_e32 v114, 32, v246
	v_cmp_lt_i32_e32 vcc, v114, v115
	s_nop 1
	v_cndmask_b32_e32 v114, v246, v114, vcc
	v_lshlrev_b32_e32 v117, 2, v114
	v_mov_b32_e32 v119, v118
	v_mov_b32_e32 v254, v118
	s_nop 1
	v_permlane32_swap_b32_e32 v119, v254
	v_lshl_add_u64 v[114:115], v[144:145], 2, s[58:59]
	s_and_saveexec_b64 s[6:7], s[0:1]
	s_cbranch_execz .LBB0_1123
	s_waitcnt lgkmcnt(0)
	v_add_f32_e32 v118, v254, v119
	flat_atomic_add_f32 v[114:115], v118
